# K and Vt stored quad-contiguous (4x4 chunk transposition) so attention fragment loads coalesce; hand-written attention loop and V tile store
# speedup vs baseline: 1.0715x; 1.0550x over previous
.LBB0_212:
	s_add_u32 s28, s12, s18
	ds_read_b128 v[150:153], v140
	ds_read_b128 v[154:157], v140 offset:1024
	ds_read_b128 v[158:161], v140 offset:2048
	ds_read_b128 v[162:165], v140 offset:3072
	s_addc_u32 s29, s13, s19
	s_add_u32 s28, s28, 0x100
	s_addc_u32 s29, s29, 0
	s_add_u32 s33, s60, s18
	s_addc_u32 s85, s61, s19
	s_cmpk_eq_i32 s18, 0x700
	s_cselect_b32 s37, s13, s29
	s_cselect_b32 s36, s12, s28
	s_cselect_b32 s29, s11, s85
	s_cselect_b32 s28, s10, s33
	s_mov_b32 m0, s63
	v_lshl_add_u64 v[146:147], v[136:137], 0, s[18:19]
	ds_read_b128 v[166:169], v141
	ds_read_b128 v[170:173], v141 offset:1024
	ds_read_b128 v[174:177], v141 offset:2048
	ds_read_b128 v[178:181], v141 offset:3072
	ds_read_b128 v[182:185], v141 offset:4096
	ds_read_b128 v[186:189], v141 offset:5120
	ds_read_b128 v[190:193], v141 offset:6144
	ds_read_b128 v[194:197], v141 offset:7168
	global_load_lds_dwordx4 v[146:147], off
	v_lshl_add_u64 v[146:147], v[138:139], 0, s[18:19]
	s_mov_b32 m0, s64
	s_nop 0
	global_load_lds_dwordx4 v[146:147], off
	s_waitcnt lgkmcnt(8)
	s_barrier
	s_waitcnt lgkmcnt(0)
	s_setprio 1
	s_waitcnt lgkmcnt(0)
	v_mfma_f32_16x16x32_bf16 v[124:127], v[150:153], v[166:169], v[124:127]
	v_mfma_f32_16x16x32_bf16 v[92:95], v[158:161], v[166:169], v[92:95]
	v_mfma_f32_16x16x32_bf16 v[120:123], v[150:153], v[174:177], v[120:123]
	v_mfma_f32_16x16x32_bf16 v[88:91], v[158:161], v[174:177], v[88:91]
	v_mfma_f32_16x16x32_bf16 v[116:119], v[150:153], v[182:185], v[116:119]
	v_mfma_f32_16x16x32_bf16 v[84:87], v[158:161], v[182:185], v[84:87]
	v_mfma_f32_16x16x32_bf16 v[112:115], v[150:153], v[190:193], v[112:115]
	v_mfma_f32_16x16x32_bf16 v[80:83], v[158:161], v[190:193], v[80:83]
	v_mfma_f32_16x16x32_bf16 v[124:127], v[154:157], v[170:173], v[124:127]
	v_mfma_f32_16x16x32_bf16 v[92:95], v[162:165], v[170:173], v[92:95]
	v_mfma_f32_16x16x32_bf16 v[120:123], v[154:157], v[178:181], v[120:123]
	v_mfma_f32_16x16x32_bf16 v[88:91], v[162:165], v[178:181], v[88:91]
	v_mfma_f32_16x16x32_bf16 v[116:119], v[154:157], v[186:189], v[116:119]
	v_mfma_f32_16x16x32_bf16 v[84:87], v[162:165], v[186:189], v[84:87]
	v_mfma_f32_16x16x32_bf16 v[112:115], v[154:157], v[194:197], v[112:115]
	v_mfma_f32_16x16x32_bf16 v[80:83], v[162:165], v[194:197], v[80:83]
	s_setprio 0
	s_barrier
	s_mov_b32 m0, s65
	v_lshl_add_u64 v[146:147], s[28:29], 0, v[130:131]
	ds_read_b128 v[198:201], v142
	ds_read_b128 v[202:205], v142 offset:1024
	ds_read_b128 v[206:209], v142 offset:2048
	ds_read_b128 v[210:213], v142 offset:3072
	global_load_lds_dwordx4 v[146:147], off
	v_lshl_add_u64 v[214:215], s[28:29], 0, v[134:135]
	s_mov_b32 m0, s66
	s_nop 0
	global_load_lds_dwordx4 v[214:215], off
	s_barrier
	s_waitcnt lgkmcnt(0)
	s_setprio 1
	s_waitcnt lgkmcnt(0)
	v_mfma_f32_16x16x32_bf16 v[60:63], v[198:201], v[166:169], v[60:63]
	v_mfma_f32_16x16x32_bf16 v[28:31], v[206:209], v[166:169], v[28:31]
	v_mfma_f32_16x16x32_bf16 v[56:59], v[198:201], v[174:177], v[56:59]
	v_mfma_f32_16x16x32_bf16 v[24:27], v[206:209], v[174:177], v[24:27]
	v_mfma_f32_16x16x32_bf16 v[52:55], v[198:201], v[182:185], v[52:55]
	v_mfma_f32_16x16x32_bf16 v[20:23], v[206:209], v[182:185], v[20:23]
	v_mfma_f32_16x16x32_bf16 v[48:51], v[198:201], v[190:193], v[48:51]
	v_mfma_f32_16x16x32_bf16 v[16:19], v[206:209], v[190:193], v[16:19]
	v_mfma_f32_16x16x32_bf16 v[60:63], v[202:205], v[170:173], v[60:63]
	v_mfma_f32_16x16x32_bf16 v[28:31], v[210:213], v[170:173], v[28:31]
	v_mfma_f32_16x16x32_bf16 v[56:59], v[202:205], v[178:181], v[56:59]
	v_mfma_f32_16x16x32_bf16 v[24:27], v[210:213], v[178:181], v[24:27]
	v_mfma_f32_16x16x32_bf16 v[52:55], v[202:205], v[186:189], v[52:55]
	v_mfma_f32_16x16x32_bf16 v[20:23], v[210:213], v[186:189], v[20:23]
	v_mfma_f32_16x16x32_bf16 v[48:51], v[202:205], v[194:197], v[48:51]
	v_mfma_f32_16x16x32_bf16 v[16:19], v[210:213], v[194:197], v[16:19]
	s_setprio 0
	s_mov_b32 m0, s5
	v_lshl_add_u64 v[218:219], s[36:37], 0, v[128:129]
	s_barrier
	ds_read_b128 v[166:169], v141 offset:16384
	ds_read_b128 v[170:173], v141 offset:17408
	ds_read_b128 v[174:177], v141 offset:18432
	ds_read_b128 v[178:181], v141 offset:19456
	ds_read_b128 v[182:185], v141 offset:20480
	ds_read_b128 v[186:189], v141 offset:21504
	ds_read_b128 v[190:193], v141 offset:22528
	ds_read_b128 v[194:197], v141 offset:23552
	global_load_lds_dwordx4 v[218:219], off
	v_lshl_add_u64 v[220:221], s[36:37], 0, v[132:133]
	s_mov_b32 m0, s54
	s_nop 0
	global_load_lds_dwordx4 v[220:221], off
	s_barrier
	s_waitcnt lgkmcnt(0)
	s_setprio 1
	s_waitcnt lgkmcnt(0)
	v_mfma_f32_16x16x32_bf16 v[108:111], v[150:153], v[166:169], v[108:111]
	v_mfma_f32_16x16x32_bf16 v[76:79], v[158:161], v[166:169], v[76:79]
	v_mfma_f32_16x16x32_bf16 v[104:107], v[150:153], v[174:177], v[104:107]
	v_mfma_f32_16x16x32_bf16 v[72:75], v[158:161], v[174:177], v[72:75]
	v_mfma_f32_16x16x32_bf16 v[100:103], v[150:153], v[182:185], v[100:103]
	v_mfma_f32_16x16x32_bf16 v[68:71], v[158:161], v[182:185], v[68:71]
	v_mfma_f32_16x16x32_bf16 v[96:99], v[150:153], v[190:193], v[96:99]
	v_mfma_f32_16x16x32_bf16 v[64:67], v[158:161], v[190:193], v[64:67]
	v_mfma_f32_16x16x32_bf16 v[108:111], v[154:157], v[170:173], v[108:111]
	v_mfma_f32_16x16x32_bf16 v[76:79], v[162:165], v[170:173], v[76:79]
	v_mfma_f32_16x16x32_bf16 v[104:107], v[154:157], v[178:181], v[104:107]
	v_mfma_f32_16x16x32_bf16 v[72:75], v[162:165], v[178:181], v[72:75]
	v_mfma_f32_16x16x32_bf16 v[100:103], v[154:157], v[186:189], v[100:103]
	v_mfma_f32_16x16x32_bf16 v[68:71], v[162:165], v[186:189], v[68:71]
	v_mfma_f32_16x16x32_bf16 v[96:99], v[154:157], v[194:197], v[96:99]
	v_mfma_f32_16x16x32_bf16 v[64:67], v[162:165], v[194:197], v[64:67]
	s_setprio 0
	s_barrier
	s_add_u32 s86, s28, 0x40000
	s_addc_u32 s87, s29, 0
	s_mov_b32 m0, s67
	v_lshl_add_u64 v[150:151], s[86:87], 0, v[130:131]
	global_load_lds_dwordx4 v[150:151], off
	v_lshl_add_u64 v[150:151], s[86:87], 0, v[134:135]
	s_mov_b32 m0, s80
	s_nop 0
	global_load_lds_dwordx4 v[150:151], off
	s_waitcnt vmcnt(6)
	s_barrier
	s_setprio 1
	v_mfma_f32_16x16x32_bf16 v[44:47], v[198:201], v[166:169], v[44:47]
	v_mfma_f32_16x16x32_bf16 v[12:15], v[206:209], v[166:169], v[12:15]
	v_mfma_f32_16x16x32_bf16 v[40:43], v[198:201], v[174:177], v[40:43]
	v_mfma_f32_16x16x32_bf16 v[8:11], v[206:209], v[174:177], v[8:11]
	v_mfma_f32_16x16x32_bf16 v[36:39], v[198:201], v[182:185], v[36:39]
	v_mfma_f32_16x16x32_bf16 v[4:7], v[206:209], v[182:185], v[4:7]
	v_mfma_f32_16x16x32_bf16 v[32:35], v[198:201], v[190:193], v[32:35]
	v_mfma_f32_16x16x32_bf16 v[0:3], v[206:209], v[190:193], v[0:3]
	v_mfma_f32_16x16x32_bf16 v[44:47], v[202:205], v[170:173], v[44:47]
	v_mfma_f32_16x16x32_bf16 v[12:15], v[210:213], v[170:173], v[12:15]
	v_mfma_f32_16x16x32_bf16 v[40:43], v[202:205], v[178:181], v[40:43]
	v_mfma_f32_16x16x32_bf16 v[8:11], v[210:213], v[178:181], v[8:11]
	v_mfma_f32_16x16x32_bf16 v[36:39], v[202:205], v[186:189], v[36:39]
	v_mfma_f32_16x16x32_bf16 v[4:7], v[210:213], v[186:189], v[4:7]
	v_mfma_f32_16x16x32_bf16 v[32:35], v[202:205], v[194:197], v[32:35]
	v_mfma_f32_16x16x32_bf16 v[0:3], v[210:213], v[194:197], v[0:3]
	s_setprio 0
	s_barrier
	ds_read_b128 v[150:153], v143
	ds_read_b128 v[154:157], v143 offset:1024
	ds_read_b128 v[158:161], v143 offset:2048
	ds_read_b128 v[162:165], v143 offset:3072
	s_add_u32 s36, s36, 0x40000
	s_addc_u32 s37, s37, 0
	s_mov_b32 m0, s56
	v_lshl_add_u64 v[198:199], s[36:37], 0, v[128:129]
	ds_read_b128 v[166:169], v141 offset:32768
	ds_read_b128 v[170:173], v141 offset:33792
	ds_read_b128 v[174:177], v141 offset:34816
	ds_read_b128 v[178:181], v141 offset:35840
	ds_read_b128 v[182:185], v141 offset:36864
	ds_read_b128 v[186:189], v141 offset:37888
	ds_read_b128 v[190:193], v141 offset:38912
	ds_read_b128 v[194:197], v141 offset:39936
	global_load_lds_dwordx4 v[198:199], off
	v_lshl_add_u64 v[198:199], s[36:37], 0, v[132:133]
	s_mov_b32 m0, s57
	s_nop 0
	global_load_lds_dwordx4 v[198:199], off
	s_waitcnt lgkmcnt(8)
	s_barrier
	s_waitcnt lgkmcnt(0)
	s_setprio 1
	s_waitcnt lgkmcnt(0)
	v_mfma_f32_16x16x32_bf16 v[124:127], v[150:153], v[166:169], v[124:127]
	v_mfma_f32_16x16x32_bf16 v[92:95], v[158:161], v[166:169], v[92:95]
	v_mfma_f32_16x16x32_bf16 v[120:123], v[150:153], v[174:177], v[120:123]
	v_mfma_f32_16x16x32_bf16 v[88:91], v[158:161], v[174:177], v[88:91]
	v_mfma_f32_16x16x32_bf16 v[116:119], v[150:153], v[182:185], v[116:119]
	v_mfma_f32_16x16x32_bf16 v[84:87], v[158:161], v[182:185], v[84:87]
	v_mfma_f32_16x16x32_bf16 v[112:115], v[150:153], v[190:193], v[112:115]
	v_mfma_f32_16x16x32_bf16 v[80:83], v[158:161], v[190:193], v[80:83]
	v_mfma_f32_16x16x32_bf16 v[124:127], v[154:157], v[170:173], v[124:127]
	v_mfma_f32_16x16x32_bf16 v[92:95], v[162:165], v[170:173], v[92:95]
	v_mfma_f32_16x16x32_bf16 v[120:123], v[154:157], v[178:181], v[120:123]
	v_mfma_f32_16x16x32_bf16 v[88:91], v[162:165], v[178:181], v[88:91]
	v_mfma_f32_16x16x32_bf16 v[116:119], v[154:157], v[186:189], v[116:119]
	v_mfma_f32_16x16x32_bf16 v[84:87], v[162:165], v[186:189], v[84:87]
	v_mfma_f32_16x16x32_bf16 v[112:115], v[154:157], v[194:197], v[112:115]
	v_mfma_f32_16x16x32_bf16 v[80:83], v[162:165], v[194:197], v[80:83]
	s_setprio 0
	s_barrier
	s_mov_b32 m0, s81
	v_lshl_add_u64 v[146:147], v[146:147], 0, s[14:15]
	ds_read_b128 v[198:201], v145
	ds_read_b128 v[202:205], v145 offset:1024
	ds_read_b128 v[206:209], v145 offset:2048
	ds_read_b128 v[210:213], v145 offset:3072
	global_load_lds_dwordx4 v[146:147], off
	v_lshl_add_u64 v[146:147], v[214:215], 0, s[14:15]
	s_mov_b32 m0, s82
	s_nop 0
	global_load_lds_dwordx4 v[146:147], off
	s_barrier
	s_waitcnt lgkmcnt(0)
	s_setprio 1
	s_waitcnt lgkmcnt(0)
	v_mfma_f32_16x16x32_bf16 v[60:63], v[198:201], v[166:169], v[60:63]
	v_mfma_f32_16x16x32_bf16 v[28:31], v[206:209], v[166:169], v[28:31]
	v_mfma_f32_16x16x32_bf16 v[56:59], v[198:201], v[174:177], v[56:59]
	v_mfma_f32_16x16x32_bf16 v[24:27], v[206:209], v[174:177], v[24:27]
	v_mfma_f32_16x16x32_bf16 v[52:55], v[198:201], v[182:185], v[52:55]
	v_mfma_f32_16x16x32_bf16 v[20:23], v[206:209], v[182:185], v[20:23]
	v_mfma_f32_16x16x32_bf16 v[48:51], v[198:201], v[190:193], v[48:51]
	v_mfma_f32_16x16x32_bf16 v[16:19], v[206:209], v[190:193], v[16:19]
	v_mfma_f32_16x16x32_bf16 v[60:63], v[202:205], v[170:173], v[60:63]
	v_mfma_f32_16x16x32_bf16 v[28:31], v[210:213], v[170:173], v[28:31]
	v_mfma_f32_16x16x32_bf16 v[56:59], v[202:205], v[178:181], v[56:59]
	v_mfma_f32_16x16x32_bf16 v[24:27], v[210:213], v[178:181], v[24:27]
	v_mfma_f32_16x16x32_bf16 v[52:55], v[202:205], v[186:189], v[52:55]
	v_mfma_f32_16x16x32_bf16 v[20:23], v[210:213], v[186:189], v[20:23]
	v_mfma_f32_16x16x32_bf16 v[48:51], v[202:205], v[194:197], v[48:51]
	v_mfma_f32_16x16x32_bf16 v[16:19], v[210:213], v[194:197], v[16:19]
	s_setprio 0
	s_mov_b32 m0, s58
	v_lshl_add_u64 v[146:147], v[218:219], 0, s[14:15]
	s_barrier
	ds_read_b128 v[166:169], v141 offset:49152
	ds_read_b128 v[170:173], v141 offset:50176
	ds_read_b128 v[174:177], v141 offset:51200
	ds_read_b128 v[178:181], v141 offset:52224
	ds_read_b128 v[182:185], v141 offset:53248
	ds_read_b128 v[186:189], v141 offset:54272
	ds_read_b128 v[190:193], v141 offset:55296
	ds_read_b128 v[194:197], v141 offset:56320
	global_load_lds_dwordx4 v[146:147], off
	v_lshl_add_u64 v[146:147], v[220:221], 0, s[14:15]
	s_mov_b32 m0, s59
	s_nop 0
	global_load_lds_dwordx4 v[146:147], off
	s_barrier
	s_waitcnt lgkmcnt(0)
	s_setprio 1
	s_waitcnt lgkmcnt(0)
	v_mfma_f32_16x16x32_bf16 v[108:111], v[150:153], v[166:169], v[108:111]
	v_mfma_f32_16x16x32_bf16 v[76:79], v[158:161], v[166:169], v[76:79]
	v_mfma_f32_16x16x32_bf16 v[104:107], v[150:153], v[174:177], v[104:107]
	v_mfma_f32_16x16x32_bf16 v[72:75], v[158:161], v[174:177], v[72:75]
	v_mfma_f32_16x16x32_bf16 v[100:103], v[150:153], v[182:185], v[100:103]
	v_mfma_f32_16x16x32_bf16 v[68:71], v[158:161], v[182:185], v[68:71]
	v_mfma_f32_16x16x32_bf16 v[96:99], v[150:153], v[190:193], v[96:99]
	v_mfma_f32_16x16x32_bf16 v[64:67], v[158:161], v[190:193], v[64:67]
	v_mfma_f32_16x16x32_bf16 v[108:111], v[154:157], v[170:173], v[108:111]
	v_mfma_f32_16x16x32_bf16 v[76:79], v[162:165], v[170:173], v[76:79]
	v_mfma_f32_16x16x32_bf16 v[104:107], v[154:157], v[178:181], v[104:107]
	v_mfma_f32_16x16x32_bf16 v[72:75], v[162:165], v[178:181], v[72:75]
	v_mfma_f32_16x16x32_bf16 v[100:103], v[154:157], v[186:189], v[100:103]
	v_mfma_f32_16x16x32_bf16 v[68:71], v[162:165], v[186:189], v[68:71]
	v_mfma_f32_16x16x32_bf16 v[96:99], v[154:157], v[194:197], v[96:99]
	v_mfma_f32_16x16x32_bf16 v[64:67], v[162:165], v[194:197], v[64:67]
	s_setprio 0
	s_barrier
	s_add_u32 s28, s28, 0x40080
	s_addc_u32 s29, s29, 0
	s_mov_b32 m0, s83
	v_lshl_add_u64 v[146:147], s[28:29], 0, v[130:131]
	global_load_lds_dwordx4 v[146:147], off
	v_lshl_add_u64 v[146:147], s[28:29], 0, v[134:135]
	s_mov_b32 m0, s84
	s_nop 0
	global_load_lds_dwordx4 v[146:147], off
	s_waitcnt vmcnt(6)
	s_barrier
	s_setprio 1
	v_mfma_f32_16x16x32_bf16 v[44:47], v[198:201], v[166:169], v[44:47]
	v_mfma_f32_16x16x32_bf16 v[12:15], v[206:209], v[166:169], v[12:15]
	v_mfma_f32_16x16x32_bf16 v[40:43], v[198:201], v[174:177], v[40:43]
	v_mfma_f32_16x16x32_bf16 v[8:11], v[206:209], v[174:177], v[8:11]
	v_mfma_f32_16x16x32_bf16 v[36:39], v[198:201], v[182:185], v[36:39]
	v_mfma_f32_16x16x32_bf16 v[4:7], v[206:209], v[182:185], v[4:7]
	v_mfma_f32_16x16x32_bf16 v[32:35], v[198:201], v[190:193], v[32:35]
	v_mfma_f32_16x16x32_bf16 v[0:3], v[206:209], v[190:193], v[0:3]
	v_mfma_f32_16x16x32_bf16 v[44:47], v[202:205], v[170:173], v[44:47]
	v_mfma_f32_16x16x32_bf16 v[12:15], v[210:213], v[170:173], v[12:15]
	v_mfma_f32_16x16x32_bf16 v[40:43], v[202:205], v[178:181], v[40:43]
	v_mfma_f32_16x16x32_bf16 v[8:11], v[210:213], v[178:181], v[8:11]
	v_mfma_f32_16x16x32_bf16 v[36:39], v[202:205], v[186:189], v[36:39]
	v_mfma_f32_16x16x32_bf16 v[4:7], v[210:213], v[186:189], v[4:7]
	v_mfma_f32_16x16x32_bf16 v[32:35], v[202:205], v[194:197], v[32:35]
	v_mfma_f32_16x16x32_bf16 v[0:3], v[210:213], v[194:197], v[0:3]
	s_setprio 0
	s_add_i32 s62, s62, 2
	s_add_u32 s18, s18, 0x100
	s_addc_u32 s19, s19, 0
	s_cmp_gt_u32 s62, 13
	s_barrier
	s_cbranch_scc0 .LBB0_212
	s_and_b32 s5, s2, 1
	s_and_b32 s4, s4, 10
	s_cmp_lg_u32 s4, 10
	s_mov_b64 s[10:11], -1
	s_cbranch_scc0 .LBB0_215
	v_lshlrev_b32_e32 v128, 2, v148
	global_load_dwordx4 v[140:143], v128, s[24:25]
	global_load_dwordx4 v[136:139], v128, s[24:25] offset:16
	global_load_dwordx4 v[132:135], v128, s[24:25] offset:128
	s_nop 0
	global_load_dwordx4 v[128:131], v128, s[24:25] offset:144
	v_mul_f32_e32 v146, v125, v125
	v_mul_f32_e32 v150, v127, v127
	v_mul_f32_e32 v151, v93, v93
	v_mul_f32_e32 v152, v95, v95
	v_mul_f32_e32 v153, v61, v61
	v_mul_f32_e32 v154, v63, v63
	v_fmac_f32_e32 v146, v124, v124
	v_fmac_f32_e32 v150, v126, v126
	v_fmac_f32_e32 v151, v92, v92
	v_fmac_f32_e32 v152, v94, v94
	v_mul_f32_e32 v155, v29, v29
	v_mul_f32_e32 v156, v31, v31
	v_fmac_f32_e32 v153, v60, v60
	v_fmac_f32_e32 v154, v62, v62
	v_add_f32_e32 v160, v146, v150
	v_add_f32_e32 v152, v151, v152
	v_fmac_f32_e32 v155, v28, v28
	v_fmac_f32_e32 v156, v30, v30
	v_add_f32_e32 v153, v153, v154
	v_add_f32_e32 v152, v160, v152
	v_add_f32_e32 v154, v155, v156
	v_add_f32_e32 v152, v152, v153
	v_add_f32_e32 v152, v152, v154
	v_mov_b32_e32 v153, v152
	s_nop 1
	v_permlane16_swap_b32_e32 v152, v153
	v_add_f32_e32 v152, v152, v153
	v_mov_b32_e32 v153, v152
	s_nop 1
	v_permlane32_swap_b32_e32 v152, v153
	s_load_dwordx8 s[56:63], s[0:1], 0xc0
	s_lshl_b32 s4, s7, 6
	s_lshl_b32 s13, s5, 8
	v_mov_b32_e32 v149, 0x358637bd
	v_add_f32_e32 v152, v152, v153
	s_or_b32 s4, s4, s13
	v_fmamk_f32 v152, v152, 0x3c800000, v149
	v_or_b32_e32 v159, s4, v148
	v_rsq_f32_e32 v152, v152
	s_ashr_i32 s12, s55, 31
	v_mov_b32_e32 v147, 0
	v_lshlrev_b32_e32 v146, 1, v159
	v_bfe_u32 v253, v217, 4, 2
	v_and_b32_e32 v254, 3, v217
	v_sub_u32_e32 v253, v253, v254
	v_lshlrev_b32_e32 v254, 4, v253
	v_sub_u32_e32 v146, v146, v254
	s_lshl_b64 s[10:11], s[8:9], 18
	v_mov_b32_e32 v145, s12
	s_waitcnt lgkmcnt(0)
	v_lshl_add_u64 v[146:147], s[60:61], 0, v[146:147]
	v_mul_f32_e32 v157, v121, v121
	v_mul_f32_e32 v158, v123, v123
	v_add_u32_e32 v254, v144, v253
	v_mov_b32_e32 v255, v145
	v_lshlrev_b64 v[150:151], 10, v[254:255]
	v_lshl_add_u64 v[146:147], v[146:147], 0, s[10:11]
	v_fmac_f32_e32 v157, v120, v120
	v_fmac_f32_e32 v158, v122, v122
	v_lshl_add_u64 v[146:147], v[146:147], 0, v[150:151]
	v_pk_mul_f32 v[150:151], v[124:125], v[152:153] op_sel_hi:[1,0]
	v_mul_f32_e32 v168, v89, v89
	v_mul_f32_e32 v169, v91, v91
	v_add_f32_e32 v145, v157, v158
	v_pk_mul_f32 v[154:155], v[126:127], v[152:153] op_sel_hi:[1,0]
	v_pk_mul_f32 v[156:157], v[92:93], v[152:153] op_sel_hi:[1,0]
	v_pk_mul_f32 v[158:159], v[94:95], v[152:153] op_sel_hi:[1,0]
	v_pk_mul_f32 v[160:161], v[60:61], v[152:153] op_sel_hi:[1,0]
	v_pk_mul_f32 v[162:163], v[62:63], v[152:153] op_sel_hi:[1,0]
	v_pk_mul_f32 v[164:165], v[28:29], v[152:153] op_sel_hi:[1,0]
	v_pk_mul_f32 v[152:153], v[30:31], v[152:153] op_sel_hi:[1,0]
	v_fmac_f32_e32 v168, v88, v88
	v_fmac_f32_e32 v169, v90, v90
	s_movk_i32 s4, 0x4000
	s_mov_b64 s[10:11], 0
	s_waitcnt vmcnt(0)
	v_pk_mul_f32 v[150:151], v[140:141], v[150:151]
	v_pk_mul_f32 v[154:155], v[142:143], v[154:155]
	v_pk_mul_f32 v[156:157], v[136:137], v[156:157]
	v_pk_mul_f32 v[166:167], v[130:131], v[152:153]
	v_cvt_pk_bf16_f32 v150, v150, v151
	v_cvt_pk_bf16_f32 v151, v154, v155
	v_cvt_pk_bf16_f32 v152, v156, v157
	v_pk_mul_f32 v[158:159], v[138:139], v[158:159]
	v_pk_mul_f32 v[162:163], v[134:135], v[162:163]
	v_cvt_pk_bf16_f32 v153, v158, v159
	global_store_dwordx4 v[146:147], v[150:153], off
	v_pk_mul_f32 v[160:161], v[132:133], v[160:161]
	v_pk_mul_f32 v[164:165], v[128:129], v[164:165]
	v_add_f32_e32 v152, v168, v169
	v_add_f32_e32 v145, v145, v152
	v_mul_f32_e32 v152, v57, v57
	v_mul_f32_e32 v153, v59, v59
	v_fmac_f32_e32 v152, v56, v56
	v_fmac_f32_e32 v153, v58, v58
	v_add_f32_e32 v152, v152, v153
	v_add_f32_e32 v145, v145, v152
	v_mul_f32_e32 v152, v25, v25
	v_mul_f32_e32 v153, v27, v27
	v_fmac_f32_e32 v152, v24, v24
	v_fmac_f32_e32 v153, v26, v26
	v_add_f32_e32 v152, v152, v153
	v_add_f32_e32 v145, v145, v152
	v_mov_b32_e32 v152, v145
	s_nop 1
	v_permlane16_swap_b32_e32 v145, v152
	v_add_f32_e32 v145, v145, v152
	v_mov_b32_e32 v152, v145
	s_nop 1
	v_permlane32_swap_b32_e32 v145, v152
	v_add_f32_e32 v145, v145, v152
	v_fmamk_f32 v145, v145, 0x3c800000, v149
	v_rsq_f32_e32 v154, v145
	v_cvt_pk_bf16_f32 v150, v160, v161
	v_cvt_pk_bf16_f32 v151, v162, v163
	v_cvt_pk_bf16_f32 v152, v164, v165
	v_cvt_pk_bf16_f32 v153, v166, v167
	global_store_dwordx4 v[146:147], v[150:153], off offset:64
	v_pk_mul_f32 v[156:157], v[88:89], v[154:155] op_sel_hi:[1,0]
	v_pk_mul_f32 v[158:159], v[90:91], v[154:155] op_sel_hi:[1,0]
	v_pk_mul_f32 v[150:151], v[120:121], v[154:155] op_sel_hi:[1,0]
	v_pk_mul_f32 v[152:153], v[122:123], v[154:155] op_sel_hi:[1,0]
	v_pk_mul_f32 v[150:151], v[140:141], v[150:151]
	v_pk_mul_f32 v[152:153], v[142:143], v[152:153]
	v_pk_mul_f32 v[156:157], v[136:137], v[156:157]
	v_cvt_pk_bf16_f32 v150, v150, v151
	v_cvt_pk_bf16_f32 v151, v152, v153
	v_pk_mul_f32 v[158:159], v[138:139], v[158:159]
	v_cvt_pk_bf16_f32 v152, v156, v157
	v_add_co_u32_e32 v156, vcc, s4, v146
	v_cvt_pk_bf16_f32 v153, v158, v159
	v_mul_f32_e32 v145, v117, v117
	s_nop 0
	v_addc_co_u32_e32 v157, vcc, 0, v147, vcc
	global_store_dwordx4 v[156:157], v[150:153], off
	v_fmac_f32_e32 v145, v116, v116
	v_pk_mul_f32 v[158:159], v[24:25], v[154:155] op_sel_hi:[1,0]
	v_pk_mul_f32 v[150:151], v[56:57], v[154:155] op_sel_hi:[1,0]
	v_pk_mul_f32 v[152:153], v[58:59], v[154:155] op_sel_hi:[1,0]
	v_pk_mul_f32 v[150:151], v[132:133], v[150:151]
	v_pk_mul_f32 v[152:153], v[134:135], v[152:153]
	v_cvt_pk_bf16_f32 v150, v150, v151
	v_pk_mul_f32 v[154:155], v[26:27], v[154:155] op_sel_hi:[1,0]
	v_cvt_pk_bf16_f32 v151, v152, v153
	v_mul_f32_e32 v152, v119, v119
	v_fmac_f32_e32 v152, v118, v118
	v_add_f32_e32 v145, v145, v152
	v_mul_f32_e32 v152, v85, v85
	v_mul_f32_e32 v153, v87, v87
	v_fmac_f32_e32 v152, v84, v84
	v_fmac_f32_e32 v153, v86, v86
	v_add_f32_e32 v152, v152, v153
	v_add_f32_e32 v145, v145, v152
	v_mul_f32_e32 v152, v53, v53
	v_mul_f32_e32 v153, v55, v55
	v_fmac_f32_e32 v152, v52, v52
	v_fmac_f32_e32 v153, v54, v54
	v_add_f32_e32 v152, v152, v153
	v_add_f32_e32 v145, v145, v152
	v_mul_f32_e32 v152, v21, v21
	v_mul_f32_e32 v153, v23, v23
	v_fmac_f32_e32 v152, v20, v20
	v_fmac_f32_e32 v153, v22, v22
	v_add_f32_e32 v152, v152, v153
	v_add_f32_e32 v145, v145, v152
	v_mov_b32_e32 v152, v145
	s_nop 1
	v_permlane16_swap_b32_e32 v145, v152
	v_add_f32_e32 v145, v145, v152
	v_mov_b32_e32 v152, v145
	s_nop 1
	v_permlane32_swap_b32_e32 v145, v152
	v_add_f32_e32 v145, v145, v152
	v_fmamk_f32 v145, v145, 0x3c800000, v149
	v_rsq_f32_e32 v160, v145
	v_pk_mul_f32 v[154:155], v[130:131], v[154:155]
	v_pk_mul_f32 v[158:159], v[128:129], v[158:159]
	s_mov_b32 s4, 0x8000
	v_cvt_pk_bf16_f32 v152, v158, v159
	v_cvt_pk_bf16_f32 v153, v154, v155
	global_store_dwordx4 v[156:157], v[150:153], off offset:64
	v_pk_mul_f32 v[154:155], v[84:85], v[160:161] op_sel_hi:[1,0]
	v_pk_mul_f32 v[156:157], v[86:87], v[160:161] op_sel_hi:[1,0]
	v_pk_mul_f32 v[150:151], v[116:117], v[160:161] op_sel_hi:[1,0]
	v_pk_mul_f32 v[152:153], v[118:119], v[160:161] op_sel_hi:[1,0]
	v_pk_mul_f32 v[150:151], v[140:141], v[150:151]
	v_pk_mul_f32 v[152:153], v[142:143], v[152:153]
	v_pk_mul_f32 v[154:155], v[136:137], v[154:155]
	v_cvt_pk_bf16_f32 v150, v150, v151
	v_cvt_pk_bf16_f32 v151, v152, v153
	v_pk_mul_f32 v[156:157], v[138:139], v[156:157]
	v_cvt_pk_bf16_f32 v152, v154, v155
	v_add_co_u32_e32 v154, vcc, s4, v146
	v_cvt_pk_bf16_f32 v153, v156, v157
	v_mul_f32_e32 v145, v113, v113
	s_nop 0
	v_addc_co_u32_e32 v155, vcc, 0, v147, vcc
	global_store_dwordx4 v[154:155], v[150:153], off
	v_fmac_f32_e32 v145, v112, v112
	v_pk_mul_f32 v[156:157], v[20:21], v[160:161] op_sel_hi:[1,0]
	v_pk_mul_f32 v[150:151], v[52:53], v[160:161] op_sel_hi:[1,0]
	v_pk_mul_f32 v[152:153], v[54:55], v[160:161] op_sel_hi:[1,0]
	v_pk_mul_f32 v[150:151], v[132:133], v[150:151]
	v_pk_mul_f32 v[152:153], v[134:135], v[152:153]
	v_cvt_pk_bf16_f32 v150, v150, v151
	v_pk_mul_f32 v[158:159], v[22:23], v[160:161] op_sel_hi:[1,0]
	v_cvt_pk_bf16_f32 v151, v152, v153
	v_mul_f32_e32 v152, v115, v115
	v_fmac_f32_e32 v152, v114, v114
	v_add_f32_e32 v145, v145, v152
	v_mul_f32_e32 v152, v81, v81
	v_mul_f32_e32 v153, v83, v83
	v_fmac_f32_e32 v152, v80, v80
	v_fmac_f32_e32 v153, v82, v82
	v_add_f32_e32 v152, v152, v153
	v_add_f32_e32 v145, v145, v152
	v_mul_f32_e32 v152, v49, v49
	v_mul_f32_e32 v153, v51, v51
	v_fmac_f32_e32 v152, v48, v48
	v_fmac_f32_e32 v153, v50, v50
	v_add_f32_e32 v152, v152, v153
	v_add_f32_e32 v145, v145, v152
	v_mul_f32_e32 v152, v17, v17
	v_mul_f32_e32 v153, v19, v19
	v_fmac_f32_e32 v152, v16, v16
	v_fmac_f32_e32 v153, v18, v18
	v_add_f32_e32 v152, v152, v153
	v_add_f32_e32 v145, v145, v152
	v_mov_b32_e32 v152, v145
	s_nop 1
	v_permlane16_swap_b32_e32 v145, v152
	v_add_f32_e32 v145, v145, v152
	v_mov_b32_e32 v152, v145
	s_nop 1
	v_permlane32_swap_b32_e32 v145, v152
	v_add_f32_e32 v145, v145, v152
	v_fmamk_f32 v145, v145, 0x3c800000, v149
	v_rsq_f32_e32 v160, v145
	v_pk_mul_f32 v[158:159], v[130:131], v[158:159]
	v_pk_mul_f32 v[156:157], v[128:129], v[156:157]
	s_mov_b32 s4, 0xc000
	v_cvt_pk_bf16_f32 v152, v156, v157
	v_cvt_pk_bf16_f32 v153, v158, v159
	global_store_dwordx4 v[154:155], v[150:153], off offset:64
	v_pk_mul_f32 v[154:155], v[80:81], v[160:161] op_sel_hi:[1,0]
	v_pk_mul_f32 v[156:157], v[82:83], v[160:161] op_sel_hi:[1,0]
	v_pk_mul_f32 v[150:151], v[112:113], v[160:161] op_sel_hi:[1,0]
	v_pk_mul_f32 v[152:153], v[114:115], v[160:161] op_sel_hi:[1,0]
	v_pk_mul_f32 v[150:151], v[140:141], v[150:151]
	v_pk_mul_f32 v[152:153], v[142:143], v[152:153]
	v_pk_mul_f32 v[154:155], v[136:137], v[154:155]
	v_cvt_pk_bf16_f32 v150, v150, v151
	v_cvt_pk_bf16_f32 v151, v152, v153
	v_pk_mul_f32 v[156:157], v[138:139], v[156:157]
	v_cvt_pk_bf16_f32 v152, v154, v155
	v_add_co_u32_e32 v154, vcc, s4, v146
	v_cvt_pk_bf16_f32 v153, v156, v157
	v_mul_f32_e32 v145, v109, v109
	s_nop 0
	v_addc_co_u32_e32 v155, vcc, 0, v147, vcc
	global_store_dwordx4 v[154:155], v[150:153], off
	v_fmac_f32_e32 v145, v108, v108
	v_pk_mul_f32 v[156:157], v[16:17], v[160:161] op_sel_hi:[1,0]
	v_pk_mul_f32 v[150:151], v[48:49], v[160:161] op_sel_hi:[1,0]
	v_pk_mul_f32 v[152:153], v[50:51], v[160:161] op_sel_hi:[1,0]
	v_pk_mul_f32 v[150:151], v[132:133], v[150:151]
	v_pk_mul_f32 v[152:153], v[134:135], v[152:153]
	v_cvt_pk_bf16_f32 v150, v150, v151
	v_pk_mul_f32 v[158:159], v[18:19], v[160:161] op_sel_hi:[1,0]
	v_cvt_pk_bf16_f32 v151, v152, v153
	v_mul_f32_e32 v152, v111, v111
	v_fmac_f32_e32 v152, v110, v110
	v_add_f32_e32 v145, v145, v152
	v_mul_f32_e32 v152, v77, v77
	v_mul_f32_e32 v153, v79, v79
	v_fmac_f32_e32 v152, v76, v76
	v_fmac_f32_e32 v153, v78, v78
	v_add_f32_e32 v152, v152, v153
	v_add_f32_e32 v145, v145, v152
	v_mul_f32_e32 v152, v45, v45
	v_mul_f32_e32 v153, v47, v47
	v_fmac_f32_e32 v152, v44, v44
	v_fmac_f32_e32 v153, v46, v46
	v_add_f32_e32 v152, v152, v153
	v_add_f32_e32 v145, v145, v152
	v_mul_f32_e32 v152, v13, v13
	v_mul_f32_e32 v153, v15, v15
	v_fmac_f32_e32 v152, v12, v12
	v_fmac_f32_e32 v153, v14, v14
	v_add_f32_e32 v152, v152, v153
	v_add_f32_e32 v145, v145, v152
	v_mov_b32_e32 v152, v145
	s_nop 1
	v_permlane16_swap_b32_e32 v145, v152
	v_add_f32_e32 v145, v145, v152
	v_mov_b32_e32 v152, v145
	s_nop 1
	v_permlane32_swap_b32_e32 v145, v152
	v_add_f32_e32 v145, v145, v152
	v_fmamk_f32 v145, v145, 0x3c800000, v149
	v_rsq_f32_e32 v160, v145
	v_pk_mul_f32 v[158:159], v[130:131], v[158:159]
	v_pk_mul_f32 v[156:157], v[128:129], v[156:157]
	s_mov_b32 s4, 0x20000
	v_cvt_pk_bf16_f32 v152, v156, v157
	v_cvt_pk_bf16_f32 v153, v158, v159
	global_store_dwordx4 v[154:155], v[150:153], off offset:64
	v_pk_mul_f32 v[154:155], v[76:77], v[160:161] op_sel_hi:[1,0]
	v_pk_mul_f32 v[156:157], v[78:79], v[160:161] op_sel_hi:[1,0]
	v_pk_mul_f32 v[150:151], v[108:109], v[160:161] op_sel_hi:[1,0]
	v_pk_mul_f32 v[152:153], v[110:111], v[160:161] op_sel_hi:[1,0]
	v_pk_mul_f32 v[150:151], v[140:141], v[150:151]
	v_pk_mul_f32 v[152:153], v[142:143], v[152:153]
	v_pk_mul_f32 v[154:155], v[136:137], v[154:155]
	v_cvt_pk_bf16_f32 v150, v150, v151
	v_cvt_pk_bf16_f32 v151, v152, v153
	v_pk_mul_f32 v[156:157], v[138:139], v[156:157]
	v_cvt_pk_bf16_f32 v152, v154, v155
	v_add_co_u32_e32 v154, vcc, s4, v146
	v_cvt_pk_bf16_f32 v153, v156, v157
	v_mul_f32_e32 v145, v105, v105
	s_nop 0
	v_addc_co_u32_e32 v155, vcc, 0, v147, vcc
	global_store_dwordx4 v[154:155], v[150:153], off
	v_fmac_f32_e32 v145, v104, v104
	v_pk_mul_f32 v[156:157], v[12:13], v[160:161] op_sel_hi:[1,0]
	v_pk_mul_f32 v[150:151], v[44:45], v[160:161] op_sel_hi:[1,0]
	v_pk_mul_f32 v[152:153], v[46:47], v[160:161] op_sel_hi:[1,0]
	v_pk_mul_f32 v[150:151], v[132:133], v[150:151]
	v_pk_mul_f32 v[152:153], v[134:135], v[152:153]
	v_cvt_pk_bf16_f32 v150, v150, v151
	v_pk_mul_f32 v[158:159], v[14:15], v[160:161] op_sel_hi:[1,0]
	v_cvt_pk_bf16_f32 v151, v152, v153
	v_mul_f32_e32 v152, v107, v107
	v_fmac_f32_e32 v152, v106, v106
	v_add_f32_e32 v145, v145, v152
	v_mul_f32_e32 v152, v73, v73
	v_mul_f32_e32 v153, v75, v75
	v_fmac_f32_e32 v152, v72, v72
	v_fmac_f32_e32 v153, v74, v74
	v_add_f32_e32 v152, v152, v153
	v_add_f32_e32 v145, v145, v152
	v_mul_f32_e32 v152, v41, v41
	v_mul_f32_e32 v153, v43, v43
	v_fmac_f32_e32 v152, v40, v40
	v_fmac_f32_e32 v153, v42, v42
	v_add_f32_e32 v152, v152, v153
	v_add_f32_e32 v145, v145, v152
	v_mul_f32_e32 v152, v9, v9
	v_mul_f32_e32 v153, v11, v11
	v_fmac_f32_e32 v152, v8, v8
	v_fmac_f32_e32 v153, v10, v10
	v_add_f32_e32 v152, v152, v153
	v_add_f32_e32 v145, v145, v152
	v_mov_b32_e32 v152, v145
	s_nop 1
	v_permlane16_swap_b32_e32 v145, v152
	v_add_f32_e32 v145, v145, v152
	v_mov_b32_e32 v152, v145
	s_nop 1
	v_permlane32_swap_b32_e32 v145, v152
	v_add_f32_e32 v145, v145, v152
	v_fmamk_f32 v145, v145, 0x3c800000, v149
	v_rsq_f32_e32 v160, v145
	v_pk_mul_f32 v[158:159], v[130:131], v[158:159]
	v_pk_mul_f32 v[156:157], v[128:129], v[156:157]
	s_mov_b32 s4, 0x24000
	v_cvt_pk_bf16_f32 v152, v156, v157
	v_cvt_pk_bf16_f32 v153, v158, v159
	global_store_dwordx4 v[154:155], v[150:153], off offset:64
	v_pk_mul_f32 v[154:155], v[72:73], v[160:161] op_sel_hi:[1,0]
	v_pk_mul_f32 v[156:157], v[74:75], v[160:161] op_sel_hi:[1,0]
	v_pk_mul_f32 v[150:151], v[104:105], v[160:161] op_sel_hi:[1,0]
	v_pk_mul_f32 v[152:153], v[106:107], v[160:161] op_sel_hi:[1,0]
	v_pk_mul_f32 v[150:151], v[140:141], v[150:151]
	v_pk_mul_f32 v[152:153], v[142:143], v[152:153]
	v_pk_mul_f32 v[154:155], v[136:137], v[154:155]
	v_cvt_pk_bf16_f32 v150, v150, v151
	v_cvt_pk_bf16_f32 v151, v152, v153
	v_pk_mul_f32 v[156:157], v[138:139], v[156:157]
	v_cvt_pk_bf16_f32 v152, v154, v155
	v_add_co_u32_e32 v154, vcc, s4, v146
	v_cvt_pk_bf16_f32 v153, v156, v157
	v_mul_f32_e32 v145, v101, v101
	s_nop 0
	v_addc_co_u32_e32 v155, vcc, 0, v147, vcc
	global_store_dwordx4 v[154:155], v[150:153], off
	v_fmac_f32_e32 v145, v100, v100
	v_pk_mul_f32 v[156:157], v[8:9], v[160:161] op_sel_hi:[1,0]
	v_pk_mul_f32 v[150:151], v[40:41], v[160:161] op_sel_hi:[1,0]
	v_pk_mul_f32 v[152:153], v[42:43], v[160:161] op_sel_hi:[1,0]
	v_pk_mul_f32 v[150:151], v[132:133], v[150:151]
	v_pk_mul_f32 v[152:153], v[134:135], v[152:153]
	v_cvt_pk_bf16_f32 v150, v150, v151
	v_pk_mul_f32 v[158:159], v[10:11], v[160:161] op_sel_hi:[1,0]
	v_cvt_pk_bf16_f32 v151, v152, v153
	v_mul_f32_e32 v152, v103, v103
	v_fmac_f32_e32 v152, v102, v102
	v_add_f32_e32 v145, v145, v152
	v_mul_f32_e32 v152, v69, v69
	v_mul_f32_e32 v153, v71, v71
	v_fmac_f32_e32 v152, v68, v68
	v_fmac_f32_e32 v153, v70, v70
	v_add_f32_e32 v152, v152, v153
	v_add_f32_e32 v145, v145, v152
	v_mul_f32_e32 v152, v37, v37
	v_mul_f32_e32 v153, v39, v39
	v_fmac_f32_e32 v152, v36, v36
	v_fmac_f32_e32 v153, v38, v38
	v_add_f32_e32 v152, v152, v153
	v_add_f32_e32 v145, v145, v152
	v_mul_f32_e32 v152, v5, v5
	v_mul_f32_e32 v153, v7, v7
	v_fmac_f32_e32 v152, v4, v4
	v_fmac_f32_e32 v153, v6, v6
	v_add_f32_e32 v152, v152, v153
	v_add_f32_e32 v145, v145, v152
	v_mov_b32_e32 v152, v145
	s_nop 1
	v_permlane16_swap_b32_e32 v145, v152
	v_add_f32_e32 v145, v145, v152
	v_mov_b32_e32 v152, v145
	s_nop 1
	v_permlane32_swap_b32_e32 v145, v152
	v_add_f32_e32 v145, v145, v152
	v_fmamk_f32 v145, v145, 0x3c800000, v149
	v_rsq_f32_e32 v160, v145
	v_pk_mul_f32 v[158:159], v[130:131], v[158:159]
	v_pk_mul_f32 v[156:157], v[128:129], v[156:157]
	s_mov_b32 s4, 0x28000
	v_cvt_pk_bf16_f32 v152, v156, v157
	v_cvt_pk_bf16_f32 v153, v158, v159
	global_store_dwordx4 v[154:155], v[150:153], off offset:64
	v_pk_mul_f32 v[154:155], v[68:69], v[160:161] op_sel_hi:[1,0]
	v_pk_mul_f32 v[156:157], v[70:71], v[160:161] op_sel_hi:[1,0]
	v_pk_mul_f32 v[150:151], v[100:101], v[160:161] op_sel_hi:[1,0]
	v_pk_mul_f32 v[152:153], v[102:103], v[160:161] op_sel_hi:[1,0]
	v_pk_mul_f32 v[150:151], v[140:141], v[150:151]
	v_pk_mul_f32 v[152:153], v[142:143], v[152:153]
	v_pk_mul_f32 v[154:155], v[136:137], v[154:155]
	v_cvt_pk_bf16_f32 v150, v150, v151
	v_cvt_pk_bf16_f32 v151, v152, v153
	v_pk_mul_f32 v[156:157], v[138:139], v[156:157]
	v_cvt_pk_bf16_f32 v152, v154, v155
	v_add_co_u32_e32 v154, vcc, s4, v146
	v_cvt_pk_bf16_f32 v153, v156, v157
	v_mul_f32_e32 v145, v97, v97
	s_nop 0
	v_addc_co_u32_e32 v155, vcc, 0, v147, vcc
	global_store_dwordx4 v[154:155], v[150:153], off
	v_fmac_f32_e32 v145, v96, v96
	v_pk_mul_f32 v[156:157], v[4:5], v[160:161] op_sel_hi:[1,0]
	v_pk_mul_f32 v[150:151], v[36:37], v[160:161] op_sel_hi:[1,0]
	v_pk_mul_f32 v[152:153], v[38:39], v[160:161] op_sel_hi:[1,0]
	v_pk_mul_f32 v[150:151], v[132:133], v[150:151]
	v_pk_mul_f32 v[152:153], v[134:135], v[152:153]
	v_cvt_pk_bf16_f32 v150, v150, v151
	v_pk_mul_f32 v[158:159], v[6:7], v[160:161] op_sel_hi:[1,0]
	v_cvt_pk_bf16_f32 v151, v152, v153
	v_mul_f32_e32 v152, v99, v99
	v_fmac_f32_e32 v152, v98, v98
	v_add_f32_e32 v145, v145, v152
	v_mul_f32_e32 v152, v65, v65
	v_mul_f32_e32 v153, v67, v67
	v_fmac_f32_e32 v152, v64, v64
	v_fmac_f32_e32 v153, v66, v66
	v_add_f32_e32 v152, v152, v153
	v_add_f32_e32 v145, v145, v152
	v_mul_f32_e32 v152, v33, v33
	v_mul_f32_e32 v153, v35, v35
	v_fmac_f32_e32 v152, v32, v32
	v_fmac_f32_e32 v153, v34, v34
	v_add_f32_e32 v152, v152, v153
	v_add_f32_e32 v145, v145, v152
	v_mul_f32_e32 v152, v1, v1
	v_mul_f32_e32 v153, v3, v3
	v_fmac_f32_e32 v152, v0, v0
	v_fmac_f32_e32 v153, v2, v2
	v_add_f32_e32 v152, v152, v153
	v_add_f32_e32 v145, v145, v152
	v_mov_b32_e32 v152, v145
	s_nop 1
	v_permlane16_swap_b32_e32 v145, v152
	v_add_f32_e32 v145, v145, v152
	v_mov_b32_e32 v152, v145
	s_nop 1
	v_permlane32_swap_b32_e32 v145, v152
	v_add_f32_e32 v145, v145, v152
	v_fmac_f32_e32 v149, 0x3c800000, v145
	v_rsq_f32_e32 v160, v149
	v_pk_mul_f32 v[158:159], v[130:131], v[158:159]
	v_pk_mul_f32 v[156:157], v[128:129], v[156:157]
	s_mov_b32 s4, 0x2c000
	v_cvt_pk_bf16_f32 v152, v156, v157
	v_cvt_pk_bf16_f32 v153, v158, v159
	global_store_dwordx4 v[154:155], v[150:153], off offset:64
	s_nop 1
	v_pk_mul_f32 v[150:151], v[96:97], v[160:161] op_sel_hi:[1,0]
	v_pk_mul_f32 v[152:153], v[98:99], v[160:161] op_sel_hi:[1,0]
	v_pk_mul_f32 v[140:141], v[140:141], v[150:151]
	v_pk_mul_f32 v[142:143], v[142:143], v[152:153]
	v_pk_mul_f32 v[150:151], v[64:65], v[160:161] op_sel_hi:[1,0]
	v_pk_mul_f32 v[152:153], v[66:67], v[160:161] op_sel_hi:[1,0]
	s_nop 0
	v_pk_mul_f32 v[152:153], v[138:139], v[152:153]
	v_pk_mul_f32 v[138:139], v[136:137], v[150:151]
	v_cvt_pk_bf16_f32 v136, v140, v141
	v_add_co_u32_e32 v140, vcc, s4, v146
	v_cvt_pk_bf16_f32 v137, v142, v143
	v_cvt_pk_bf16_f32 v138, v138, v139
	v_cvt_pk_bf16_f32 v139, v152, v153
	s_nop 1
	v_addc_co_u32_e32 v141, vcc, 0, v147, vcc
	global_store_dwordx4 v[140:141], v[136:139], off
	s_nop 1
	v_pk_mul_f32 v[136:137], v[32:33], v[160:161] op_sel_hi:[1,0]
	v_pk_mul_f32 v[138:139], v[34:35], v[160:161] op_sel_hi:[1,0]
	v_pk_mul_f32 v[132:133], v[132:133], v[136:137]
	v_pk_mul_f32 v[134:135], v[134:135], v[138:139]
	v_pk_mul_f32 v[136:137], v[0:1], v[160:161] op_sel_hi:[1,0]
	v_pk_mul_f32 v[138:139], v[2:3], v[160:161] op_sel_hi:[1,0]
	s_nop 0
	v_pk_mul_f32 v[138:139], v[130:131], v[138:139]
	v_pk_mul_f32 v[130:131], v[128:129], v[136:137]
	v_cvt_pk_bf16_f32 v128, v132, v133
	v_cvt_pk_bf16_f32 v129, v134, v135
	s_nop 0
	v_cvt_pk_bf16_f32 v130, v130, v131
	v_cvt_pk_bf16_f32 v131, v138, v139
	global_store_dwordx4 v[140:141], v[128:131], off offset:64
.LBB0_215:
	s_andn2_b64 vcc, exec, s[10:11]
	s_cbranch_vccnz .LBB0_217
	s_lshl_b32 s4, s7, 5
	s_lshl_b32 s5, s5, 8
	s_or_b32 s4, s4, s5
	s_lshl_b32 s5, s6, 9
	s_mul_i32 s7, s6, 0xffffffef
	s_or_b32 s4, s4, s5
	s_add_i32 s7, s8, s7
	v_or_b32_e32 v128, s4, v148
	s_movk_i32 s4, 0x2200
	v_lshl_add_u32 v130, s7, 8, v144
	v_mul_lo_u32 v128, v128, s4
	v_mov_b32_e32 v129, 0
	v_ashrrev_i32_e32 v131, 31, v130
	v_lshl_add_u64 v[132:133], s[76:77], 0, v[128:129]
	v_lshl_add_u64 v[130:131], v[130:131], 1, v[132:133]
	v_bfe_u32 v172, v217, 3, 1
	v_mul_u32_u24_e32 v172, 0x21f0, v172
	v_mov_b32_e32 v173, 0
	v_lshl_add_u64 v[174:175], v[130:131], 0, v[172:173]
	v_add_co_u32_e32 v178, vcc, 0x43e0, v174
	s_nop 1
	v_addc_co_u32_e32 v179, vcc, 0, v175, vcc
	v_cvt_pk_bf16_f32 v124, v124, v173
	global_store_short v[174:175], v124, off
	v_cvt_pk_bf16_f32 v125, v125, v173
	global_store_short v[174:175], v125, off offset:16
	v_cvt_pk_bf16_f32 v126, v126, v173
	global_store_short v[174:175], v126, off offset:32
	v_cvt_pk_bf16_f32 v127, v127, v173
	global_store_short v[174:175], v127, off offset:48
	v_cvt_pk_bf16_f32 v120, v120, v173
	global_store_short v[178:179], v120, off offset:32
	v_cvt_pk_bf16_f32 v121, v121, v173
	global_store_short v[178:179], v121, off offset:48
	v_cvt_pk_bf16_f32 v122, v122, v173
	global_store_short v[178:179], v122, off offset:64
	v_cvt_pk_bf16_f32 v123, v123, v173
	global_store_short v[178:179], v123, off offset:80
	v_cvt_pk_bf16_f32 v116, v116, v173
	global_store_short v[174:175], v116, off offset:64
	v_cvt_pk_bf16_f32 v117, v117, v173
	global_store_short v[174:175], v117, off offset:80
	v_cvt_pk_bf16_f32 v118, v118, v173
	global_store_short v[174:175], v118, off offset:96
	v_cvt_pk_bf16_f32 v119, v119, v173
	global_store_short v[174:175], v119, off offset:112
	v_cvt_pk_bf16_f32 v112, v112, v173
	global_store_short v[178:179], v112, off offset:96
	v_cvt_pk_bf16_f32 v113, v113, v173
	global_store_short v[178:179], v113, off offset:112
	v_cvt_pk_bf16_f32 v114, v114, v173
	global_store_short v[178:179], v114, off offset:128
	v_cvt_pk_bf16_f32 v115, v115, v173
	global_store_short v[178:179], v115, off offset:144
	v_cvt_pk_bf16_f32 v108, v108, v173
	global_store_short v[174:175], v108, off offset:256
	v_cvt_pk_bf16_f32 v109, v109, v173
	global_store_short v[174:175], v109, off offset:272
	v_cvt_pk_bf16_f32 v110, v110, v173
	global_store_short v[174:175], v110, off offset:288
	v_cvt_pk_bf16_f32 v111, v111, v173
	global_store_short v[174:175], v111, off offset:304
	v_cvt_pk_bf16_f32 v104, v104, v173
	global_store_short v[178:179], v104, off offset:288
	v_cvt_pk_bf16_f32 v105, v105, v173
	global_store_short v[178:179], v105, off offset:304
	v_cvt_pk_bf16_f32 v106, v106, v173
	global_store_short v[178:179], v106, off offset:320
	v_cvt_pk_bf16_f32 v107, v107, v173
	global_store_short v[178:179], v107, off offset:336
	v_cvt_pk_bf16_f32 v100, v100, v173
	global_store_short v[174:175], v100, off offset:320
	v_cvt_pk_bf16_f32 v101, v101, v173
	global_store_short v[174:175], v101, off offset:336
	v_cvt_pk_bf16_f32 v102, v102, v173
	global_store_short v[174:175], v102, off offset:352
	v_cvt_pk_bf16_f32 v103, v103, v173
	global_store_short v[174:175], v103, off offset:368
	v_cvt_pk_bf16_f32 v96, v96, v173
	global_store_short v[178:179], v96, off offset:352
	v_cvt_pk_bf16_f32 v97, v97, v173
	global_store_short v[178:179], v97, off offset:368
	v_cvt_pk_bf16_f32 v98, v98, v173
	global_store_short v[178:179], v98, off offset:384
	v_cvt_pk_bf16_f32 v99, v99, v173
	global_store_short v[178:179], v99, off offset:400
	v_add_co_u32_e32 v176, vcc, 0x8800, v174
	s_nop 1
	v_addc_co_u32_e32 v177, vcc, 0, v175, vcc
	v_add_co_u32_e32 v178, vcc, 0x43e0, v176
	s_nop 1
	v_addc_co_u32_e32 v179, vcc, 0, v177, vcc
	v_cvt_pk_bf16_f32 v92, v92, v173
	global_store_short v[176:177], v92, off
	v_cvt_pk_bf16_f32 v93, v93, v173
	global_store_short v[176:177], v93, off offset:16
	v_cvt_pk_bf16_f32 v94, v94, v173
	global_store_short v[176:177], v94, off offset:32
	v_cvt_pk_bf16_f32 v95, v95, v173
	global_store_short v[176:177], v95, off offset:48
	v_cvt_pk_bf16_f32 v88, v88, v173
	global_store_short v[178:179], v88, off offset:32
	v_cvt_pk_bf16_f32 v89, v89, v173
	global_store_short v[178:179], v89, off offset:48
	v_cvt_pk_bf16_f32 v90, v90, v173
	global_store_short v[178:179], v90, off offset:64
	v_cvt_pk_bf16_f32 v91, v91, v173
	global_store_short v[178:179], v91, off offset:80
	v_cvt_pk_bf16_f32 v84, v84, v173
	global_store_short v[176:177], v84, off offset:64
	v_cvt_pk_bf16_f32 v85, v85, v173
	global_store_short v[176:177], v85, off offset:80
	v_cvt_pk_bf16_f32 v86, v86, v173
	global_store_short v[176:177], v86, off offset:96
	v_cvt_pk_bf16_f32 v87, v87, v173
	global_store_short v[176:177], v87, off offset:112
	v_cvt_pk_bf16_f32 v80, v80, v173
	global_store_short v[178:179], v80, off offset:96
	v_cvt_pk_bf16_f32 v81, v81, v173
	global_store_short v[178:179], v81, off offset:112
	v_cvt_pk_bf16_f32 v82, v82, v173
	global_store_short v[178:179], v82, off offset:128
	v_cvt_pk_bf16_f32 v83, v83, v173
	global_store_short v[178:179], v83, off offset:144
	v_cvt_pk_bf16_f32 v76, v76, v173
	global_store_short v[176:177], v76, off offset:256
	v_cvt_pk_bf16_f32 v77, v77, v173
	global_store_short v[176:177], v77, off offset:272
	v_cvt_pk_bf16_f32 v78, v78, v173
	global_store_short v[176:177], v78, off offset:288
	v_cvt_pk_bf16_f32 v79, v79, v173
	global_store_short v[176:177], v79, off offset:304
	v_cvt_pk_bf16_f32 v72, v72, v173
	global_store_short v[178:179], v72, off offset:288
	v_cvt_pk_bf16_f32 v73, v73, v173
	global_store_short v[178:179], v73, off offset:304
	v_cvt_pk_bf16_f32 v74, v74, v173
	global_store_short v[178:179], v74, off offset:320
	v_cvt_pk_bf16_f32 v75, v75, v173
	global_store_short v[178:179], v75, off offset:336
	v_cvt_pk_bf16_f32 v68, v68, v173
	global_store_short v[176:177], v68, off offset:320
	v_cvt_pk_bf16_f32 v69, v69, v173
	global_store_short v[176:177], v69, off offset:336
	v_cvt_pk_bf16_f32 v70, v70, v173
	global_store_short v[176:177], v70, off offset:352
	v_cvt_pk_bf16_f32 v71, v71, v173
	global_store_short v[176:177], v71, off offset:368
	v_cvt_pk_bf16_f32 v64, v64, v173
	global_store_short v[178:179], v64, off offset:352
	v_cvt_pk_bf16_f32 v65, v65, v173
	global_store_short v[178:179], v65, off offset:368
	v_cvt_pk_bf16_f32 v66, v66, v173
	global_store_short v[178:179], v66, off offset:384
	v_cvt_pk_bf16_f32 v67, v67, v173
	global_store_short v[178:179], v67, off offset:400
	v_add_co_u32_e32 v176, vcc, 0x110000, v174
	s_nop 1
	v_addc_co_u32_e32 v177, vcc, 0, v175, vcc
	v_add_co_u32_e32 v178, vcc, 0x43e0, v176
	s_nop 1
	v_addc_co_u32_e32 v179, vcc, 0, v177, vcc
	v_cvt_pk_bf16_f32 v60, v60, v173
	global_store_short v[176:177], v60, off
	v_cvt_pk_bf16_f32 v61, v61, v173
	global_store_short v[176:177], v61, off offset:16
	v_cvt_pk_bf16_f32 v62, v62, v173
	global_store_short v[176:177], v62, off offset:32
	v_cvt_pk_bf16_f32 v63, v63, v173
	global_store_short v[176:177], v63, off offset:48
	v_cvt_pk_bf16_f32 v56, v56, v173
	global_store_short v[178:179], v56, off offset:32
	v_cvt_pk_bf16_f32 v57, v57, v173
	global_store_short v[178:179], v57, off offset:48
	v_cvt_pk_bf16_f32 v58, v58, v173
	global_store_short v[178:179], v58, off offset:64
	v_cvt_pk_bf16_f32 v59, v59, v173
	global_store_short v[178:179], v59, off offset:80
	v_cvt_pk_bf16_f32 v52, v52, v173
	global_store_short v[176:177], v52, off offset:64
	v_cvt_pk_bf16_f32 v53, v53, v173
	global_store_short v[176:177], v53, off offset:80
	v_cvt_pk_bf16_f32 v54, v54, v173
	global_store_short v[176:177], v54, off offset:96
	v_cvt_pk_bf16_f32 v55, v55, v173
	global_store_short v[176:177], v55, off offset:112
	v_cvt_pk_bf16_f32 v48, v48, v173
	global_store_short v[178:179], v48, off offset:96
	v_cvt_pk_bf16_f32 v49, v49, v173
	global_store_short v[178:179], v49, off offset:112
	v_cvt_pk_bf16_f32 v50, v50, v173
	global_store_short v[178:179], v50, off offset:128
	v_cvt_pk_bf16_f32 v51, v51, v173
	global_store_short v[178:179], v51, off offset:144
	v_cvt_pk_bf16_f32 v44, v44, v173
	global_store_short v[176:177], v44, off offset:256
	v_cvt_pk_bf16_f32 v45, v45, v173
	global_store_short v[176:177], v45, off offset:272
	v_cvt_pk_bf16_f32 v46, v46, v173
	global_store_short v[176:177], v46, off offset:288
	v_cvt_pk_bf16_f32 v47, v47, v173
	global_store_short v[176:177], v47, off offset:304
	v_cvt_pk_bf16_f32 v40, v40, v173
	global_store_short v[178:179], v40, off offset:288
	v_cvt_pk_bf16_f32 v41, v41, v173
	global_store_short v[178:179], v41, off offset:304
	v_cvt_pk_bf16_f32 v42, v42, v173
	global_store_short v[178:179], v42, off offset:320
	v_cvt_pk_bf16_f32 v43, v43, v173
	global_store_short v[178:179], v43, off offset:336
	v_cvt_pk_bf16_f32 v36, v36, v173
	global_store_short v[176:177], v36, off offset:320
	v_cvt_pk_bf16_f32 v37, v37, v173
	global_store_short v[176:177], v37, off offset:336
	v_cvt_pk_bf16_f32 v38, v38, v173
	global_store_short v[176:177], v38, off offset:352
	v_cvt_pk_bf16_f32 v39, v39, v173
	global_store_short v[176:177], v39, off offset:368
	v_cvt_pk_bf16_f32 v32, v32, v173
	global_store_short v[178:179], v32, off offset:352
	v_cvt_pk_bf16_f32 v33, v33, v173
	global_store_short v[178:179], v33, off offset:368
	v_cvt_pk_bf16_f32 v34, v34, v173
	global_store_short v[178:179], v34, off offset:384
	v_cvt_pk_bf16_f32 v35, v35, v173
	global_store_short v[178:179], v35, off offset:400
	v_add_co_u32_e32 v176, vcc, 0x118800, v174
	s_nop 1
	v_addc_co_u32_e32 v177, vcc, 0, v175, vcc
	v_add_co_u32_e32 v178, vcc, 0x43e0, v176
	s_nop 1
	v_addc_co_u32_e32 v179, vcc, 0, v177, vcc
	v_cvt_pk_bf16_f32 v28, v28, v173
	global_store_short v[176:177], v28, off
	v_cvt_pk_bf16_f32 v29, v29, v173
	global_store_short v[176:177], v29, off offset:16
	v_cvt_pk_bf16_f32 v30, v30, v173
	global_store_short v[176:177], v30, off offset:32
	v_cvt_pk_bf16_f32 v31, v31, v173
	global_store_short v[176:177], v31, off offset:48
	v_cvt_pk_bf16_f32 v24, v24, v173
	global_store_short v[178:179], v24, off offset:32
	v_cvt_pk_bf16_f32 v25, v25, v173
	global_store_short v[178:179], v25, off offset:48
	v_cvt_pk_bf16_f32 v26, v26, v173
	global_store_short v[178:179], v26, off offset:64
	v_cvt_pk_bf16_f32 v27, v27, v173
	global_store_short v[178:179], v27, off offset:80
	v_cvt_pk_bf16_f32 v20, v20, v173
	global_store_short v[176:177], v20, off offset:64
	v_cvt_pk_bf16_f32 v21, v21, v173
	global_store_short v[176:177], v21, off offset:80
	v_cvt_pk_bf16_f32 v22, v22, v173
	global_store_short v[176:177], v22, off offset:96
	v_cvt_pk_bf16_f32 v23, v23, v173
	global_store_short v[176:177], v23, off offset:112
	v_cvt_pk_bf16_f32 v16, v16, v173
	global_store_short v[178:179], v16, off offset:96
	v_cvt_pk_bf16_f32 v17, v17, v173
	global_store_short v[178:179], v17, off offset:112
	v_cvt_pk_bf16_f32 v18, v18, v173
	global_store_short v[178:179], v18, off offset:128
	v_cvt_pk_bf16_f32 v19, v19, v173
	global_store_short v[178:179], v19, off offset:144
	v_cvt_pk_bf16_f32 v12, v12, v173
	global_store_short v[176:177], v12, off offset:256
	v_cvt_pk_bf16_f32 v13, v13, v173
	global_store_short v[176:177], v13, off offset:272
	v_cvt_pk_bf16_f32 v14, v14, v173
	global_store_short v[176:177], v14, off offset:288
	v_cvt_pk_bf16_f32 v15, v15, v173
	global_store_short v[176:177], v15, off offset:304
	v_cvt_pk_bf16_f32 v8, v8, v173
	global_store_short v[178:179], v8, off offset:288
	v_cvt_pk_bf16_f32 v9, v9, v173
	global_store_short v[178:179], v9, off offset:304
	v_cvt_pk_bf16_f32 v10, v10, v173
	global_store_short v[178:179], v10, off offset:320
	v_cvt_pk_bf16_f32 v11, v11, v173
	global_store_short v[178:179], v11, off offset:336
	v_cvt_pk_bf16_f32 v4, v4, v173
	global_store_short v[176:177], v4, off offset:320
	v_cvt_pk_bf16_f32 v5, v5, v173
	global_store_short v[176:177], v5, off offset:336
	v_cvt_pk_bf16_f32 v6, v6, v173
	global_store_short v[176:177], v6, off offset:352
	v_cvt_pk_bf16_f32 v7, v7, v173
	global_store_short v[176:177], v7, off offset:368
	v_cvt_pk_bf16_f32 v0, v0, v173
	global_store_short v[178:179], v0, off offset:352
	v_cvt_pk_bf16_f32 v1, v1, v173
	global_store_short v[178:179], v1, off offset:368
	v_cvt_pk_bf16_f32 v2, v2, v173
	global_store_short v[178:179], v2, off offset:384
	v_cvt_pk_bf16_f32 v3, v3, v173
	global_store_short v[178:179], v3, off offset:400

.LBB0_359:
	s_and_b64 vcc, exec, s[0:1]
	s_cbranch_vccz .LBB0_361
	s_cmp_eq_u32 s59, 3
	s_cselect_b64 vcc, -1, 0
	s_and_b64 s[0:1], vcc, exec
	s_cselect_b32 s1, s23, s25
	s_cselect_b32 s0, s22, s24
	global_load_dwordx4 v[146:149], v167, s[0:1]
	global_load_dwordx4 v[150:153], v167, s[0:1] offset:16
	global_load_dwordx4 v[172:175], v167, s[0:1] offset:128
	global_load_dwordx4 v[176:179], v167, s[0:1] offset:144
	v_mul_f32_e32 v154, v125, v125
	v_mul_f32_e32 v155, v127, v127
	v_mul_f32_e32 v156, v93, v93
	v_mul_f32_e32 v157, v95, v95
	v_mul_f32_e32 v158, v61, v61
	v_mul_f32_e32 v159, v63, v63
	v_fmac_f32_e32 v154, v124, v124
	v_fmac_f32_e32 v155, v126, v126
	v_fmac_f32_e32 v156, v92, v92
	v_fmac_f32_e32 v157, v94, v94
	v_mul_f32_e32 v160, v29, v29
	v_mul_f32_e32 v161, v31, v31
	v_fmac_f32_e32 v158, v60, v60
	v_fmac_f32_e32 v159, v62, v62
	v_add_f32_e32 v154, v154, v155
	v_add_f32_e32 v155, v156, v157
	v_fmac_f32_e32 v160, v28, v28
	v_fmac_f32_e32 v161, v30, v30
	v_add_f32_e32 v156, v158, v159
	v_add_f32_e32 v154, v154, v155
	v_add_f32_e32 v157, v160, v161
	v_add_f32_e32 v154, v154, v156
	v_add_f32_e32 v154, v154, v157
	v_mov_b32_e32 v155, v154
	s_nop 1
	v_permlane16_swap_b32_e32 v154, v155
	v_add_f32_e32 v154, v154, v155
	v_mov_b32_e32 v155, v154
	s_nop 1
	v_permlane32_swap_b32_e32 v154, v155
	v_add_f32_e32 v154, v154, v155
	v_fmamk_f32 v154, v154, 0x3c800000, v169
	v_rsq_f32_e32 v154, v154
	v_readlane_b32 s68, v252, 0
	v_mul_f32_e32 v181, v121, v121
	v_mul_f32_e32 v182, v123, v123
	v_readlane_b32 s70, v252, 2
	v_readlane_b32 s71, v252, 3
	v_readlane_b32 s72, v252, 4
	v_readlane_b32 s73, v252, 5
	v_cndmask_b32_e32 v180, 1.0, v170, vcc
	v_lshl_or_b32 v136, s57, 9, v168
	v_fmac_f32_e32 v181, v120, v120
	v_fmac_f32_e32 v182, v122, v122
	s_cselect_b32 s1, s71, s73
	s_cselect_b32 s0, s70, s72
	v_bfe_u32 v253, v217, 4, 2
	v_and_b32_e32 v254, 3, v217
	v_sub_u32_e32 v253, v253, v254
	v_cndmask_b32_e64 v253, v253, 0, vcc
	v_add_u32_e32 v144, v144, v253
	v_lshlrev_b32_e32 v253, 4, v253
	v_sub_u32_e32 v136, v136, v253
	v_lshlrev_b64 v[144:145], 10, v[144:145]
	v_add_f32_e32 v200, v181, v182
	v_lshl_add_u64 v[156:157], s[0:1], 0, v[136:137]
	v_pk_mul_f32 v[182:183], v[124:125], v[154:155] op_sel_hi:[1,0]
	v_pk_mul_f32 v[184:185], v[126:127], v[154:155] op_sel_hi:[1,0]
	v_lshl_add_u64 v[144:145], v[156:157], 0, v[144:145]
	v_pk_mul_f32 v[186:187], v[92:93], v[154:155] op_sel_hi:[1,0]
	v_pk_mul_f32 v[188:189], v[94:95], v[154:155] op_sel_hi:[1,0]
	v_pk_mul_f32 v[190:191], v[60:61], v[154:155] op_sel_hi:[1,0]
	v_pk_mul_f32 v[192:193], v[62:63], v[154:155] op_sel_hi:[1,0]
	v_pk_mul_f32 v[194:195], v[28:29], v[154:155] op_sel_hi:[1,0]
	v_pk_mul_f32 v[196:197], v[30:31], v[154:155] op_sel_hi:[1,0]
	v_mul_f32_e32 v198, v89, v89
	v_mul_f32_e32 v199, v91, v91
	v_fmac_f32_e32 v198, v88, v88
	v_fmac_f32_e32 v199, v90, v90
	v_add_f32_e32 v136, v198, v199
	v_add_f32_e32 v136, v200, v136
	s_movk_i32 s0, 0x4000
	v_readlane_b32 s69, v252, 1
	v_readlane_b32 s74, v252, 6
	v_readlane_b32 s75, v252, 7
	s_waitcnt vmcnt(0)
	v_pk_mul_f32 v[158:159], v[180:181], v[148:149] op_sel_hi:[0,1]
	v_pk_mul_f32 v[160:161], v[180:181], v[146:147] op_sel_hi:[0,1]
	v_pk_mul_f32 v[154:155], v[180:181], v[152:153] op_sel_hi:[0,1]
	v_pk_mul_f32 v[156:157], v[180:181], v[150:151] op_sel_hi:[0,1]
	v_pk_mul_f32 v[150:151], v[180:181], v[174:175] op_sel_hi:[0,1]
	v_pk_mul_f32 v[152:153], v[180:181], v[172:173] op_sel_hi:[0,1]
	v_pk_mul_f32 v[174:175], v[158:159], v[184:185]
	v_pk_mul_f32 v[172:173], v[160:161], v[182:183]
	v_pk_mul_f32 v[146:147], v[180:181], v[178:179] op_sel_hi:[0,1]
	v_pk_mul_f32 v[148:149], v[180:181], v[176:177] op_sel_hi:[0,1]
	v_pk_mul_f32 v[176:177], v[154:155], v[188:189]
	v_pk_mul_f32 v[178:179], v[156:157], v[186:187]
	v_cvt_pk_bf16_f32 v172, v172, v173
	v_cvt_pk_bf16_f32 v173, v174, v175
	v_pk_mul_f32 v[180:181], v[150:151], v[192:193]
	v_cvt_pk_bf16_f32 v174, v178, v179
	v_cvt_pk_bf16_f32 v175, v176, v177
	global_store_dwordx4 v[144:145], v[172:175], off
	v_pk_mul_f32 v[182:183], v[152:153], v[190:191]
	v_pk_mul_f32 v[184:185], v[146:147], v[196:197]
	v_mul_f32_e32 v174, v57, v57
	v_mul_f32_e32 v175, v59, v59
	v_fmac_f32_e32 v174, v56, v56
	v_fmac_f32_e32 v175, v58, v58
	v_add_f32_e32 v174, v174, v175
	v_add_f32_e32 v136, v136, v174
	v_mul_f32_e32 v174, v25, v25
	v_mul_f32_e32 v175, v27, v27
	v_fmac_f32_e32 v174, v24, v24
	v_fmac_f32_e32 v175, v26, v26
	v_add_f32_e32 v174, v174, v175
	v_add_f32_e32 v136, v136, v174
	v_mov_b32_e32 v174, v136
	s_nop 1
	v_permlane16_swap_b32_e32 v136, v174
	v_add_f32_e32 v136, v136, v174
	v_mov_b32_e32 v174, v136
	s_nop 1
	v_permlane32_swap_b32_e32 v136, v174
	v_add_f32_e32 v136, v136, v174
	v_fmamk_f32 v136, v136, 0x3c800000, v169
	v_rsq_f32_e32 v136, v136
	v_pk_mul_f32 v[186:187], v[148:149], v[194:195]
	v_cvt_pk_bf16_f32 v172, v182, v183
	v_cvt_pk_bf16_f32 v173, v180, v181
	v_pk_mul_f32 v[176:177], v[88:89], v[136:137] op_sel_hi:[1,0]
	v_cvt_pk_bf16_f32 v174, v186, v187
	v_cvt_pk_bf16_f32 v175, v184, v185
	global_store_dwordx4 v[144:145], v[172:175], off offset:64
	v_pk_mul_f32 v[176:177], v[156:157], v[176:177]
	v_pk_mul_f32 v[178:179], v[90:91], v[136:137] op_sel_hi:[1,0]
	v_pk_mul_f32 v[172:173], v[120:121], v[136:137] op_sel_hi:[1,0]
	v_pk_mul_f32 v[174:175], v[122:123], v[136:137] op_sel_hi:[1,0]
	v_pk_mul_f32 v[172:173], v[160:161], v[172:173]
	v_pk_mul_f32 v[174:175], v[158:159], v[174:175]
	v_cvt_pk_bf16_f32 v172, v172, v173
	v_pk_mul_f32 v[178:179], v[154:155], v[178:179]
	v_cvt_pk_bf16_f32 v173, v174, v175
	v_cvt_pk_bf16_f32 v174, v176, v177
	v_add_co_u32_e32 v176, vcc, s0, v144
	v_cvt_pk_bf16_f32 v175, v178, v179
	v_pk_mul_f32 v[178:179], v[24:25], v[136:137] op_sel_hi:[1,0]
	s_nop 0
	v_addc_co_u32_e32 v177, vcc, 0, v145, vcc
	global_store_dwordx4 v[176:177], v[172:175], off
	v_pk_mul_f32 v[180:181], v[26:27], v[136:137] op_sel_hi:[1,0]
	v_pk_mul_f32 v[178:179], v[148:149], v[178:179]
	v_pk_mul_f32 v[172:173], v[56:57], v[136:137] op_sel_hi:[1,0]
	v_pk_mul_f32 v[174:175], v[58:59], v[136:137] op_sel_hi:[1,0]
	v_pk_mul_f32 v[172:173], v[152:153], v[172:173]
	v_pk_mul_f32 v[174:175], v[150:151], v[174:175]
	v_cvt_pk_bf16_f32 v172, v172, v173
	v_mul_f32_e32 v136, v117, v117
	v_cvt_pk_bf16_f32 v173, v174, v175
	v_mul_f32_e32 v174, v119, v119
	v_fmac_f32_e32 v136, v116, v116
	v_fmac_f32_e32 v174, v118, v118
	v_add_f32_e32 v136, v136, v174
	v_mul_f32_e32 v174, v85, v85
	v_mul_f32_e32 v175, v87, v87
	v_fmac_f32_e32 v174, v84, v84
	v_fmac_f32_e32 v175, v86, v86
	v_add_f32_e32 v174, v174, v175
	v_add_f32_e32 v136, v136, v174
	v_mul_f32_e32 v174, v53, v53
	v_mul_f32_e32 v175, v55, v55
	v_fmac_f32_e32 v174, v52, v52
	v_fmac_f32_e32 v175, v54, v54
	v_add_f32_e32 v174, v174, v175
	v_add_f32_e32 v136, v136, v174
	v_mul_f32_e32 v174, v21, v21
	v_mul_f32_e32 v175, v23, v23
	v_fmac_f32_e32 v174, v20, v20
	v_fmac_f32_e32 v175, v22, v22
	v_add_f32_e32 v174, v174, v175
	v_add_f32_e32 v136, v136, v174
	v_mov_b32_e32 v174, v136
	s_nop 1
	v_permlane16_swap_b32_e32 v136, v174
	v_add_f32_e32 v136, v136, v174
	v_mov_b32_e32 v174, v136
	s_nop 1
	v_permlane32_swap_b32_e32 v136, v174
	v_add_f32_e32 v136, v136, v174
	v_fmamk_f32 v136, v136, 0x3c800000, v169
	v_rsq_f32_e32 v136, v136
	v_pk_mul_f32 v[180:181], v[146:147], v[180:181]
	v_cvt_pk_bf16_f32 v174, v178, v179
	v_pk_mul_f32 v[178:179], v[86:87], v[136:137] op_sel_hi:[1,0]
	v_cvt_pk_bf16_f32 v175, v180, v181
	global_store_dwordx4 v[176:177], v[172:175], off offset:64
	v_pk_mul_f32 v[176:177], v[84:85], v[136:137] op_sel_hi:[1,0]
	v_pk_mul_f32 v[178:179], v[154:155], v[178:179]
	v_pk_mul_f32 v[172:173], v[116:117], v[136:137] op_sel_hi:[1,0]
	v_pk_mul_f32 v[174:175], v[118:119], v[136:137] op_sel_hi:[1,0]
	v_pk_mul_f32 v[172:173], v[160:161], v[172:173]
	v_pk_mul_f32 v[174:175], v[158:159], v[174:175]
	v_pk_mul_f32 v[176:177], v[156:157], v[176:177]
	v_cvt_pk_bf16_f32 v172, v172, v173
	v_cvt_pk_bf16_f32 v173, v174, v175
	v_pk_mul_f32 v[180:181], v[22:23], v[136:137] op_sel_hi:[1,0]
	v_cvt_pk_bf16_f32 v174, v176, v177
	v_add_co_u32_e32 v176, vcc, s88, v144
	v_cvt_pk_bf16_f32 v175, v178, v179
	v_pk_mul_f32 v[178:179], v[20:21], v[136:137] op_sel_hi:[1,0]
	s_nop 0
	v_addc_co_u32_e32 v177, vcc, 0, v145, vcc
	global_store_dwordx4 v[176:177], v[172:175], off
	v_pk_mul_f32 v[180:181], v[146:147], v[180:181]
	v_pk_mul_f32 v[178:179], v[148:149], v[178:179]
	v_pk_mul_f32 v[172:173], v[52:53], v[136:137] op_sel_hi:[1,0]
	v_pk_mul_f32 v[174:175], v[54:55], v[136:137] op_sel_hi:[1,0]
	v_pk_mul_f32 v[172:173], v[152:153], v[172:173]
	v_pk_mul_f32 v[174:175], v[150:151], v[174:175]
	v_cvt_pk_bf16_f32 v172, v172, v173
	v_mul_f32_e32 v136, v113, v113
	v_cvt_pk_bf16_f32 v173, v174, v175
	v_mul_f32_e32 v174, v115, v115
	v_fmac_f32_e32 v136, v112, v112
	v_fmac_f32_e32 v174, v114, v114
	v_add_f32_e32 v136, v136, v174
	v_mul_f32_e32 v174, v81, v81
	v_mul_f32_e32 v175, v83, v83
	v_fmac_f32_e32 v174, v80, v80
	v_fmac_f32_e32 v175, v82, v82
	v_add_f32_e32 v174, v174, v175
	v_add_f32_e32 v136, v136, v174
	v_mul_f32_e32 v174, v49, v49
	v_mul_f32_e32 v175, v51, v51
	v_fmac_f32_e32 v174, v48, v48
	v_fmac_f32_e32 v175, v50, v50
	v_add_f32_e32 v174, v174, v175
	v_add_f32_e32 v136, v136, v174
	v_mul_f32_e32 v174, v17, v17
	v_mul_f32_e32 v175, v19, v19
	v_fmac_f32_e32 v174, v16, v16
	v_fmac_f32_e32 v175, v18, v18
	v_add_f32_e32 v174, v174, v175
	v_add_f32_e32 v136, v136, v174
	v_mov_b32_e32 v174, v136
	s_nop 1
	v_permlane16_swap_b32_e32 v136, v174
	v_add_f32_e32 v136, v136, v174
	v_mov_b32_e32 v174, v136
	s_nop 1
	v_permlane32_swap_b32_e32 v136, v174
	v_add_f32_e32 v136, v136, v174
	v_fmamk_f32 v136, v136, 0x3c800000, v169
	v_rsq_f32_e32 v136, v136
	v_cvt_pk_bf16_f32 v174, v178, v179
	v_cvt_pk_bf16_f32 v175, v180, v181
	global_store_dwordx4 v[176:177], v[172:175], off offset:64
	v_pk_mul_f32 v[176:177], v[80:81], v[136:137] op_sel_hi:[1,0]
	v_pk_mul_f32 v[178:179], v[82:83], v[136:137] op_sel_hi:[1,0]
	v_pk_mul_f32 v[172:173], v[112:113], v[136:137] op_sel_hi:[1,0]
	v_pk_mul_f32 v[174:175], v[114:115], v[136:137] op_sel_hi:[1,0]
	v_pk_mul_f32 v[172:173], v[160:161], v[172:173]
	v_pk_mul_f32 v[174:175], v[158:159], v[174:175]
	v_pk_mul_f32 v[176:177], v[156:157], v[176:177]
	v_cvt_pk_bf16_f32 v172, v172, v173
	v_cvt_pk_bf16_f32 v173, v174, v175
	v_pk_mul_f32 v[178:179], v[154:155], v[178:179]
	v_cvt_pk_bf16_f32 v174, v176, v177
	v_add_co_u32_e32 v176, vcc, s90, v144
	v_cvt_pk_bf16_f32 v175, v178, v179
	v_pk_mul_f32 v[178:179], v[16:17], v[136:137] op_sel_hi:[1,0]
	s_nop 0
	v_addc_co_u32_e32 v177, vcc, 0, v145, vcc
	global_store_dwordx4 v[176:177], v[172:175], off
	v_pk_mul_f32 v[180:181], v[18:19], v[136:137] op_sel_hi:[1,0]
	v_pk_mul_f32 v[178:179], v[148:149], v[178:179]
	v_pk_mul_f32 v[172:173], v[48:49], v[136:137] op_sel_hi:[1,0]
	v_pk_mul_f32 v[174:175], v[50:51], v[136:137] op_sel_hi:[1,0]
	v_pk_mul_f32 v[172:173], v[152:153], v[172:173]
	v_pk_mul_f32 v[174:175], v[150:151], v[174:175]
	v_cvt_pk_bf16_f32 v172, v172, v173
	v_mul_f32_e32 v136, v109, v109
	v_cvt_pk_bf16_f32 v173, v174, v175
	v_mul_f32_e32 v174, v111, v111
	v_fmac_f32_e32 v136, v108, v108
	v_fmac_f32_e32 v174, v110, v110
	v_add_f32_e32 v136, v136, v174
	v_mul_f32_e32 v174, v77, v77
	v_mul_f32_e32 v175, v79, v79
	v_fmac_f32_e32 v174, v76, v76
	v_fmac_f32_e32 v175, v78, v78
	v_add_f32_e32 v174, v174, v175
	v_add_f32_e32 v136, v136, v174
	v_mul_f32_e32 v174, v45, v45
	v_mul_f32_e32 v175, v47, v47
	v_fmac_f32_e32 v174, v44, v44
	v_fmac_f32_e32 v175, v46, v46
	v_add_f32_e32 v174, v174, v175
	v_add_f32_e32 v136, v136, v174
	v_mul_f32_e32 v174, v13, v13
	v_mul_f32_e32 v175, v15, v15
	v_fmac_f32_e32 v174, v12, v12
	v_fmac_f32_e32 v175, v14, v14
	v_add_f32_e32 v174, v174, v175
	v_add_f32_e32 v136, v136, v174
	v_mov_b32_e32 v174, v136
	s_nop 1
	v_permlane16_swap_b32_e32 v136, v174
	v_add_f32_e32 v136, v136, v174
	v_mov_b32_e32 v174, v136
	s_nop 1
	v_permlane32_swap_b32_e32 v136, v174
	v_add_f32_e32 v136, v136, v174
	v_fmamk_f32 v136, v136, 0x3c800000, v169
	v_rsq_f32_e32 v136, v136
	v_pk_mul_f32 v[180:181], v[146:147], v[180:181]
	v_cvt_pk_bf16_f32 v174, v178, v179
	v_pk_mul_f32 v[178:179], v[78:79], v[136:137] op_sel_hi:[1,0]
	v_cvt_pk_bf16_f32 v175, v180, v181
	global_store_dwordx4 v[176:177], v[172:175], off offset:64
	v_pk_mul_f32 v[176:177], v[76:77], v[136:137] op_sel_hi:[1,0]
	v_pk_mul_f32 v[178:179], v[154:155], v[178:179]
	v_pk_mul_f32 v[172:173], v[108:109], v[136:137] op_sel_hi:[1,0]
	v_pk_mul_f32 v[174:175], v[110:111], v[136:137] op_sel_hi:[1,0]
	v_pk_mul_f32 v[172:173], v[160:161], v[172:173]
	v_pk_mul_f32 v[174:175], v[158:159], v[174:175]
	v_pk_mul_f32 v[176:177], v[156:157], v[176:177]
	v_cvt_pk_bf16_f32 v172, v172, v173
	v_cvt_pk_bf16_f32 v173, v174, v175
	v_pk_mul_f32 v[180:181], v[14:15], v[136:137] op_sel_hi:[1,0]
	v_cvt_pk_bf16_f32 v174, v176, v177
	v_add_co_u32_e32 v176, vcc, s92, v144
	v_cvt_pk_bf16_f32 v175, v178, v179
	v_pk_mul_f32 v[178:179], v[12:13], v[136:137] op_sel_hi:[1,0]
	s_nop 0
	v_addc_co_u32_e32 v177, vcc, 0, v145, vcc
	global_store_dwordx4 v[176:177], v[172:175], off
	v_pk_mul_f32 v[180:181], v[146:147], v[180:181]
	v_pk_mul_f32 v[178:179], v[148:149], v[178:179]
	v_pk_mul_f32 v[172:173], v[44:45], v[136:137] op_sel_hi:[1,0]
	v_pk_mul_f32 v[174:175], v[46:47], v[136:137] op_sel_hi:[1,0]
	v_pk_mul_f32 v[172:173], v[152:153], v[172:173]
	v_pk_mul_f32 v[174:175], v[150:151], v[174:175]
	v_cvt_pk_bf16_f32 v172, v172, v173
	v_mul_f32_e32 v136, v105, v105
	v_cvt_pk_bf16_f32 v173, v174, v175
	v_mul_f32_e32 v174, v107, v107
	v_fmac_f32_e32 v136, v104, v104
	v_fmac_f32_e32 v174, v106, v106
	v_add_f32_e32 v136, v136, v174
	v_mul_f32_e32 v174, v73, v73
	v_mul_f32_e32 v175, v75, v75
	v_fmac_f32_e32 v174, v72, v72
	v_fmac_f32_e32 v175, v74, v74
	v_add_f32_e32 v174, v174, v175
	v_add_f32_e32 v136, v136, v174
	v_mul_f32_e32 v174, v41, v41
	v_mul_f32_e32 v175, v43, v43
	v_fmac_f32_e32 v174, v40, v40
	v_fmac_f32_e32 v175, v42, v42
	v_add_f32_e32 v174, v174, v175
	v_add_f32_e32 v136, v136, v174
	v_mul_f32_e32 v174, v9, v9
	v_mul_f32_e32 v175, v11, v11
	v_fmac_f32_e32 v174, v8, v8
	v_fmac_f32_e32 v175, v10, v10
	v_add_f32_e32 v174, v174, v175
	v_add_f32_e32 v136, v136, v174
	v_mov_b32_e32 v174, v136
	s_nop 1
	v_permlane16_swap_b32_e32 v136, v174
	v_add_f32_e32 v136, v136, v174
	v_mov_b32_e32 v174, v136
	s_nop 1
	v_permlane32_swap_b32_e32 v136, v174
	v_add_f32_e32 v136, v136, v174
	v_fmamk_f32 v136, v136, 0x3c800000, v169
	v_rsq_f32_e32 v136, v136
	v_cvt_pk_bf16_f32 v174, v178, v179
	v_cvt_pk_bf16_f32 v175, v180, v181
	global_store_dwordx4 v[176:177], v[172:175], off offset:64
	v_pk_mul_f32 v[176:177], v[72:73], v[136:137] op_sel_hi:[1,0]
	v_pk_mul_f32 v[178:179], v[74:75], v[136:137] op_sel_hi:[1,0]
	v_pk_mul_f32 v[172:173], v[104:105], v[136:137] op_sel_hi:[1,0]
	v_pk_mul_f32 v[174:175], v[106:107], v[136:137] op_sel_hi:[1,0]
	v_pk_mul_f32 v[172:173], v[160:161], v[172:173]
	v_pk_mul_f32 v[174:175], v[158:159], v[174:175]
	v_pk_mul_f32 v[176:177], v[156:157], v[176:177]
	v_cvt_pk_bf16_f32 v172, v172, v173
	v_cvt_pk_bf16_f32 v173, v174, v175
	v_pk_mul_f32 v[178:179], v[154:155], v[178:179]
	v_cvt_pk_bf16_f32 v174, v176, v177
	v_add_co_u32_e32 v176, vcc, s93, v144
	v_cvt_pk_bf16_f32 v175, v178, v179
	v_pk_mul_f32 v[178:179], v[8:9], v[136:137] op_sel_hi:[1,0]
	s_nop 0
	v_addc_co_u32_e32 v177, vcc, 0, v145, vcc
	global_store_dwordx4 v[176:177], v[172:175], off
	v_pk_mul_f32 v[180:181], v[10:11], v[136:137] op_sel_hi:[1,0]
	v_pk_mul_f32 v[178:179], v[148:149], v[178:179]
	v_pk_mul_f32 v[172:173], v[40:41], v[136:137] op_sel_hi:[1,0]
	v_pk_mul_f32 v[174:175], v[42:43], v[136:137] op_sel_hi:[1,0]
	v_pk_mul_f32 v[172:173], v[152:153], v[172:173]
	v_pk_mul_f32 v[174:175], v[150:151], v[174:175]
	v_cvt_pk_bf16_f32 v172, v172, v173
	v_mul_f32_e32 v136, v101, v101
	v_cvt_pk_bf16_f32 v173, v174, v175
	v_mul_f32_e32 v174, v103, v103
	v_fmac_f32_e32 v136, v100, v100
	v_fmac_f32_e32 v174, v102, v102
	v_add_f32_e32 v136, v136, v174
	v_mul_f32_e32 v174, v69, v69
	v_mul_f32_e32 v175, v71, v71
	v_fmac_f32_e32 v174, v68, v68
	v_fmac_f32_e32 v175, v70, v70
	v_add_f32_e32 v174, v174, v175
	v_add_f32_e32 v136, v136, v174
	v_mul_f32_e32 v174, v37, v37
	v_mul_f32_e32 v175, v39, v39
	v_fmac_f32_e32 v174, v36, v36
	v_fmac_f32_e32 v175, v38, v38
	v_add_f32_e32 v174, v174, v175
	v_add_f32_e32 v136, v136, v174
	v_mul_f32_e32 v174, v5, v5
	v_mul_f32_e32 v175, v7, v7
	v_fmac_f32_e32 v174, v4, v4
	v_fmac_f32_e32 v175, v6, v6
	v_add_f32_e32 v174, v174, v175
	v_add_f32_e32 v136, v136, v174
	v_mov_b32_e32 v174, v136
	s_nop 1
	v_permlane16_swap_b32_e32 v136, v174
	v_add_f32_e32 v136, v136, v174
	v_mov_b32_e32 v174, v136
	s_nop 1
	v_permlane32_swap_b32_e32 v136, v174
	v_add_f32_e32 v136, v136, v174
	v_fmamk_f32 v136, v136, 0x3c800000, v169
	v_rsq_f32_e32 v136, v136
	v_pk_mul_f32 v[180:181], v[146:147], v[180:181]
	v_cvt_pk_bf16_f32 v174, v178, v179
	v_pk_mul_f32 v[178:179], v[70:71], v[136:137] op_sel_hi:[1,0]
	v_cvt_pk_bf16_f32 v175, v180, v181
	global_store_dwordx4 v[176:177], v[172:175], off offset:64
	v_pk_mul_f32 v[176:177], v[68:69], v[136:137] op_sel_hi:[1,0]
	v_pk_mul_f32 v[178:179], v[154:155], v[178:179]
	v_pk_mul_f32 v[172:173], v[100:101], v[136:137] op_sel_hi:[1,0]
	v_pk_mul_f32 v[174:175], v[102:103], v[136:137] op_sel_hi:[1,0]
	v_pk_mul_f32 v[172:173], v[160:161], v[172:173]
	v_pk_mul_f32 v[174:175], v[158:159], v[174:175]
	v_pk_mul_f32 v[176:177], v[156:157], v[176:177]
	v_cvt_pk_bf16_f32 v172, v172, v173
	v_cvt_pk_bf16_f32 v173, v174, v175
	v_pk_mul_f32 v[180:181], v[6:7], v[136:137] op_sel_hi:[1,0]
	v_cvt_pk_bf16_f32 v174, v176, v177
	v_add_co_u32_e32 v176, vcc, s94, v144
	v_cvt_pk_bf16_f32 v175, v178, v179
	v_pk_mul_f32 v[178:179], v[4:5], v[136:137] op_sel_hi:[1,0]
	s_nop 0
	v_addc_co_u32_e32 v177, vcc, 0, v145, vcc
	global_store_dwordx4 v[176:177], v[172:175], off
	v_pk_mul_f32 v[180:181], v[146:147], v[180:181]
	v_pk_mul_f32 v[178:179], v[148:149], v[178:179]
	v_pk_mul_f32 v[172:173], v[36:37], v[136:137] op_sel_hi:[1,0]
	v_pk_mul_f32 v[174:175], v[38:39], v[136:137] op_sel_hi:[1,0]
	v_pk_mul_f32 v[172:173], v[152:153], v[172:173]
	v_pk_mul_f32 v[174:175], v[150:151], v[174:175]
	v_cvt_pk_bf16_f32 v172, v172, v173
	v_mul_f32_e32 v136, v97, v97
	v_cvt_pk_bf16_f32 v173, v174, v175
	v_mul_f32_e32 v174, v99, v99
	v_fmac_f32_e32 v136, v96, v96
	v_fmac_f32_e32 v174, v98, v98
	v_add_f32_e32 v136, v136, v174
	v_mul_f32_e32 v174, v65, v65
	v_mul_f32_e32 v175, v67, v67
	v_fmac_f32_e32 v174, v64, v64
	v_fmac_f32_e32 v175, v66, v66
	v_add_f32_e32 v174, v174, v175
	v_add_f32_e32 v136, v136, v174
	v_mul_f32_e32 v174, v33, v33
	v_mul_f32_e32 v175, v35, v35
	v_fmac_f32_e32 v174, v32, v32
	v_fmac_f32_e32 v175, v34, v34
	v_add_f32_e32 v174, v174, v175
	v_add_f32_e32 v136, v136, v174
	v_mul_f32_e32 v174, v1, v1
	v_mul_f32_e32 v175, v3, v3
	v_fmac_f32_e32 v174, v0, v0
	v_fmac_f32_e32 v175, v2, v2
	v_add_f32_e32 v174, v174, v175
	v_add_f32_e32 v136, v136, v174
	v_mov_b32_e32 v174, v136
	s_nop 1
	v_permlane16_swap_b32_e32 v136, v174
	v_add_f32_e32 v136, v136, v174
	v_mov_b32_e32 v174, v136
	s_nop 1
	v_permlane32_swap_b32_e32 v136, v174
	v_add_f32_e32 v136, v136, v174
	v_fmamk_f32 v136, v136, 0x3c800000, v169
	v_rsq_f32_e32 v136, v136
	v_cvt_pk_bf16_f32 v174, v178, v179
	v_cvt_pk_bf16_f32 v175, v180, v181
	global_store_dwordx4 v[176:177], v[172:175], off offset:64
	s_nop 1
	v_pk_mul_f32 v[174:175], v[98:99], v[136:137] op_sel_hi:[1,0]
	v_pk_mul_f32 v[172:173], v[96:97], v[136:137] op_sel_hi:[1,0]
	v_pk_mul_f32 v[158:159], v[158:159], v[174:175]
	v_pk_mul_f32 v[174:175], v[66:67], v[136:137] op_sel_hi:[1,0]
	v_pk_mul_f32 v[160:161], v[160:161], v[172:173]
	v_pk_mul_f32 v[172:173], v[64:65], v[136:137] op_sel_hi:[1,0]
	v_pk_mul_f32 v[174:175], v[154:155], v[174:175]
	v_cvt_pk_bf16_f32 v154, v160, v161
	v_cvt_pk_bf16_f32 v155, v158, v159
	v_add_co_u32_e32 v158, vcc, s95, v144
	v_pk_mul_f32 v[156:157], v[156:157], v[172:173]
	s_nop 0
	v_addc_co_u32_e32 v159, vcc, 0, v145, vcc
	v_cvt_pk_bf16_f32 v156, v156, v157
	v_cvt_pk_bf16_f32 v157, v174, v175
	global_store_dwordx4 v[158:159], v[154:157], off
	v_pk_mul_f32 v[144:145], v[32:33], v[136:137] op_sel_hi:[1,0]
	s_nop 0
	v_pk_mul_f32 v[154:155], v[34:35], v[136:137] op_sel_hi:[1,0]
	v_pk_mul_f32 v[144:145], v[152:153], v[144:145]
	v_pk_mul_f32 v[150:151], v[150:151], v[154:155]
	v_pk_mul_f32 v[152:153], v[0:1], v[136:137] op_sel_hi:[1,0]
	v_pk_mul_f32 v[154:155], v[2:3], v[136:137] op_sel_hi:[1,0]
	v_cvt_pk_bf16_f32 v144, v144, v145
	v_cvt_pk_bf16_f32 v145, v150, v151
	s_nop 0
	v_pk_mul_f32 v[154:155], v[146:147], v[154:155]
	v_pk_mul_f32 v[146:147], v[148:149], v[152:153]
	s_nop 0
	v_cvt_pk_bf16_f32 v146, v146, v147
	v_cvt_pk_bf16_f32 v147, v154, v155
	global_store_dwordx4 v[158:159], v[144:147], off offset:64

.LBB0_362:
	s_andn2_b64 vcc, exec, s[0:1]
	s_cbranch_vccnz .LBB0_278
	s_mul_hi_i32 s0, s66, 0x78787879
	s_lshr_b32 s1, s0, 31
	s_ashr_i32 s0, s0, 3
	s_add_i32 s0, s0, s1
	s_mul_i32 s1, s0, 0xffffffef
	s_add_i32 s1, s1, s66
	v_lshl_add_u32 v146, s1, 8, v138
	s_ashr_i32 s1, s0, 31
	v_lshl_or_b32 v136, s57, 8, v163
	s_lshl_b64 s[0:1], s[0:1], 9
	v_or_b32_e32 v136, s0, v136
	v_mov_b64_e32 v[144:145], s[76:77]
	v_ashrrev_i32_e32 v147, 31, v146
	v_mad_u64_u32 v[148:149], s[4:5], v136, s96, v[144:145]
	v_mad_i32_i24 v149, s1, v171, v149
	v_lshlrev_b64 v[146:147], 1, v[146:147]
	v_lshl_add_u64 v[148:149], v[148:149], 0, v[146:147]
	v_bfe_u32 v172, v217, 3, 1
	v_mul_u32_u24_e32 v172, 0x21f0, v172
	v_mov_b32_e32 v173, 0
	v_lshl_add_u64 v[174:175], v[148:149], 0, v[172:173]
	v_add_co_u32_e32 v178, vcc, 0x43e0, v174
	s_nop 1
	v_addc_co_u32_e32 v179, vcc, 0, v175, vcc
	v_cvt_pk_bf16_f32 v124, v124, v173
	global_store_short v[174:175], v124, off
	v_cvt_pk_bf16_f32 v125, v125, v173
	global_store_short v[174:175], v125, off offset:16
	v_cvt_pk_bf16_f32 v126, v126, v173
	global_store_short v[174:175], v126, off offset:32
	v_cvt_pk_bf16_f32 v127, v127, v173
	global_store_short v[174:175], v127, off offset:48
	v_cvt_pk_bf16_f32 v120, v120, v173
	global_store_short v[178:179], v120, off offset:32
	v_cvt_pk_bf16_f32 v121, v121, v173
	global_store_short v[178:179], v121, off offset:48
	v_cvt_pk_bf16_f32 v122, v122, v173
	global_store_short v[178:179], v122, off offset:64
	v_cvt_pk_bf16_f32 v123, v123, v173
	global_store_short v[178:179], v123, off offset:80
	v_cvt_pk_bf16_f32 v116, v116, v173
	global_store_short v[174:175], v116, off offset:64
	v_cvt_pk_bf16_f32 v117, v117, v173
	global_store_short v[174:175], v117, off offset:80
	v_cvt_pk_bf16_f32 v118, v118, v173
	global_store_short v[174:175], v118, off offset:96
	v_cvt_pk_bf16_f32 v119, v119, v173
	global_store_short v[174:175], v119, off offset:112
	v_cvt_pk_bf16_f32 v112, v112, v173
	global_store_short v[178:179], v112, off offset:96
	v_cvt_pk_bf16_f32 v113, v113, v173
	global_store_short v[178:179], v113, off offset:112
	v_cvt_pk_bf16_f32 v114, v114, v173
	global_store_short v[178:179], v114, off offset:128
	v_cvt_pk_bf16_f32 v115, v115, v173
	global_store_short v[178:179], v115, off offset:144
	v_cvt_pk_bf16_f32 v108, v108, v173
	global_store_short v[174:175], v108, off offset:256
	v_cvt_pk_bf16_f32 v109, v109, v173
	global_store_short v[174:175], v109, off offset:272
	v_cvt_pk_bf16_f32 v110, v110, v173
	global_store_short v[174:175], v110, off offset:288
	v_cvt_pk_bf16_f32 v111, v111, v173
	global_store_short v[174:175], v111, off offset:304
	v_cvt_pk_bf16_f32 v104, v104, v173
	global_store_short v[178:179], v104, off offset:288
	v_cvt_pk_bf16_f32 v105, v105, v173
	global_store_short v[178:179], v105, off offset:304
	v_cvt_pk_bf16_f32 v106, v106, v173
	global_store_short v[178:179], v106, off offset:320
	v_cvt_pk_bf16_f32 v107, v107, v173
	global_store_short v[178:179], v107, off offset:336
	v_cvt_pk_bf16_f32 v100, v100, v173
	global_store_short v[174:175], v100, off offset:320
	v_cvt_pk_bf16_f32 v101, v101, v173
	global_store_short v[174:175], v101, off offset:336
	v_cvt_pk_bf16_f32 v102, v102, v173
	global_store_short v[174:175], v102, off offset:352
	v_cvt_pk_bf16_f32 v103, v103, v173
	global_store_short v[174:175], v103, off offset:368
	v_cvt_pk_bf16_f32 v96, v96, v173
	global_store_short v[178:179], v96, off offset:352
	v_cvt_pk_bf16_f32 v97, v97, v173
	global_store_short v[178:179], v97, off offset:368
	v_cvt_pk_bf16_f32 v98, v98, v173
	global_store_short v[178:179], v98, off offset:384
	v_cvt_pk_bf16_f32 v99, v99, v173
	global_store_short v[178:179], v99, off offset:400
	v_add_co_u32_e32 v176, vcc, 0x8800, v174
	s_nop 1
	v_addc_co_u32_e32 v177, vcc, 0, v175, vcc
	v_add_co_u32_e32 v178, vcc, 0x43e0, v176
	s_nop 1
	v_addc_co_u32_e32 v179, vcc, 0, v177, vcc
	v_cvt_pk_bf16_f32 v92, v92, v173
	global_store_short v[176:177], v92, off
	v_cvt_pk_bf16_f32 v93, v93, v173
	global_store_short v[176:177], v93, off offset:16
	v_cvt_pk_bf16_f32 v94, v94, v173
	global_store_short v[176:177], v94, off offset:32
	v_cvt_pk_bf16_f32 v95, v95, v173
	global_store_short v[176:177], v95, off offset:48
	v_cvt_pk_bf16_f32 v88, v88, v173
	global_store_short v[178:179], v88, off offset:32
	v_cvt_pk_bf16_f32 v89, v89, v173
	global_store_short v[178:179], v89, off offset:48
	v_cvt_pk_bf16_f32 v90, v90, v173
	global_store_short v[178:179], v90, off offset:64
	v_cvt_pk_bf16_f32 v91, v91, v173
	global_store_short v[178:179], v91, off offset:80
	v_cvt_pk_bf16_f32 v84, v84, v173
	global_store_short v[176:177], v84, off offset:64
	v_cvt_pk_bf16_f32 v85, v85, v173
	global_store_short v[176:177], v85, off offset:80
	v_cvt_pk_bf16_f32 v86, v86, v173
	global_store_short v[176:177], v86, off offset:96
	v_cvt_pk_bf16_f32 v87, v87, v173
	global_store_short v[176:177], v87, off offset:112
	v_cvt_pk_bf16_f32 v80, v80, v173
	global_store_short v[178:179], v80, off offset:96
	v_cvt_pk_bf16_f32 v81, v81, v173
	global_store_short v[178:179], v81, off offset:112
	v_cvt_pk_bf16_f32 v82, v82, v173
	global_store_short v[178:179], v82, off offset:128
	v_cvt_pk_bf16_f32 v83, v83, v173
	global_store_short v[178:179], v83, off offset:144
	v_cvt_pk_bf16_f32 v76, v76, v173
	global_store_short v[176:177], v76, off offset:256
	v_cvt_pk_bf16_f32 v77, v77, v173
	global_store_short v[176:177], v77, off offset:272
	v_cvt_pk_bf16_f32 v78, v78, v173
	global_store_short v[176:177], v78, off offset:288
	v_cvt_pk_bf16_f32 v79, v79, v173
	global_store_short v[176:177], v79, off offset:304
	v_cvt_pk_bf16_f32 v72, v72, v173
	global_store_short v[178:179], v72, off offset:288
	v_cvt_pk_bf16_f32 v73, v73, v173
	global_store_short v[178:179], v73, off offset:304
	v_cvt_pk_bf16_f32 v74, v74, v173
	global_store_short v[178:179], v74, off offset:320
	v_cvt_pk_bf16_f32 v75, v75, v173
	global_store_short v[178:179], v75, off offset:336
	v_cvt_pk_bf16_f32 v68, v68, v173
	global_store_short v[176:177], v68, off offset:320
	v_cvt_pk_bf16_f32 v69, v69, v173
	global_store_short v[176:177], v69, off offset:336
	v_cvt_pk_bf16_f32 v70, v70, v173
	global_store_short v[176:177], v70, off offset:352
	v_cvt_pk_bf16_f32 v71, v71, v173
	global_store_short v[176:177], v71, off offset:368
	v_cvt_pk_bf16_f32 v64, v64, v173
	global_store_short v[178:179], v64, off offset:352
	v_cvt_pk_bf16_f32 v65, v65, v173
	global_store_short v[178:179], v65, off offset:368
	v_cvt_pk_bf16_f32 v66, v66, v173
	global_store_short v[178:179], v66, off offset:384
	v_cvt_pk_bf16_f32 v67, v67, v173
	global_store_short v[178:179], v67, off offset:400
	v_add_co_u32_e32 v176, vcc, 0x110000, v174
	s_nop 1
	v_addc_co_u32_e32 v177, vcc, 0, v175, vcc
	v_add_co_u32_e32 v178, vcc, 0x43e0, v176
	s_nop 1
	v_addc_co_u32_e32 v179, vcc, 0, v177, vcc
	v_cvt_pk_bf16_f32 v60, v60, v173
	global_store_short v[176:177], v60, off
	v_cvt_pk_bf16_f32 v61, v61, v173
	global_store_short v[176:177], v61, off offset:16
	v_cvt_pk_bf16_f32 v62, v62, v173
	global_store_short v[176:177], v62, off offset:32
	v_cvt_pk_bf16_f32 v63, v63, v173
	global_store_short v[176:177], v63, off offset:48
	v_cvt_pk_bf16_f32 v56, v56, v173
	global_store_short v[178:179], v56, off offset:32
	v_cvt_pk_bf16_f32 v57, v57, v173
	global_store_short v[178:179], v57, off offset:48
	v_cvt_pk_bf16_f32 v58, v58, v173
	global_store_short v[178:179], v58, off offset:64
	v_cvt_pk_bf16_f32 v59, v59, v173
	global_store_short v[178:179], v59, off offset:80
	v_cvt_pk_bf16_f32 v52, v52, v173
	global_store_short v[176:177], v52, off offset:64
	v_cvt_pk_bf16_f32 v53, v53, v173
	global_store_short v[176:177], v53, off offset:80
	v_cvt_pk_bf16_f32 v54, v54, v173
	global_store_short v[176:177], v54, off offset:96
	v_cvt_pk_bf16_f32 v55, v55, v173
	global_store_short v[176:177], v55, off offset:112
	v_cvt_pk_bf16_f32 v48, v48, v173
	global_store_short v[178:179], v48, off offset:96
	v_cvt_pk_bf16_f32 v49, v49, v173
	global_store_short v[178:179], v49, off offset:112
	v_cvt_pk_bf16_f32 v50, v50, v173
	global_store_short v[178:179], v50, off offset:128
	v_cvt_pk_bf16_f32 v51, v51, v173
	global_store_short v[178:179], v51, off offset:144
	v_cvt_pk_bf16_f32 v44, v44, v173
	global_store_short v[176:177], v44, off offset:256
	v_cvt_pk_bf16_f32 v45, v45, v173
	global_store_short v[176:177], v45, off offset:272
	v_cvt_pk_bf16_f32 v46, v46, v173
	global_store_short v[176:177], v46, off offset:288
	v_cvt_pk_bf16_f32 v47, v47, v173
	global_store_short v[176:177], v47, off offset:304
	v_cvt_pk_bf16_f32 v40, v40, v173
	global_store_short v[178:179], v40, off offset:288
	v_cvt_pk_bf16_f32 v41, v41, v173
	global_store_short v[178:179], v41, off offset:304
	v_cvt_pk_bf16_f32 v42, v42, v173
	global_store_short v[178:179], v42, off offset:320
	v_cvt_pk_bf16_f32 v43, v43, v173
	global_store_short v[178:179], v43, off offset:336
	v_cvt_pk_bf16_f32 v36, v36, v173
	global_store_short v[176:177], v36, off offset:320
	v_cvt_pk_bf16_f32 v37, v37, v173
	global_store_short v[176:177], v37, off offset:336
	v_cvt_pk_bf16_f32 v38, v38, v173
	global_store_short v[176:177], v38, off offset:352
	v_cvt_pk_bf16_f32 v39, v39, v173
	global_store_short v[176:177], v39, off offset:368
	v_cvt_pk_bf16_f32 v32, v32, v173
	global_store_short v[178:179], v32, off offset:352
	v_cvt_pk_bf16_f32 v33, v33, v173
	global_store_short v[178:179], v33, off offset:368
	v_cvt_pk_bf16_f32 v34, v34, v173
	global_store_short v[178:179], v34, off offset:384
	v_cvt_pk_bf16_f32 v35, v35, v173
	global_store_short v[178:179], v35, off offset:400
	v_add_co_u32_e32 v176, vcc, 0x118800, v174
	s_nop 1
	v_addc_co_u32_e32 v177, vcc, 0, v175, vcc
	v_add_co_u32_e32 v178, vcc, 0x43e0, v176
	s_nop 1
	v_addc_co_u32_e32 v179, vcc, 0, v177, vcc
	v_cvt_pk_bf16_f32 v28, v28, v173
	global_store_short v[176:177], v28, off
	v_cvt_pk_bf16_f32 v29, v29, v173
	global_store_short v[176:177], v29, off offset:16
	v_cvt_pk_bf16_f32 v30, v30, v173
	global_store_short v[176:177], v30, off offset:32
	v_cvt_pk_bf16_f32 v31, v31, v173
	global_store_short v[176:177], v31, off offset:48
	v_cvt_pk_bf16_f32 v24, v24, v173
	global_store_short v[178:179], v24, off offset:32
	v_cvt_pk_bf16_f32 v25, v25, v173
	global_store_short v[178:179], v25, off offset:48
	v_cvt_pk_bf16_f32 v26, v26, v173
	global_store_short v[178:179], v26, off offset:64
	v_cvt_pk_bf16_f32 v27, v27, v173
	global_store_short v[178:179], v27, off offset:80
	v_cvt_pk_bf16_f32 v20, v20, v173
	global_store_short v[176:177], v20, off offset:64
	v_cvt_pk_bf16_f32 v21, v21, v173
	global_store_short v[176:177], v21, off offset:80
	v_cvt_pk_bf16_f32 v22, v22, v173
	global_store_short v[176:177], v22, off offset:96
	v_cvt_pk_bf16_f32 v23, v23, v173
	global_store_short v[176:177], v23, off offset:112
	v_cvt_pk_bf16_f32 v16, v16, v173
	global_store_short v[178:179], v16, off offset:96
	v_cvt_pk_bf16_f32 v17, v17, v173
	global_store_short v[178:179], v17, off offset:112
	v_cvt_pk_bf16_f32 v18, v18, v173
	global_store_short v[178:179], v18, off offset:128
	v_cvt_pk_bf16_f32 v19, v19, v173
	global_store_short v[178:179], v19, off offset:144
	v_cvt_pk_bf16_f32 v12, v12, v173
	global_store_short v[176:177], v12, off offset:256
	v_cvt_pk_bf16_f32 v13, v13, v173
	global_store_short v[176:177], v13, off offset:272
	v_cvt_pk_bf16_f32 v14, v14, v173
	global_store_short v[176:177], v14, off offset:288
	v_cvt_pk_bf16_f32 v15, v15, v173
	global_store_short v[176:177], v15, off offset:304
	v_cvt_pk_bf16_f32 v8, v8, v173
	global_store_short v[178:179], v8, off offset:288
	v_cvt_pk_bf16_f32 v9, v9, v173
	global_store_short v[178:179], v9, off offset:304
	v_cvt_pk_bf16_f32 v10, v10, v173
	global_store_short v[178:179], v10, off offset:320
	v_cvt_pk_bf16_f32 v11, v11, v173
	global_store_short v[178:179], v11, off offset:336
	v_cvt_pk_bf16_f32 v4, v4, v173
	global_store_short v[176:177], v4, off offset:320
	v_cvt_pk_bf16_f32 v5, v5, v173
	global_store_short v[176:177], v5, off offset:336
	v_cvt_pk_bf16_f32 v6, v6, v173
	global_store_short v[176:177], v6, off offset:352
	v_cvt_pk_bf16_f32 v7, v7, v173
	global_store_short v[176:177], v7, off offset:368
	v_cvt_pk_bf16_f32 v0, v0, v173
	global_store_short v[178:179], v0, off offset:352
	v_cvt_pk_bf16_f32 v1, v1, v173
	global_store_short v[178:179], v1, off offset:368
	v_cvt_pk_bf16_f32 v2, v2, v173
	global_store_short v[178:179], v2, off offset:384
	v_cvt_pk_bf16_f32 v3, v3, v173
	global_store_short v[178:179], v3, off offset:400
	s_branch .LBB0_278

.LBB0_447:
	s_or_b64 exec, exec, s[0:1]
	v_lshlrev_b32_e32 v0, 2, v226
	s_waitcnt lgkmcnt(0)
	s_barrier
	global_load_dword v0, v0, s[24:25]
	s_waitcnt vmcnt(1)
	v_mbcnt_hi_u32_b32 v1, -1, v154
	v_and_b32_e32 v2, 64, v1
	v_xor_b32_e32 v3, 1, v1
	v_add_u32_e32 v2, 64, v2
	v_cmp_lt_i32_e32 vcc, v3, v2
	v_xor_b32_e32 v4, 2, v1
	v_xor_b32_e32 v5, 4, v1
	v_cndmask_b32_e32 v3, v1, v3, vcc
	v_lshlrev_b32_e32 v3, 2, v3
	v_cmp_lt_i32_e32 vcc, v4, v2
	v_xor_b32_e32 v6, 8, v1
	s_ashr_i32 s0, s2, 2
	v_cndmask_b32_e32 v4, v1, v4, vcc
	v_lshlrev_b32_e32 v4, 2, v4
	v_cmp_lt_i32_e32 vcc, v5, v2
	s_ashr_i32 s65, s9, 8
	s_and_b32 s0, s0, -2
	v_cndmask_b32_e32 v5, v1, v5, vcc
	v_lshlrev_b32_e32 v5, 2, v5
	v_cmp_lt_i32_e32 vcc, v6, v2
	s_add_i32 s65, s65, s0
	s_ashr_i32 s0, s65, 1
	v_cndmask_b32_e32 v6, v1, v6, vcc
	v_lshlrev_b32_e32 v6, 2, v6
	s_and_b32 s64, s2, 7
	s_and_b32 s0, s0, -8
	s_or_b32 s0, s0, s64
	s_cmp_gt_i32 s0, 63
	s_mov_b32 s37, 0
	s_waitcnt vmcnt(0)
	v_and_b32_e32 v7, 0x7fffffff, v0
	ds_bpermute_b32 v3, v3, v7
	v_max_f32_e64 v0, |v0|, |v0|
	s_waitcnt lgkmcnt(0)
	v_max_f32_e32 v3, v3, v3
	v_max_f32_e32 v0, v0, v3
	ds_bpermute_b32 v3, v4, v0
	v_xor_b32_e32 v4, 16, v1
	v_cmp_lt_i32_e32 vcc, v4, v2
	s_waitcnt lgkmcnt(0)
	v_max_f32_e32 v3, v3, v3
	v_max_f32_e32 v0, v0, v3
	ds_bpermute_b32 v3, v5, v0
	v_cndmask_b32_e32 v4, v1, v4, vcc
	v_lshlrev_b32_e32 v4, 2, v4
	v_xor_b32_e32 v5, 32, v1
	v_cmp_lt_i32_e32 vcc, v5, v2
	s_waitcnt lgkmcnt(0)
	v_max_f32_e32 v3, v3, v3
	v_max_f32_e32 v0, v0, v3
	ds_bpermute_b32 v3, v6, v0
	v_cndmask_b32_e32 v1, v1, v5, vcc
	v_lshlrev_b32_e32 v1, 2, v1
	s_waitcnt lgkmcnt(0)
	v_max_f32_e32 v3, v3, v3
	v_max_f32_e32 v0, v0, v3
	ds_bpermute_b32 v3, v4, v0
	s_waitcnt lgkmcnt(0)
	v_max_f32_e32 v2, v3, v3
	v_max_f32_e32 v0, v0, v2
	ds_bpermute_b32 v1, v1, v0
	s_cbranch_scc1 .LBB0_547
	v_readlane_b32 s12, v252, 0
	v_readlane_b32 s13, v252, 1
	v_readlane_b32 s14, v252, 2
	v_readlane_b32 s15, v252, 3
	v_readlane_b32 s16, v252, 4
	v_readlane_b32 s17, v252, 5
	s_add_i32 s0, s3, 7
	v_readlane_b32 s18, v252, 6
	v_readlane_b32 s19, v252, 7
	s_mov_b64 s[10:11], s[14:15]
	s_mov_b64 s[12:13], s[16:17]
	s_ashr_i32 s0, s0, 2
	s_and_b32 s25, s13, 0xffff
	s_and_b32 s41, s77, 0xffff
	s_and_b32 s66, s0, -2
	s_bfe_u32 s67, s9, 0x20006
	s_cmp_eq_u32 s67, 2
	s_mov_b64 s[28:29], s[68:69]
	s_cselect_b32 s68, 24, 32
	s_lshl_b32 s69, s67, 4
	s_waitcnt lgkmcnt(0)
	v_max_f32_e32 v1, v1, v1
	v_max_f32_e32 v0, v0, v0
	v_or_b32_e32 v216, s69, v150
	v_max_f32_e32 v0, v0, v1
	v_sub_u32_e64 v1, v216, 8 clamp
	v_min_u32_e32 v229, 48, v1
	s_lshl_b32 s0, s8, 13
	v_lshlrev_b32_e32 v1, 1, v226
	s_add_i32 s0, s0, 0
	s_lshl_b32 s72, s64, 6
	v_and_or_b32 v1, v1, 24, v151
	s_lshl_b32 s5, s64, 7
	v_lshl_add_u32 v230, v226, 4, s0
	v_and_b32_e32 v232, 24, v152
	v_lshl_or_b32 v233, v1, 10, v153
	v_lshlrev_b32_e32 v253, 1, v226
	v_and_b32_e32 v253, 24, v253
	v_lshrrev_b32_e32 v254, 4, v226
	v_or_b32_e32 v253, v253, v254
	v_and_b32_e32 v254, 3, v226
	v_lshlrev_b32_e32 v254, 4, v254
	v_lshl_or_b32 v233, v253, 10, v254
	v_mul_u32_u24_e32 v1, 0x1100, v1
	s_add_u32 s0, s10, s5
	v_mul_f32_e32 v0, 0x41000000, v0
	s_mov_b64 s[14:15], s[18:19]
	v_or_b32_e32 v1, v1, v232
	s_addc_u32 s1, s11, 0
	v_mul_f32_e32 v227, 0x3f8020c5, v0
	v_mov_b32_e32 v0, 0
	v_lshlrev_b32_e32 v234, 1, v1
	s_add_u32 s46, s14, s5
	v_lshlrev_b32_e32 v1, 1, v96
	s_mul_i32 s4, s64, 0xf00
	v_lshlrev_b32_e32 v2, 1, v232
	v_mov_b32_e32 v3, v0
	s_addc_u32 s47, s15, 0
	v_and_b32_e32 v1, 0x60, v1
	ds_read_b32 v228, v0 offset:30720
	v_lshl_add_u64 v[218:219], s[0:1], 0, v[2:3]
	s_add_u32 s48, s78, s5
	v_or_b32_e32 v1, s4, v1
	v_lshlrev_b32_e32 v2, 2, v150
	s_addc_u32 s49, s79, 0
	v_sub_u32_e32 v1, v1, v2
	s_lshl_b32 s0, s67, 6
	v_subrev_u32_e32 v1, s0, v1
	v_add_u32_e32 v1, 0, v1
	s_mov_b32 s27, 0x20000
	s_mov_b32 s26, 0x2200000
	s_mov_b32 s24, s12
	s_mov_b32 s40, s76
	v_add_u32_e32 v231, 0x8000, v230
	v_or_b32_e32 v235, 64, v233
	v_add_u32_e32 v236, 0x7c, v1
	s_mov_b32 s70, 0xf800000
	v_mov_b32_e32 v237, 0x260
	v_mov_b32_e32 v238, 0xf149f2ca
	s_mov_b32 s4, s65
	s_mov_b32 s71, 0
	s_branch .LBB0_451

.LBB0_465:
	v_add_f32_e32 v1, v1, v4
	v_mul_f32_e32 v4, 0x4f800000, v1
	v_cmp_gt_f32_e32 vcc, s70, v1
	v_add_f32_e32 v2, v2, v3
	v_mul_f32_e32 v3, 0x4f800000, v2
	v_cndmask_b32_e32 v1, v1, v4, vcc
	v_sqrt_f32_e32 v4, v1
	s_mul_i32 s82, s82, 0x88000
	s_lshl_b32 s81, s7, 1
	s_mov_b32 s42, s26
	v_add_u32_e32 v9, -1, v4
	v_fma_f32 v10, -v9, v4, v1
	v_cmp_ge_f32_e64 s[0:1], 0, v10
	v_add_u32_e32 v10, 1, v4
	s_mov_b32 s43, s27
	v_cndmask_b32_e64 v9, v4, v9, s[0:1]
	v_fma_f32 v4, -v10, v4, v1
	v_cmp_lt_f32_e64 s[0:1], 0, v4
	s_or_b32 s20, s5, 1
	s_and_b32 s4, s4, 15
	v_cndmask_b32_e64 v4, v9, v10, s[0:1]
	v_mul_f32_e32 v9, 0x37800000, v4
	v_cndmask_b32_e32 v4, v4, v9, vcc
	v_cmp_gt_f32_e32 vcc, s70, v2
	v_cmp_class_f32_e64 s[0:1], v1, v237
	s_lshl_b32 s4, s4, 10
	v_cndmask_b32_e32 v2, v2, v3, vcc
	v_sqrt_f32_e32 v3, v2
	v_cndmask_b32_e64 v1, v4, v1, s[0:1]
	s_waitcnt lgkmcnt(8)
	v_fma_f32 v1, v227, v1, v228
	v_mov_b32_e32 v224, 0
	v_add_u32_e32 v4, -1, v3
	v_fma_f32 v9, -v4, v3, v2
	v_cmp_ge_f32_e64 s[0:1], 0, v9
	v_add_u32_e32 v9, 1, v3
	s_mov_b32 s92, 0
	v_cndmask_b32_e64 v4, v3, v4, s[0:1]
	v_fma_f32 v3, -v9, v3, v2
	v_cmp_lt_f32_e64 s[0:1], 0, v3
	s_add_i32 s83, s83, 20
	s_add_i32 s84, s75, 4
	v_cndmask_b32_e64 v3, v4, v9, s[0:1]
	v_mul_f32_e32 v4, 0x37800000, v3
	v_cndmask_b32_e32 v3, v3, v4, vcc
	v_add_f32_e32 v4, v5, v6
	v_mul_f32_e32 v5, 0x4f800000, v4
	v_cmp_gt_f32_e32 vcc, s70, v4
	v_cmp_class_f32_e64 s[0:1], v2, v237
	v_mov_b32_e32 v225, v224
	v_cndmask_b32_e32 v4, v4, v5, vcc
	v_sqrt_f32_e32 v5, v4
	v_cndmask_b32_e64 v2, v3, v2, s[0:1]
	v_fma_f32 v2, v227, v2, v228
	v_max3_f32 v1, v1, 0, v2
	v_add_u32_e32 v2, -1, v5
	v_fma_f32 v3, -v2, v5, v4
	v_cmp_ge_f32_e64 s[0:1], 0, v3
	v_add_u32_e32 v3, 1, v5
	v_mov_b32_e32 v222, v224
	v_cndmask_b32_e64 v2, v5, v2, s[0:1]
	v_fma_f32 v5, -v3, v5, v4
	v_cmp_lt_f32_e64 s[0:1], 0, v5
	v_mov_b32_e32 v223, v224
	s_nop 0
	v_cndmask_b32_e64 v2, v2, v3, s[0:1]
	v_mul_f32_e32 v3, 0x37800000, v2
	s_lshl_b32 s0, s8, 1
	v_cndmask_b32_e32 v2, v2, v3, vcc
	v_cmp_class_f32_e32 vcc, v4, v237
	v_add_f32_e32 v3, v7, v8
	s_add_i32 s0, s0, s82
	v_cndmask_b32_e32 v2, v2, v4, vcc
	v_mul_f32_e32 v4, 0x4f800000, v3
	v_cmp_gt_f32_e32 vcc, s70, v3
	s_add_i32 s7, s0, 0x44000
	s_add_i32 s1, s0, 0x4c800
	v_cndmask_b32_e32 v3, v3, v4, vcc
	s_add_i32 s9, s0, 0x8800
	v_add_u32_e32 v80, 0x1000, v233
	v_add_u32_e32 v81, 0x1000, v235
	s_bfe_u32 s60, s59, 0x20003
	v_lshrrev_b32_e32 v85, 4, v226
	v_add_u32_e32 v86, s60, v85
	v_and_b32_e32 v87, 3, v86
	v_lshrrev_b32_e32 v86, 2, v86
	v_bfe_u32 v220, v226, 2, 2
	v_lshl_add_u32 v87, v220, 3, v87
	v_mul_u32_u24_e32 v87, 0x2200, v87
	v_lshl_add_u32 v87, v86, 6, v87
	v_and_b32_e32 v221, 3, v226
	v_lshl_add_u32 v234, v221, 4, v87
	v_lshl_add_u32 v87, v220, 3, v85
	v_mul_u32_u24_e32 v87, 0x2200, v87
	v_lshl_add_u32 v250, v221, 4, v87
	v_add_u32_e32 v251, 0x8800, v250
	v_add_u32_e32 v253, 0x44000, v250
	v_add_u32_e32 v254, 0x4c800, v250
	v_add_u32_e32 v82, 0x8800, v234
	v_add_u32_e32 v83, 0x44000, v234
	v_add_u32_e32 v84, 0x4c800, v234
	s_lshl_b32 s60, s6, 10
	s_add_i32 s60, s60, s81
	s_lshr_b32 s61, s6, 5
	s_lshl_b32 s61, s61, 6
	s_add_i32 s61, s61, s82
	s_lshl_b32 s62, s8, 10
	s_add_i32 s62, s62, s81
	s_lshr_b32 s63, s8, 5
	s_lshl_b32 s63, s63, 6
	s_add_i32 s63, s63, s82
	buffer_load_dwordx4 v[176:179], v233, s[24:27], s60 offen
	buffer_load_dwordx4 v[172:175], v235, s[24:27], s60 offen
	buffer_load_dwordx4 v[168:171], v80, s[24:27], s60 offen
	buffer_load_dwordx4 v[164:167], v81, s[24:27], s60 offen
	buffer_load_dwordx4 v[32:35], v234, s[40:43], s61 offen
	buffer_load_dwordx4 v[28:31], v82, s[40:43], s61 offen
	buffer_load_dwordx4 v[24:27], v83, s[40:43], s61 offen
	buffer_load_dwordx4 v[20:23], v84, s[40:43], s61 offen
	buffer_load_dwordx4 v[48:51], v233, s[24:27], s62 offen
	buffer_load_dwordx4 v[44:47], v235, s[24:27], s62 offen
	buffer_load_dwordx4 v[40:43], v80, s[24:27], s62 offen
	buffer_load_dwordx4 v[36:39], v81, s[24:27], s62 offen
	buffer_load_dwordx4 v[16:19], v234, s[40:43], s63 offen
	buffer_load_dwordx4 v[12:15], v82, s[40:43], s63 offen
	buffer_load_dwordx4 v[8:11], v83, s[40:43], s63 offen
	buffer_load_dwordx4 v[4:7], v84, s[40:43], s63 offen
	v_sqrt_f32_e32 v52, v3
	v_fma_f32 v2, v227, v2, v228
	v_add_u32_e32 v53, -1, v52
	v_fma_f32 v54, -v53, v52, v3
	v_cmp_ge_f32_e64 s[0:1], 0, v54
	v_add_u32_e32 v54, 1, v52
	s_nop 0
	v_cndmask_b32_e64 v53, v52, v53, s[0:1]
	v_fma_f32 v52, -v54, v52, v3
	v_cmp_lt_f32_e64 s[0:1], 0, v52
	s_nop 1
	v_cndmask_b32_e64 v52, v53, v54, s[0:1]
	v_mul_f32_e32 v53, 0x37800000, v52
	v_cndmask_b32_e32 v52, v52, v53, vcc
	v_cmp_class_f32_e32 vcc, v3, v237
	s_nop 1
	v_cndmask_b32_e32 v3, v52, v3, vcc
	v_fma_f32 v3, v227, v3, v228
	v_max3_f32 v239, v1, v2, v3
	v_add_u32_e32 v1, s59, v232
	v_sub_u32_e32 v1, v229, v1
	v_add_u32_e32 v2, 15, v1
	v_cmp_gt_u32_e64 s[0:1], 16, v2
	v_add_u32_e32 v2, 14, v1
	v_cmp_gt_u32_e64 s[6:7], 16, v2
	v_add_u32_e32 v2, 13, v1
	v_cmp_gt_u32_e64 s[8:9], 16, v2
	v_add_u32_e32 v2, 12, v1
	v_cmp_gt_u32_e64 s[10:11], 16, v2
	v_add_u32_e32 v2, 11, v1
	v_cmp_gt_u32_e64 s[12:13], 16, v2
	v_add_u32_e32 v2, 10, v1
	v_cmp_gt_u32_e64 s[14:15], 16, v2
	v_add_u32_e32 v2, 9, v1
	v_add_u32_e32 v1, 8, v1
	v_cmp_gt_u32_e64 s[18:19], 16, v1
	v_sub_u32_e64 v1, s20, 4 clamp
	v_cmp_gt_u32_e64 s[16:17], 16, v2
	v_readfirstlane_b32 s20, v1
	s_min_u32 s85, s20, 56
	s_or_b32 s20, s5, 2
	v_sub_u32_e64 v1, s20, 4 clamp
	s_or_b32 s5, s5, 3
	v_readfirstlane_b32 s20, v1
	v_sub_u32_e64 v1, s5, 4 clamp
	s_min_u32 s87, s20, 56
	v_readfirstlane_b32 s5, v1
	s_min_u32 s89, s5, 56
	s_lshl_b32 s5, s75, 8
	s_lshl_b32 s20, s59, 2
	s_or_b32 s5, s5, s20
	s_sub_i32 s4, s5, s4
	v_add_u32_e32 v240, s4, v236
	ds_read_b128 v[132:135], v231 offset:0
	ds_read_b128 v[136:139], v231 offset:1024
	ds_read_b128 v[140:143], v231 offset:2048
	ds_read_b128 v[144:147], v231 offset:3072
	ds_read_b128 v[148:151], v231 offset:4096
	ds_read_b128 v[152:155], v231 offset:5120
	ds_read_b128 v[156:159], v231 offset:6144
	ds_read_b128 v[160:163], v231 offset:7168
	v_xor_b32_e32 v76, 0x80000000, v239
	v_xor_b32_e32 v77, 0x80000000, v239
	v_xor_b32_e32 v78, 0x80000000, v239
	v_xor_b32_e32 v79, 0x80000000, v239
	v_cndmask_b32_e64 v180, 0, -1, s[0:1]
	v_cndmask_b32_e64 v181, 0, -1, s[6:7]
	v_cndmask_b32_e64 v182, 0, -1, s[8:9]
	v_cndmask_b32_e64 v183, 0, -1, s[10:11]
	v_cndmask_b32_e64 v184, 0, -1, s[12:13]
	v_cndmask_b32_e64 v185, 0, -1, s[14:15]
	v_cndmask_b32_e64 v186, 0, -1, s[16:17]
	v_cndmask_b32_e64 v187, 0, -1, s[18:19]
	v_mov_b32_e32 v96, 0
	v_mov_b32_e32 v97, 0
	v_mov_b32_e32 v98, 0
	v_mov_b32_e32 v99, 0
	v_mov_b32_e32 v88, 0
	v_mov_b32_e32 v89, 0
	v_mov_b32_e32 v90, 0
	v_mov_b32_e32 v91, 0
	v_mov_b32_e32 v72, 0
	v_mov_b32_e32 v73, 0
	v_mov_b32_e32 v74, 0
	v_mov_b32_e32 v75, 0
	v_mov_b32_e32 v68, 0
	v_mov_b32_e32 v69, 0
	v_mov_b32_e32 v70, 0
	v_mov_b32_e32 v71, 0
	v_mov_b32_e32 v222, 0
	v_mov_b32_e32 v64, 0
	v_mov_b32_e32 v65, 0
	v_mov_b32_e32 v66, 0
	v_mov_b32_e32 v67, 0
	v_mov_b32_e32 v60, 0
	v_mov_b32_e32 v61, 0
	v_mov_b32_e32 v62, 0
	v_mov_b32_e32 v63, 0
	v_mov_b32_e32 v56, 0
	v_mov_b32_e32 v57, 0
	v_mov_b32_e32 v58, 0
	v_mov_b32_e32 v59, 0
	v_mov_b32_e32 v52, 0
	v_mov_b32_e32 v53, 0
	v_mov_b32_e32 v54, 0
	v_mov_b32_e32 v55, 0
	v_mov_b32_e32 v223, 0
	v_mov_b32_e32 v128, 0
	v_mov_b32_e32 v129, 0
	v_mov_b32_e32 v130, 0
	v_mov_b32_e32 v131, 0
	v_mov_b32_e32 v124, 0
	v_mov_b32_e32 v125, 0
	v_mov_b32_e32 v126, 0
	v_mov_b32_e32 v127, 0
	v_mov_b32_e32 v120, 0
	v_mov_b32_e32 v121, 0
	v_mov_b32_e32 v122, 0
	v_mov_b32_e32 v123, 0
	v_mov_b32_e32 v116, 0
	v_mov_b32_e32 v117, 0
	v_mov_b32_e32 v118, 0
	v_mov_b32_e32 v119, 0
	v_mov_b32_e32 v224, 0
	v_mov_b32_e32 v112, 0
	v_mov_b32_e32 v113, 0
	v_mov_b32_e32 v114, 0
	v_mov_b32_e32 v115, 0
	v_mov_b32_e32 v108, 0
	v_mov_b32_e32 v109, 0
	v_mov_b32_e32 v110, 0
	v_mov_b32_e32 v111, 0
	v_mov_b32_e32 v104, 0
	v_mov_b32_e32 v105, 0
	v_mov_b32_e32 v106, 0
	v_mov_b32_e32 v107, 0
	v_mov_b32_e32 v100, 0
	v_mov_b32_e32 v101, 0
	v_mov_b32_e32 v102, 0
	v_mov_b32_e32 v103, 0
	v_mov_b32_e32 v225, 0
	s_mov_b32 s92, 0
	s_waitcnt lgkmcnt(0)
	s_cmp_eq_u32 s76, 8
	s_cbranch_scc1 .Latt_n8
	s_add_i32 s20, s92, 2
	s_min_i32 s20, s20, s80
	s_add_i32 s21, s20, s77
	s_lshl_b32 s21, s21, 6
	s_or_b32 s21, s21, s59
	s_sub_i32 s22, s20, s76
	s_lshl_b32 s22, s22, 5
	s_addk_i32 s22, 0x1000
	s_cmp_lt_i32 s20, s76
	s_cselect_b32 s60, 1, 0
	s_cselect_b32 s20, s21, s22
	s_lshl_b32 s23, s20, 10
	s_add_i32 s23, s23, s81
	s_lshr_b32 s33, s20, 5
	s_lshl_b32 s33, s33, 6
	s_add_i32 s33, s33, s82
	s_waitcnt vmcnt(12)
	ds_read2_b32 v[204:205], v240 offset0:192 offset1:193
	ds_read2_b32 v[206:207], v240 offset0:194 offset1:195
	ds_read2_b32 v[208:209], v240 offset0:196 offset1:197
	ds_read2_b32 v[210:211], v240 offset0:198 offset1:199
	v_mfma_f32_16x16x32_bf16 v[188:191], v[176:179], v[132:135], v[76:79]
	v_mfma_f32_16x16x32_bf16 v[192:195], v[168:171], v[132:135], v[76:79]
	v_mfma_f32_16x16x32_bf16 v[188:191], v[172:175], v[136:139], v[188:191]
	v_mfma_f32_16x16x32_bf16 v[192:195], v[164:167], v[136:139], v[192:195]
	buffer_load_dwordx4 v[176:179], v233, s[24:27], s23 offen
	buffer_load_dwordx4 v[172:175], v235, s[24:27], s23 offen
	buffer_load_dwordx4 v[168:171], v80, s[24:27], s23 offen
	buffer_load_dwordx4 v[164:167], v81, s[24:27], s23 offen
	s_waitcnt lgkmcnt(0)
	s_nop 1
	v_add_f32_e32 v188, v188, v204
	v_add_f32_e32 v189, v189, v205
	v_add_f32_e32 v190, v190, v206
	v_add_f32_e32 v191, v191, v207
	v_add_f32_e32 v192, v192, v208
	v_add_f32_e32 v193, v193, v209
	v_add_f32_e32 v194, v194, v210
	v_add_f32_e32 v195, v195, v211
	v_exp_f32_e32 v188, v188
	v_exp_f32_e32 v189, v189
	v_exp_f32_e32 v190, v190
	v_exp_f32_e32 v191, v191
	v_exp_f32_e32 v192, v192
	v_exp_f32_e32 v193, v193
	v_exp_f32_e32 v194, v194
	v_exp_f32_e32 v195, v195
	v_and_b32_e32 v188, v180, v188
	v_and_b32_e32 v189, v181, v189
	v_and_b32_e32 v190, v182, v190
	v_and_b32_e32 v191, v183, v191
	v_and_b32_e32 v192, v184, v192
	v_and_b32_e32 v193, v185, v193
	v_and_b32_e32 v194, v186, v194
	v_and_b32_e32 v195, v187, v195
	v_cvt_pk_bf16_f32 v246, v188, v189
	v_cvt_pk_bf16_f32 v247, v190, v191
	v_cvt_pk_bf16_f32 v248, v192, v193
	v_cvt_pk_bf16_f32 v249, v194, v195
	v_add_f32_e32 v1, v188, v189
	v_add_f32_e32 v2, v190, v191
	v_add_f32_e32 v3, v192, v193
	v_add_f32_e32 v85, v194, v195
	v_add_f32_e32 v1, v1, v2
	v_add_f32_e32 v3, v3, v85
	v_add_f32_e32 v1, v1, v3
	v_add_f32_e32 v222, v222, v1
	s_waitcnt vmcnt(12)
	v_mfma_f32_16x16x32_bf16 v[96:99], v[32:35], v[246:249], v[96:99]
	v_mfma_f32_16x16x32_bf16 v[88:91], v[28:31], v[246:249], v[88:91]
	v_mfma_f32_16x16x32_bf16 v[72:75], v[24:27], v[246:249], v[72:75]
	v_mfma_f32_16x16x32_bf16 v[68:71], v[20:23], v[246:249], v[68:71]
	s_cmp_eq_u32 s60, 0
	s_cbranch_scc1 .Latt_vc1
	buffer_load_dwordx4 v[32:35], v234, s[40:43], s33 offen
	buffer_load_dwordx4 v[28:31], v82, s[40:43], s33 offen
	buffer_load_dwordx4 v[24:27], v83, s[40:43], s33 offen
	buffer_load_dwordx4 v[20:23], v84, s[40:43], s33 offen
	s_branch .Latt_ve1
.Latt_vc1:
	buffer_load_dwordx4 v[32:35], v250, s[40:43], s33 offen
	buffer_load_dwordx4 v[28:31], v251, s[40:43], s33 offen
	buffer_load_dwordx4 v[24:27], v253, s[40:43], s33 offen
	buffer_load_dwordx4 v[20:23], v254, s[40:43], s33 offen
.Latt_ve1:
	v_add_u32_e32 v240, 0x100, v240
	s_add_i32 s92, s92, 1
	s_add_i32 s20, s92, 2
	s_min_i32 s20, s20, s80
	s_add_i32 s21, s20, s77
	s_lshl_b32 s21, s21, 6
	s_or_b32 s21, s21, s59
	s_sub_i32 s22, s20, s76
	s_lshl_b32 s22, s22, 5
	s_addk_i32 s22, 0x1000
	s_cmp_lt_i32 s20, s76
	s_cselect_b32 s60, 1, 0
	s_cselect_b32 s20, s21, s22
	s_lshl_b32 s23, s20, 10
	s_add_i32 s23, s23, s81
	s_lshr_b32 s33, s20, 5
	s_lshl_b32 s33, s33, 6
	s_add_i32 s33, s33, s82
	s_waitcnt vmcnt(12)
	ds_read2_b32 v[204:205], v240 offset0:192 offset1:193
	ds_read2_b32 v[206:207], v240 offset0:194 offset1:195
	ds_read2_b32 v[208:209], v240 offset0:196 offset1:197
	ds_read2_b32 v[210:211], v240 offset0:198 offset1:199
	ds_read2_b32 v[212:213], v240 offset0:128 offset1:129
	ds_read2_b32 v[214:215], v240 offset0:130 offset1:131
	ds_read2_b32 v[242:243], v240 offset0:132 offset1:133
	ds_read2_b32 v[244:245], v240 offset0:134 offset1:135
	v_mfma_f32_16x16x32_bf16 v[188:191], v[48:51], v[132:135], v[76:79]
	v_mfma_f32_16x16x32_bf16 v[192:195], v[40:43], v[132:135], v[76:79]
	v_mfma_f32_16x16x32_bf16 v[188:191], v[44:47], v[136:139], v[188:191]
	v_mfma_f32_16x16x32_bf16 v[192:195], v[36:39], v[136:139], v[192:195]
	v_mfma_f32_16x16x32_bf16 v[196:199], v[48:51], v[140:143], v[76:79]
	v_mfma_f32_16x16x32_bf16 v[200:203], v[40:43], v[140:143], v[76:79]
	v_mfma_f32_16x16x32_bf16 v[196:199], v[44:47], v[144:147], v[196:199]
	v_mfma_f32_16x16x32_bf16 v[200:203], v[36:39], v[144:147], v[200:203]
	buffer_load_dwordx4 v[48:51], v233, s[24:27], s23 offen
	buffer_load_dwordx4 v[44:47], v235, s[24:27], s23 offen
	buffer_load_dwordx4 v[40:43], v80, s[24:27], s23 offen
	buffer_load_dwordx4 v[36:39], v81, s[24:27], s23 offen
	s_waitcnt lgkmcnt(4)
	v_add_f32_e32 v188, v188, v204
	v_add_f32_e32 v189, v189, v205
	v_add_f32_e32 v190, v190, v206
	v_add_f32_e32 v191, v191, v207
	v_add_f32_e32 v192, v192, v208
	v_add_f32_e32 v193, v193, v209
	v_add_f32_e32 v194, v194, v210
	v_add_f32_e32 v195, v195, v211
	v_exp_f32_e32 v188, v188
	v_exp_f32_e32 v189, v189
	v_exp_f32_e32 v190, v190
	v_exp_f32_e32 v191, v191
	v_exp_f32_e32 v192, v192
	v_exp_f32_e32 v193, v193
	v_exp_f32_e32 v194, v194
	v_exp_f32_e32 v195, v195
	v_and_b32_e32 v188, v180, v188
	v_and_b32_e32 v189, v181, v189
	v_and_b32_e32 v190, v182, v190
	v_and_b32_e32 v191, v183, v191
	v_and_b32_e32 v192, v184, v192
	v_and_b32_e32 v193, v185, v193
	v_and_b32_e32 v194, v186, v194
	v_and_b32_e32 v195, v187, v195
	v_cvt_pk_bf16_f32 v246, v188, v189
	v_cvt_pk_bf16_f32 v247, v190, v191
	v_cvt_pk_bf16_f32 v248, v192, v193
	v_cvt_pk_bf16_f32 v249, v194, v195
	v_add_f32_e32 v1, v188, v189
	v_add_f32_e32 v2, v190, v191
	v_add_f32_e32 v3, v192, v193
	v_add_f32_e32 v85, v194, v195
	v_add_f32_e32 v1, v1, v2
	v_add_f32_e32 v3, v3, v85
	v_add_f32_e32 v1, v1, v3
	v_add_f32_e32 v222, v222, v1
	s_waitcnt vmcnt(12)
	s_waitcnt lgkmcnt(0)
	v_add_f32_e32 v196, v196, v212
	v_add_f32_e32 v197, v197, v213
	v_add_f32_e32 v198, v198, v214
	v_add_f32_e32 v199, v199, v215
	v_add_f32_e32 v200, v200, v242
	v_add_f32_e32 v201, v201, v243
	v_add_f32_e32 v202, v202, v244
	v_add_f32_e32 v203, v203, v245
	v_exp_f32_e32 v196, v196
	v_exp_f32_e32 v197, v197
	v_exp_f32_e32 v198, v198
	v_exp_f32_e32 v199, v199
	v_exp_f32_e32 v200, v200
	v_mfma_f32_16x16x32_bf16 v[96:99], v[16:19], v[246:249], v[96:99]
	v_exp_f32_e32 v201, v201
	v_exp_f32_e32 v202, v202
	v_exp_f32_e32 v203, v203
	v_and_b32_e32 v196, v180, v196
	v_and_b32_e32 v197, v181, v197
	v_mfma_f32_16x16x32_bf16 v[88:91], v[12:15], v[246:249], v[88:91]
	v_and_b32_e32 v198, v182, v198
	v_and_b32_e32 v199, v183, v199
	v_and_b32_e32 v200, v184, v200
	v_and_b32_e32 v201, v185, v201
	v_and_b32_e32 v202, v186, v202
	v_mfma_f32_16x16x32_bf16 v[72:75], v[8:11], v[246:249], v[72:75]
	v_and_b32_e32 v203, v187, v203
	v_cvt_pk_bf16_f32 v92, v196, v197
	v_cvt_pk_bf16_f32 v93, v198, v199
	v_cvt_pk_bf16_f32 v94, v200, v201
	v_cvt_pk_bf16_f32 v95, v202, v203
	v_mfma_f32_16x16x32_bf16 v[68:71], v[4:7], v[246:249], v[68:71]
	v_add_f32_e32 v86, v196, v197
	v_add_f32_e32 v87, v198, v199
	v_add_f32_e32 v220, v200, v201
	v_add_f32_e32 v221, v202, v203
	v_add_f32_e32 v86, v86, v87
	v_add_f32_e32 v220, v220, v221
	v_add_f32_e32 v86, v86, v220
	v_add_f32_e32 v223, v223, v86
	v_mfma_f32_16x16x32_bf16 v[64:67], v[16:19], v[92:95], v[64:67]
	v_mfma_f32_16x16x32_bf16 v[60:63], v[12:15], v[92:95], v[60:63]
	v_mfma_f32_16x16x32_bf16 v[56:59], v[8:11], v[92:95], v[56:59]
	v_mfma_f32_16x16x32_bf16 v[52:55], v[4:7], v[92:95], v[52:55]
	s_cmp_eq_u32 s60, 0
	s_cbranch_scc1 .Latt_vc2
	buffer_load_dwordx4 v[16:19], v234, s[40:43], s33 offen
	buffer_load_dwordx4 v[12:15], v82, s[40:43], s33 offen
	buffer_load_dwordx4 v[8:11], v83, s[40:43], s33 offen
	buffer_load_dwordx4 v[4:7], v84, s[40:43], s33 offen
	s_branch .Latt_ve2
.Latt_vc2:
	buffer_load_dwordx4 v[16:19], v250, s[40:43], s33 offen
	buffer_load_dwordx4 v[12:15], v251, s[40:43], s33 offen
	buffer_load_dwordx4 v[8:11], v253, s[40:43], s33 offen
	buffer_load_dwordx4 v[4:7], v254, s[40:43], s33 offen
.Latt_ve2:
	v_add_u32_e32 v240, 0x100, v240
	s_add_i32 s92, s92, 1
	s_add_i32 s20, s92, 2
	s_min_i32 s20, s20, s80
	s_add_i32 s21, s20, s77
	s_lshl_b32 s21, s21, 6
	s_or_b32 s21, s21, s59
	s_sub_i32 s22, s20, s76
	s_lshl_b32 s22, s22, 5
	s_addk_i32 s22, 0x1000
	s_cmp_lt_i32 s20, s76
	s_cselect_b32 s60, 1, 0
	s_cselect_b32 s20, s21, s22
	s_lshl_b32 s23, s20, 10
	s_add_i32 s23, s23, s81
	s_lshr_b32 s33, s20, 5
	s_lshl_b32 s33, s33, 6
	s_add_i32 s33, s33, s82
	s_waitcnt vmcnt(12)
	ds_read2_b32 v[204:205], v240 offset0:192 offset1:193
	ds_read2_b32 v[206:207], v240 offset0:194 offset1:195
	ds_read2_b32 v[208:209], v240 offset0:196 offset1:197
	ds_read2_b32 v[210:211], v240 offset0:198 offset1:199
	ds_read2_b32 v[212:213], v240 offset0:128 offset1:129
	ds_read2_b32 v[214:215], v240 offset0:130 offset1:131
	ds_read2_b32 v[242:243], v240 offset0:132 offset1:133
	ds_read2_b32 v[244:245], v240 offset0:134 offset1:135
	v_mfma_f32_16x16x32_bf16 v[188:191], v[176:179], v[132:135], v[76:79]
	v_mfma_f32_16x16x32_bf16 v[192:195], v[168:171], v[132:135], v[76:79]
	v_mfma_f32_16x16x32_bf16 v[188:191], v[172:175], v[136:139], v[188:191]
	v_mfma_f32_16x16x32_bf16 v[192:195], v[164:167], v[136:139], v[192:195]
	v_mfma_f32_16x16x32_bf16 v[196:199], v[176:179], v[140:143], v[76:79]
	v_mfma_f32_16x16x32_bf16 v[200:203], v[168:171], v[140:143], v[76:79]
	v_mfma_f32_16x16x32_bf16 v[196:199], v[172:175], v[144:147], v[196:199]
	v_mfma_f32_16x16x32_bf16 v[200:203], v[164:167], v[144:147], v[200:203]
	s_waitcnt lgkmcnt(4)
	s_nop 1
	v_add_f32_e32 v188, v188, v204
	v_add_f32_e32 v189, v189, v205
	v_add_f32_e32 v190, v190, v206
	v_add_f32_e32 v191, v191, v207
	v_add_f32_e32 v192, v192, v208
	v_add_f32_e32 v193, v193, v209
	v_add_f32_e32 v194, v194, v210
	v_add_f32_e32 v195, v195, v211
	ds_read2_b32 v[204:205], v240 offset0:64 offset1:65
	ds_read2_b32 v[206:207], v240 offset0:66 offset1:67
	ds_read2_b32 v[208:209], v240 offset0:68 offset1:69
	ds_read2_b32 v[210:211], v240 offset0:70 offset1:71
	v_exp_f32_e32 v188, v188
	v_exp_f32_e32 v189, v189
	v_exp_f32_e32 v190, v190
	v_exp_f32_e32 v191, v191
	v_exp_f32_e32 v192, v192
	v_exp_f32_e32 v193, v193
	v_exp_f32_e32 v194, v194
	v_exp_f32_e32 v195, v195
	v_and_b32_e32 v188, v180, v188
	v_and_b32_e32 v189, v181, v189
	v_and_b32_e32 v190, v182, v190
	v_and_b32_e32 v191, v183, v191
	v_and_b32_e32 v192, v184, v192
	v_and_b32_e32 v193, v185, v193
	v_and_b32_e32 v194, v186, v194
	v_and_b32_e32 v195, v187, v195
	v_cvt_pk_bf16_f32 v246, v188, v189
	v_cvt_pk_bf16_f32 v247, v190, v191
	v_cvt_pk_bf16_f32 v248, v192, v193
	v_cvt_pk_bf16_f32 v249, v194, v195
	v_add_f32_e32 v1, v188, v189
	v_add_f32_e32 v2, v190, v191
	v_add_f32_e32 v3, v192, v193
	v_add_f32_e32 v85, v194, v195
	v_add_f32_e32 v1, v1, v2
	v_add_f32_e32 v3, v3, v85
	v_add_f32_e32 v1, v1, v3
	v_add_f32_e32 v222, v222, v1
	v_mfma_f32_16x16x32_bf16 v[188:191], v[176:179], v[148:151], v[76:79]
	v_mfma_f32_16x16x32_bf16 v[192:195], v[168:171], v[148:151], v[76:79]
	v_mfma_f32_16x16x32_bf16 v[188:191], v[172:175], v[152:155], v[188:191]
	v_mfma_f32_16x16x32_bf16 v[192:195], v[164:167], v[152:155], v[192:195]
	buffer_load_dwordx4 v[176:179], v233, s[24:27], s23 offen
	buffer_load_dwordx4 v[172:175], v235, s[24:27], s23 offen
	buffer_load_dwordx4 v[168:171], v80, s[24:27], s23 offen
	buffer_load_dwordx4 v[164:167], v81, s[24:27], s23 offen
	s_waitcnt vmcnt(12)
	s_waitcnt lgkmcnt(4)
	v_add_f32_e32 v196, v196, v212
	v_add_f32_e32 v197, v197, v213
	v_add_f32_e32 v198, v198, v214
	v_add_f32_e32 v199, v199, v215
	v_add_f32_e32 v200, v200, v242
	v_add_f32_e32 v201, v201, v243
	v_add_f32_e32 v202, v202, v244
	v_add_f32_e32 v203, v203, v245
	v_exp_f32_e32 v196, v196
	v_exp_f32_e32 v197, v197
	v_exp_f32_e32 v198, v198
	v_exp_f32_e32 v199, v199
	v_exp_f32_e32 v200, v200
	v_mfma_f32_16x16x32_bf16 v[96:99], v[32:35], v[246:249], v[96:99]
	v_exp_f32_e32 v201, v201
	v_exp_f32_e32 v202, v202
	v_exp_f32_e32 v203, v203
	v_and_b32_e32 v196, v180, v196
	v_and_b32_e32 v197, v181, v197
	v_mfma_f32_16x16x32_bf16 v[88:91], v[28:31], v[246:249], v[88:91]
	v_and_b32_e32 v198, v182, v198
	v_and_b32_e32 v199, v183, v199
	v_and_b32_e32 v200, v184, v200
	v_and_b32_e32 v201, v185, v201
	v_and_b32_e32 v202, v186, v202
	v_mfma_f32_16x16x32_bf16 v[72:75], v[24:27], v[246:249], v[72:75]
	v_and_b32_e32 v203, v187, v203
	v_cvt_pk_bf16_f32 v92, v196, v197
	v_cvt_pk_bf16_f32 v93, v198, v199
	v_cvt_pk_bf16_f32 v94, v200, v201
	v_cvt_pk_bf16_f32 v95, v202, v203
	v_mfma_f32_16x16x32_bf16 v[68:71], v[20:23], v[246:249], v[68:71]
	v_add_f32_e32 v86, v196, v197
	v_add_f32_e32 v87, v198, v199
	v_add_f32_e32 v220, v200, v201
	v_add_f32_e32 v221, v202, v203
	v_add_f32_e32 v86, v86, v87
	v_add_f32_e32 v220, v220, v221
	v_add_f32_e32 v86, v86, v220
	v_add_f32_e32 v223, v223, v86
	s_waitcnt lgkmcnt(0)
	v_add_f32_e32 v188, v188, v204
	v_add_f32_e32 v189, v189, v205
	v_add_f32_e32 v190, v190, v206
	v_add_f32_e32 v191, v191, v207
	v_add_f32_e32 v192, v192, v208
	v_add_f32_e32 v193, v193, v209
	v_add_f32_e32 v194, v194, v210
	v_add_f32_e32 v195, v195, v211
	v_exp_f32_e32 v188, v188
	v_exp_f32_e32 v189, v189
	v_exp_f32_e32 v190, v190
	v_exp_f32_e32 v191, v191
	v_exp_f32_e32 v192, v192
	v_mfma_f32_16x16x32_bf16 v[64:67], v[32:35], v[92:95], v[64:67]
	v_exp_f32_e32 v193, v193
	v_exp_f32_e32 v194, v194
	v_exp_f32_e32 v195, v195
	v_and_b32_e32 v188, v180, v188
	v_and_b32_e32 v189, v181, v189
	v_mfma_f32_16x16x32_bf16 v[60:63], v[28:31], v[92:95], v[60:63]
	v_and_b32_e32 v190, v182, v190
	v_and_b32_e32 v191, v183, v191
	v_and_b32_e32 v192, v184, v192
	v_and_b32_e32 v193, v185, v193
	v_and_b32_e32 v194, v186, v194
	v_mfma_f32_16x16x32_bf16 v[56:59], v[24:27], v[92:95], v[56:59]
	v_and_b32_e32 v195, v187, v195
	v_cvt_pk_bf16_f32 v246, v188, v189
	v_cvt_pk_bf16_f32 v247, v190, v191
	v_cvt_pk_bf16_f32 v248, v192, v193
	v_cvt_pk_bf16_f32 v249, v194, v195
	v_mfma_f32_16x16x32_bf16 v[52:55], v[20:23], v[92:95], v[52:55]
	v_add_f32_e32 v1, v188, v189
	v_add_f32_e32 v2, v190, v191
	v_add_f32_e32 v3, v192, v193
	v_add_f32_e32 v85, v194, v195
	v_add_f32_e32 v1, v1, v2
	v_add_f32_e32 v3, v3, v85
	v_add_f32_e32 v1, v1, v3
	v_add_f32_e32 v224, v224, v1
	v_mfma_f32_16x16x32_bf16 v[128:131], v[32:35], v[246:249], v[128:131]
	v_mfma_f32_16x16x32_bf16 v[124:127], v[28:31], v[246:249], v[124:127]
	v_mfma_f32_16x16x32_bf16 v[120:123], v[24:27], v[246:249], v[120:123]
	v_mfma_f32_16x16x32_bf16 v[116:119], v[20:23], v[246:249], v[116:119]
	s_cmp_eq_u32 s60, 0
	s_cbranch_scc1 .Latt_vc3
	buffer_load_dwordx4 v[32:35], v234, s[40:43], s33 offen
	buffer_load_dwordx4 v[28:31], v82, s[40:43], s33 offen
	buffer_load_dwordx4 v[24:27], v83, s[40:43], s33 offen
	buffer_load_dwordx4 v[20:23], v84, s[40:43], s33 offen
	s_branch .Latt_ve3

.Latt_ve3:
	v_add_u32_e32 v240, 0x100, v240
	s_add_i32 s92, s92, 1
	s_mov_b32 s91, 5
	s_branch .Latt_FB

.Latt_FA:
	s_add_i32 s20, s92, 2
	s_min_i32 s20, s20, s80
	s_add_i32 s21, s20, s77
	s_lshl_b32 s21, s21, 6
	s_or_b32 s21, s21, s59
	s_sub_i32 s22, s20, s76
	s_lshl_b32 s22, s22, 5
	s_addk_i32 s22, 0x1000
	s_cmp_lt_i32 s20, s76
	s_cselect_b32 s60, 1, 0
	s_cselect_b32 s20, s21, s22
	s_lshl_b32 s23, s20, 10
	s_add_i32 s23, s23, s81
	s_lshr_b32 s33, s20, 5
	s_lshl_b32 s33, s33, 6
	s_add_i32 s33, s33, s82
	s_waitcnt vmcnt(12)
	ds_read2_b32 v[204:205], v240 offset0:192 offset1:193
	ds_read2_b32 v[206:207], v240 offset0:194 offset1:195
	ds_read2_b32 v[208:209], v240 offset0:196 offset1:197
	ds_read2_b32 v[210:211], v240 offset0:198 offset1:199
	ds_read2_b32 v[212:213], v240 offset0:128 offset1:129
	ds_read2_b32 v[214:215], v240 offset0:130 offset1:131
	ds_read2_b32 v[242:243], v240 offset0:132 offset1:133
	ds_read2_b32 v[244:245], v240 offset0:134 offset1:135
	v_mfma_f32_16x16x32_bf16 v[188:191], v[176:179], v[132:135], v[76:79]
	v_mfma_f32_16x16x32_bf16 v[192:195], v[168:171], v[132:135], v[76:79]
	v_mfma_f32_16x16x32_bf16 v[188:191], v[172:175], v[136:139], v[188:191]
	v_mfma_f32_16x16x32_bf16 v[192:195], v[164:167], v[136:139], v[192:195]
	v_mfma_f32_16x16x32_bf16 v[196:199], v[176:179], v[140:143], v[76:79]
	v_mfma_f32_16x16x32_bf16 v[200:203], v[168:171], v[140:143], v[76:79]
	v_mfma_f32_16x16x32_bf16 v[196:199], v[172:175], v[144:147], v[196:199]
	v_mfma_f32_16x16x32_bf16 v[200:203], v[164:167], v[144:147], v[200:203]
	s_waitcnt lgkmcnt(4)
	s_nop 1
	v_add_f32_e32 v188, v188, v204
	v_add_f32_e32 v189, v189, v205
	v_add_f32_e32 v190, v190, v206
	v_add_f32_e32 v191, v191, v207
	v_add_f32_e32 v192, v192, v208
	v_add_f32_e32 v193, v193, v209
	v_add_f32_e32 v194, v194, v210
	v_add_f32_e32 v195, v195, v211
	ds_read2_b32 v[204:205], v240 offset0:64 offset1:65
	ds_read2_b32 v[206:207], v240 offset0:66 offset1:67
	ds_read2_b32 v[208:209], v240 offset0:68 offset1:69
	ds_read2_b32 v[210:211], v240 offset0:70 offset1:71
	v_exp_f32_e32 v188, v188
	v_exp_f32_e32 v189, v189
	v_exp_f32_e32 v190, v190
	v_exp_f32_e32 v191, v191
	v_exp_f32_e32 v192, v192
	v_exp_f32_e32 v193, v193
	v_exp_f32_e32 v194, v194
	v_exp_f32_e32 v195, v195
	v_and_b32_e32 v188, v180, v188
	v_and_b32_e32 v189, v181, v189
	v_and_b32_e32 v190, v182, v190
	v_and_b32_e32 v191, v183, v191
	v_and_b32_e32 v192, v184, v192
	v_and_b32_e32 v193, v185, v193
	v_and_b32_e32 v194, v186, v194
	v_and_b32_e32 v195, v187, v195
	v_cvt_pk_bf16_f32 v246, v188, v189
	v_cvt_pk_bf16_f32 v247, v190, v191
	v_cvt_pk_bf16_f32 v248, v192, v193
	v_cvt_pk_bf16_f32 v249, v194, v195
	v_add_f32_e32 v1, v188, v189
	v_add_f32_e32 v2, v190, v191
	v_add_f32_e32 v3, v192, v193
	v_add_f32_e32 v85, v194, v195
	v_add_f32_e32 v1, v1, v2
	v_add_f32_e32 v3, v3, v85
	v_add_f32_e32 v1, v1, v3
	v_add_f32_e32 v222, v222, v1
	v_mfma_f32_16x16x32_bf16 v[188:191], v[176:179], v[148:151], v[76:79]
	v_mfma_f32_16x16x32_bf16 v[192:195], v[168:171], v[148:151], v[76:79]
	v_mfma_f32_16x16x32_bf16 v[188:191], v[172:175], v[152:155], v[188:191]
	v_mfma_f32_16x16x32_bf16 v[192:195], v[164:167], v[152:155], v[192:195]
	s_waitcnt vmcnt(8)
	s_waitcnt lgkmcnt(4)
	v_add_f32_e32 v196, v196, v212
	v_add_f32_e32 v197, v197, v213
	v_add_f32_e32 v198, v198, v214
	v_add_f32_e32 v199, v199, v215
	v_add_f32_e32 v200, v200, v242
	v_add_f32_e32 v201, v201, v243
	v_add_f32_e32 v202, v202, v244
	v_add_f32_e32 v203, v203, v245
	ds_read2_b32 v[212:213], v240 offset0:0 offset1:1
	ds_read2_b32 v[214:215], v240 offset0:2 offset1:3
	ds_read2_b32 v[242:243], v240 offset0:4 offset1:5
	ds_read2_b32 v[244:245], v240 offset0:6 offset1:7
	v_exp_f32_e32 v196, v196
	v_exp_f32_e32 v197, v197
	v_exp_f32_e32 v198, v198
	v_exp_f32_e32 v199, v199
	v_exp_f32_e32 v200, v200
	v_mfma_f32_16x16x32_bf16 v[96:99], v[32:35], v[246:249], v[96:99]
	v_exp_f32_e32 v201, v201
	v_exp_f32_e32 v202, v202
	v_exp_f32_e32 v203, v203
	v_and_b32_e32 v196, v180, v196
	v_and_b32_e32 v197, v181, v197
	v_mfma_f32_16x16x32_bf16 v[88:91], v[28:31], v[246:249], v[88:91]
	v_and_b32_e32 v198, v182, v198
	v_and_b32_e32 v199, v183, v199
	v_and_b32_e32 v200, v184, v200
	v_and_b32_e32 v201, v185, v201
	v_and_b32_e32 v202, v186, v202
	v_mfma_f32_16x16x32_bf16 v[72:75], v[24:27], v[246:249], v[72:75]
	v_and_b32_e32 v203, v187, v203
	v_cvt_pk_bf16_f32 v92, v196, v197
	v_cvt_pk_bf16_f32 v93, v198, v199
	v_cvt_pk_bf16_f32 v94, v200, v201
	v_cvt_pk_bf16_f32 v95, v202, v203
	v_mfma_f32_16x16x32_bf16 v[68:71], v[20:23], v[246:249], v[68:71]
	v_add_f32_e32 v86, v196, v197
	v_add_f32_e32 v87, v198, v199
	v_add_f32_e32 v220, v200, v201
	v_add_f32_e32 v221, v202, v203
	v_add_f32_e32 v86, v86, v87
	v_add_f32_e32 v220, v220, v221
	v_add_f32_e32 v86, v86, v220
	v_add_f32_e32 v223, v223, v86
	v_mfma_f32_16x16x32_bf16 v[196:199], v[176:179], v[156:159], v[76:79]
	v_mfma_f32_16x16x32_bf16 v[200:203], v[168:171], v[156:159], v[76:79]
	v_mfma_f32_16x16x32_bf16 v[196:199], v[172:175], v[160:163], v[196:199]
	v_mfma_f32_16x16x32_bf16 v[200:203], v[164:167], v[160:163], v[200:203]
	buffer_load_dwordx4 v[176:179], v233, s[24:27], s23 offen
	buffer_load_dwordx4 v[172:175], v235, s[24:27], s23 offen
	buffer_load_dwordx4 v[168:171], v80, s[24:27], s23 offen
	buffer_load_dwordx4 v[164:167], v81, s[24:27], s23 offen
	s_waitcnt lgkmcnt(4)
	v_add_f32_e32 v188, v188, v204
	v_add_f32_e32 v189, v189, v205
	v_add_f32_e32 v190, v190, v206
	v_add_f32_e32 v191, v191, v207
	v_add_f32_e32 v192, v192, v208
	v_add_f32_e32 v193, v193, v209
	v_add_f32_e32 v194, v194, v210
	v_add_f32_e32 v195, v195, v211
	v_exp_f32_e32 v188, v188
	v_exp_f32_e32 v189, v189
	v_exp_f32_e32 v190, v190
	v_exp_f32_e32 v191, v191
	v_exp_f32_e32 v192, v192
	v_mfma_f32_16x16x32_bf16 v[64:67], v[32:35], v[92:95], v[64:67]
	v_exp_f32_e32 v193, v193
	v_exp_f32_e32 v194, v194
	v_exp_f32_e32 v195, v195
	v_and_b32_e32 v188, v180, v188
	v_and_b32_e32 v189, v181, v189
	v_mfma_f32_16x16x32_bf16 v[60:63], v[28:31], v[92:95], v[60:63]
	v_and_b32_e32 v190, v182, v190
	v_and_b32_e32 v191, v183, v191
	v_and_b32_e32 v192, v184, v192
	v_and_b32_e32 v193, v185, v193
	v_and_b32_e32 v194, v186, v194
	v_mfma_f32_16x16x32_bf16 v[56:59], v[24:27], v[92:95], v[56:59]
	v_and_b32_e32 v195, v187, v195
	v_cvt_pk_bf16_f32 v246, v188, v189
	v_cvt_pk_bf16_f32 v247, v190, v191
	v_cvt_pk_bf16_f32 v248, v192, v193
	v_cvt_pk_bf16_f32 v249, v194, v195
	v_mfma_f32_16x16x32_bf16 v[52:55], v[20:23], v[92:95], v[52:55]
	v_add_f32_e32 v1, v188, v189
	v_add_f32_e32 v2, v190, v191
	v_add_f32_e32 v3, v192, v193
	v_add_f32_e32 v85, v194, v195
	v_add_f32_e32 v1, v1, v2
	v_add_f32_e32 v3, v3, v85
	v_add_f32_e32 v1, v1, v3
	v_add_f32_e32 v224, v224, v1
	s_waitcnt lgkmcnt(0)
	v_add_f32_e32 v196, v196, v212
	v_add_f32_e32 v197, v197, v213
	v_add_f32_e32 v198, v198, v214
	v_add_f32_e32 v199, v199, v215
	v_add_f32_e32 v200, v200, v242
	v_add_f32_e32 v201, v201, v243
	v_add_f32_e32 v202, v202, v244
	v_add_f32_e32 v203, v203, v245
	v_exp_f32_e32 v196, v196
	v_exp_f32_e32 v197, v197
	v_exp_f32_e32 v198, v198
	v_exp_f32_e32 v199, v199
	v_exp_f32_e32 v200, v200
	v_mfma_f32_16x16x32_bf16 v[128:131], v[32:35], v[246:249], v[128:131]
	v_exp_f32_e32 v201, v201
	v_exp_f32_e32 v202, v202
	v_exp_f32_e32 v203, v203
	v_and_b32_e32 v196, v180, v196
	v_and_b32_e32 v197, v181, v197
	v_mfma_f32_16x16x32_bf16 v[124:127], v[28:31], v[246:249], v[124:127]
	v_and_b32_e32 v198, v182, v198
	v_and_b32_e32 v199, v183, v199
	v_and_b32_e32 v200, v184, v200
	v_and_b32_e32 v201, v185, v201
	v_and_b32_e32 v202, v186, v202
	v_mfma_f32_16x16x32_bf16 v[120:123], v[24:27], v[246:249], v[120:123]
	v_and_b32_e32 v203, v187, v203
	v_cvt_pk_bf16_f32 v92, v196, v197
	v_cvt_pk_bf16_f32 v93, v198, v199
	v_cvt_pk_bf16_f32 v94, v200, v201
	v_cvt_pk_bf16_f32 v95, v202, v203
	v_mfma_f32_16x16x32_bf16 v[116:119], v[20:23], v[246:249], v[116:119]
	v_add_f32_e32 v86, v196, v197
	v_add_f32_e32 v87, v198, v199
	v_add_f32_e32 v220, v200, v201
	v_add_f32_e32 v221, v202, v203
	v_add_f32_e32 v86, v86, v87
	v_add_f32_e32 v220, v220, v221
	v_add_f32_e32 v86, v86, v220
	v_add_f32_e32 v225, v225, v86
	v_mfma_f32_16x16x32_bf16 v[112:115], v[32:35], v[92:95], v[112:115]
	v_mfma_f32_16x16x32_bf16 v[108:111], v[28:31], v[92:95], v[108:111]
	v_mfma_f32_16x16x32_bf16 v[104:107], v[24:27], v[92:95], v[104:107]
	v_mfma_f32_16x16x32_bf16 v[100:103], v[20:23], v[92:95], v[100:103]
	s_cmp_eq_u32 s60, 0
	s_cbranch_scc1 .Latt_vc4
	buffer_load_dwordx4 v[32:35], v234, s[40:43], s33 offen
	buffer_load_dwordx4 v[28:31], v82, s[40:43], s33 offen
	buffer_load_dwordx4 v[24:27], v83, s[40:43], s33 offen
	buffer_load_dwordx4 v[20:23], v84, s[40:43], s33 offen
	s_branch .Latt_ve4

.Latt_ve4:
	v_add_u32_e32 v240, 0x100, v240
	s_add_i32 s92, s92, 1
	s_sub_u32 s91, s91, 1
.Latt_FB:
	s_add_i32 s20, s92, 2
	s_min_i32 s20, s20, s80
	s_add_i32 s21, s20, s77
	s_lshl_b32 s21, s21, 6
	s_or_b32 s21, s21, s59
	s_sub_i32 s22, s20, s76
	s_lshl_b32 s22, s22, 5
	s_addk_i32 s22, 0x1000
	s_cmp_lt_i32 s20, s76
	s_cselect_b32 s60, 1, 0
	s_cselect_b32 s20, s21, s22
	s_lshl_b32 s23, s20, 10
	s_add_i32 s23, s23, s81
	s_lshr_b32 s33, s20, 5
	s_lshl_b32 s33, s33, 6
	s_add_i32 s33, s33, s82
	s_waitcnt vmcnt(12)
	ds_read2_b32 v[204:205], v240 offset0:192 offset1:193
	ds_read2_b32 v[206:207], v240 offset0:194 offset1:195
	ds_read2_b32 v[208:209], v240 offset0:196 offset1:197
	ds_read2_b32 v[210:211], v240 offset0:198 offset1:199
	ds_read2_b32 v[212:213], v240 offset0:128 offset1:129
	ds_read2_b32 v[214:215], v240 offset0:130 offset1:131
	ds_read2_b32 v[242:243], v240 offset0:132 offset1:133
	ds_read2_b32 v[244:245], v240 offset0:134 offset1:135
	v_mfma_f32_16x16x32_bf16 v[188:191], v[48:51], v[132:135], v[76:79]
	v_mfma_f32_16x16x32_bf16 v[192:195], v[40:43], v[132:135], v[76:79]
	v_mfma_f32_16x16x32_bf16 v[188:191], v[44:47], v[136:139], v[188:191]
	v_mfma_f32_16x16x32_bf16 v[192:195], v[36:39], v[136:139], v[192:195]
	v_mfma_f32_16x16x32_bf16 v[196:199], v[48:51], v[140:143], v[76:79]
	v_mfma_f32_16x16x32_bf16 v[200:203], v[40:43], v[140:143], v[76:79]
	v_mfma_f32_16x16x32_bf16 v[196:199], v[44:47], v[144:147], v[196:199]
	v_mfma_f32_16x16x32_bf16 v[200:203], v[36:39], v[144:147], v[200:203]
	s_waitcnt lgkmcnt(4)
	s_nop 1
	v_add_f32_e32 v188, v188, v204
	v_add_f32_e32 v189, v189, v205
	v_add_f32_e32 v190, v190, v206
	v_add_f32_e32 v191, v191, v207
	v_add_f32_e32 v192, v192, v208
	v_add_f32_e32 v193, v193, v209
	v_add_f32_e32 v194, v194, v210
	v_add_f32_e32 v195, v195, v211
	ds_read2_b32 v[204:205], v240 offset0:64 offset1:65
	ds_read2_b32 v[206:207], v240 offset0:66 offset1:67
	ds_read2_b32 v[208:209], v240 offset0:68 offset1:69
	ds_read2_b32 v[210:211], v240 offset0:70 offset1:71
	v_exp_f32_e32 v188, v188
	v_exp_f32_e32 v189, v189
	v_exp_f32_e32 v190, v190
	v_exp_f32_e32 v191, v191
	v_exp_f32_e32 v192, v192
	v_exp_f32_e32 v193, v193
	v_exp_f32_e32 v194, v194
	v_exp_f32_e32 v195, v195
	v_and_b32_e32 v188, v180, v188
	v_and_b32_e32 v189, v181, v189
	v_and_b32_e32 v190, v182, v190
	v_and_b32_e32 v191, v183, v191
	v_and_b32_e32 v192, v184, v192
	v_and_b32_e32 v193, v185, v193
	v_and_b32_e32 v194, v186, v194
	v_and_b32_e32 v195, v187, v195
	v_cvt_pk_bf16_f32 v246, v188, v189
	v_cvt_pk_bf16_f32 v247, v190, v191
	v_cvt_pk_bf16_f32 v248, v192, v193
	v_cvt_pk_bf16_f32 v249, v194, v195
	v_add_f32_e32 v1, v188, v189
	v_add_f32_e32 v2, v190, v191
	v_add_f32_e32 v3, v192, v193
	v_add_f32_e32 v85, v194, v195
	v_add_f32_e32 v1, v1, v2
	v_add_f32_e32 v3, v3, v85
	v_add_f32_e32 v1, v1, v3
	v_add_f32_e32 v222, v222, v1
	v_mfma_f32_16x16x32_bf16 v[188:191], v[48:51], v[148:151], v[76:79]
	v_mfma_f32_16x16x32_bf16 v[192:195], v[40:43], v[148:151], v[76:79]
	v_mfma_f32_16x16x32_bf16 v[188:191], v[44:47], v[152:155], v[188:191]
	v_mfma_f32_16x16x32_bf16 v[192:195], v[36:39], v[152:155], v[192:195]
	s_waitcnt vmcnt(8)
	s_waitcnt lgkmcnt(4)
	v_add_f32_e32 v196, v196, v212
	v_add_f32_e32 v197, v197, v213
	v_add_f32_e32 v198, v198, v214
	v_add_f32_e32 v199, v199, v215
	v_add_f32_e32 v200, v200, v242
	v_add_f32_e32 v201, v201, v243
	v_add_f32_e32 v202, v202, v244
	v_add_f32_e32 v203, v203, v245
	ds_read2_b32 v[212:213], v240 offset0:0 offset1:1
	ds_read2_b32 v[214:215], v240 offset0:2 offset1:3
	ds_read2_b32 v[242:243], v240 offset0:4 offset1:5
	ds_read2_b32 v[244:245], v240 offset0:6 offset1:7
	v_exp_f32_e32 v196, v196
	v_exp_f32_e32 v197, v197
	v_exp_f32_e32 v198, v198
	v_exp_f32_e32 v199, v199
	v_exp_f32_e32 v200, v200
	v_mfma_f32_16x16x32_bf16 v[96:99], v[16:19], v[246:249], v[96:99]
	v_exp_f32_e32 v201, v201
	v_exp_f32_e32 v202, v202
	v_exp_f32_e32 v203, v203
	v_and_b32_e32 v196, v180, v196
	v_and_b32_e32 v197, v181, v197
	v_mfma_f32_16x16x32_bf16 v[88:91], v[12:15], v[246:249], v[88:91]
	v_and_b32_e32 v198, v182, v198
	v_and_b32_e32 v199, v183, v199
	v_and_b32_e32 v200, v184, v200
	v_and_b32_e32 v201, v185, v201
	v_and_b32_e32 v202, v186, v202
	v_mfma_f32_16x16x32_bf16 v[72:75], v[8:11], v[246:249], v[72:75]
	v_and_b32_e32 v203, v187, v203
	v_cvt_pk_bf16_f32 v92, v196, v197
	v_cvt_pk_bf16_f32 v93, v198, v199
	v_cvt_pk_bf16_f32 v94, v200, v201
	v_cvt_pk_bf16_f32 v95, v202, v203
	v_mfma_f32_16x16x32_bf16 v[68:71], v[4:7], v[246:249], v[68:71]
	v_add_f32_e32 v86, v196, v197
	v_add_f32_e32 v87, v198, v199
	v_add_f32_e32 v220, v200, v201
	v_add_f32_e32 v221, v202, v203
	v_add_f32_e32 v86, v86, v87
	v_add_f32_e32 v220, v220, v221
	v_add_f32_e32 v86, v86, v220
	v_add_f32_e32 v223, v223, v86
	v_mfma_f32_16x16x32_bf16 v[196:199], v[48:51], v[156:159], v[76:79]
	v_mfma_f32_16x16x32_bf16 v[200:203], v[40:43], v[156:159], v[76:79]
	v_mfma_f32_16x16x32_bf16 v[196:199], v[44:47], v[160:163], v[196:199]
	v_mfma_f32_16x16x32_bf16 v[200:203], v[36:39], v[160:163], v[200:203]
	buffer_load_dwordx4 v[48:51], v233, s[24:27], s23 offen
	buffer_load_dwordx4 v[44:47], v235, s[24:27], s23 offen
	buffer_load_dwordx4 v[40:43], v80, s[24:27], s23 offen
	buffer_load_dwordx4 v[36:39], v81, s[24:27], s23 offen
	s_waitcnt lgkmcnt(4)
	v_add_f32_e32 v188, v188, v204
	v_add_f32_e32 v189, v189, v205
	v_add_f32_e32 v190, v190, v206
	v_add_f32_e32 v191, v191, v207
	v_add_f32_e32 v192, v192, v208
	v_add_f32_e32 v193, v193, v209
	v_add_f32_e32 v194, v194, v210
	v_add_f32_e32 v195, v195, v211
	v_exp_f32_e32 v188, v188
	v_exp_f32_e32 v189, v189
	v_exp_f32_e32 v190, v190
	v_exp_f32_e32 v191, v191
	v_exp_f32_e32 v192, v192
	v_mfma_f32_16x16x32_bf16 v[64:67], v[16:19], v[92:95], v[64:67]
	v_exp_f32_e32 v193, v193
	v_exp_f32_e32 v194, v194
	v_exp_f32_e32 v195, v195
	v_and_b32_e32 v188, v180, v188
	v_and_b32_e32 v189, v181, v189
	v_mfma_f32_16x16x32_bf16 v[60:63], v[12:15], v[92:95], v[60:63]
	v_and_b32_e32 v190, v182, v190
	v_and_b32_e32 v191, v183, v191
	v_and_b32_e32 v192, v184, v192
	v_and_b32_e32 v193, v185, v193
	v_and_b32_e32 v194, v186, v194
	v_mfma_f32_16x16x32_bf16 v[56:59], v[8:11], v[92:95], v[56:59]
	v_and_b32_e32 v195, v187, v195
	v_cvt_pk_bf16_f32 v246, v188, v189
	v_cvt_pk_bf16_f32 v247, v190, v191
	v_cvt_pk_bf16_f32 v248, v192, v193
	v_cvt_pk_bf16_f32 v249, v194, v195
	v_mfma_f32_16x16x32_bf16 v[52:55], v[4:7], v[92:95], v[52:55]
	v_add_f32_e32 v1, v188, v189
	v_add_f32_e32 v2, v190, v191
	v_add_f32_e32 v3, v192, v193
	v_add_f32_e32 v85, v194, v195
	v_add_f32_e32 v1, v1, v2
	v_add_f32_e32 v3, v3, v85
	v_add_f32_e32 v1, v1, v3
	v_add_f32_e32 v224, v224, v1
	s_waitcnt lgkmcnt(0)
	v_add_f32_e32 v196, v196, v212
	v_add_f32_e32 v197, v197, v213
	v_add_f32_e32 v198, v198, v214
	v_add_f32_e32 v199, v199, v215
	v_add_f32_e32 v200, v200, v242
	v_add_f32_e32 v201, v201, v243
	v_add_f32_e32 v202, v202, v244
	v_add_f32_e32 v203, v203, v245
	v_exp_f32_e32 v196, v196
	v_exp_f32_e32 v197, v197
	v_exp_f32_e32 v198, v198
	v_exp_f32_e32 v199, v199
	v_exp_f32_e32 v200, v200
	v_mfma_f32_16x16x32_bf16 v[128:131], v[16:19], v[246:249], v[128:131]
	v_exp_f32_e32 v201, v201
	v_exp_f32_e32 v202, v202
	v_exp_f32_e32 v203, v203
	v_and_b32_e32 v196, v180, v196
	v_and_b32_e32 v197, v181, v197
	v_mfma_f32_16x16x32_bf16 v[124:127], v[12:15], v[246:249], v[124:127]
	v_and_b32_e32 v198, v182, v198
	v_and_b32_e32 v199, v183, v199
	v_and_b32_e32 v200, v184, v200
	v_and_b32_e32 v201, v185, v201
	v_and_b32_e32 v202, v186, v202
	v_mfma_f32_16x16x32_bf16 v[120:123], v[8:11], v[246:249], v[120:123]
	v_and_b32_e32 v203, v187, v203
	v_cvt_pk_bf16_f32 v92, v196, v197
	v_cvt_pk_bf16_f32 v93, v198, v199
	v_cvt_pk_bf16_f32 v94, v200, v201
	v_cvt_pk_bf16_f32 v95, v202, v203
	v_mfma_f32_16x16x32_bf16 v[116:119], v[4:7], v[246:249], v[116:119]
	v_add_f32_e32 v86, v196, v197
	v_add_f32_e32 v87, v198, v199
	v_add_f32_e32 v220, v200, v201
	v_add_f32_e32 v221, v202, v203
	v_add_f32_e32 v86, v86, v87
	v_add_f32_e32 v220, v220, v221
	v_add_f32_e32 v86, v86, v220
	v_add_f32_e32 v225, v225, v86
	v_mfma_f32_16x16x32_bf16 v[112:115], v[16:19], v[92:95], v[112:115]
	v_mfma_f32_16x16x32_bf16 v[108:111], v[12:15], v[92:95], v[108:111]
	v_mfma_f32_16x16x32_bf16 v[104:107], v[8:11], v[92:95], v[104:107]
	v_mfma_f32_16x16x32_bf16 v[100:103], v[4:7], v[92:95], v[100:103]
	s_cmp_eq_u32 s60, 0
	s_cbranch_scc1 .Latt_vc5
	buffer_load_dwordx4 v[16:19], v234, s[40:43], s33 offen
	buffer_load_dwordx4 v[12:15], v82, s[40:43], s33 offen
	buffer_load_dwordx4 v[8:11], v83, s[40:43], s33 offen
	buffer_load_dwordx4 v[4:7], v84, s[40:43], s33 offen
	s_branch .Latt_ve5

.Latt_ve5:
	v_add_u32_e32 v240, 0x100, v240
	s_add_i32 s92, s92, 1
	s_sub_u32 s91, s91, 1
	s_cmp_lg_u32 s91, 0
	s_cbranch_scc1 .Latt_FA
	s_cmp_eq_u32 s76, 8
	s_cbranch_scc1 .Latt_ctx8
	s_add_i32 s20, s92, 2
	s_min_i32 s20, s20, s80
	s_add_i32 s21, s20, s77
	s_lshl_b32 s21, s21, 6
	s_or_b32 s21, s21, s59
	s_sub_i32 s22, s20, s76
	s_lshl_b32 s22, s22, 5
	s_addk_i32 s22, 0x1000
	s_cmp_lt_i32 s20, s76
	s_cselect_b32 s60, 1, 0
	s_cselect_b32 s20, s21, s22
	s_lshl_b32 s23, s20, 10
	s_add_i32 s23, s23, s81
	s_lshr_b32 s33, s20, 5
	s_lshl_b32 s33, s33, 6
	s_add_i32 s33, s33, s82
	s_waitcnt vmcnt(12)
	ds_read2_b32 v[204:205], v240 offset0:128 offset1:129
	ds_read2_b32 v[206:207], v240 offset0:130 offset1:131
	ds_read2_b32 v[208:209], v240 offset0:132 offset1:133
	ds_read2_b32 v[210:211], v240 offset0:134 offset1:135
	ds_read2_b32 v[212:213], v240 offset0:64 offset1:65
	ds_read2_b32 v[214:215], v240 offset0:66 offset1:67
	ds_read2_b32 v[242:243], v240 offset0:68 offset1:69
	ds_read2_b32 v[244:245], v240 offset0:70 offset1:71
	v_mfma_f32_16x16x32_bf16 v[188:191], v[176:179], v[140:143], v[76:79]
	v_mfma_f32_16x16x32_bf16 v[192:195], v[168:171], v[140:143], v[76:79]
	v_mfma_f32_16x16x32_bf16 v[188:191], v[172:175], v[144:147], v[188:191]
	v_mfma_f32_16x16x32_bf16 v[192:195], v[164:167], v[144:147], v[192:195]
	v_mfma_f32_16x16x32_bf16 v[196:199], v[176:179], v[148:151], v[76:79]
	v_mfma_f32_16x16x32_bf16 v[200:203], v[168:171], v[148:151], v[76:79]
	v_mfma_f32_16x16x32_bf16 v[196:199], v[172:175], v[152:155], v[196:199]
	v_mfma_f32_16x16x32_bf16 v[200:203], v[164:167], v[152:155], v[200:203]
	s_waitcnt lgkmcnt(4)
	s_nop 1
	v_add_f32_e32 v188, v188, v204
	v_add_f32_e32 v189, v189, v205
	v_add_f32_e32 v190, v190, v206
	v_add_f32_e32 v191, v191, v207
	v_add_f32_e32 v192, v192, v208
	v_add_f32_e32 v193, v193, v209
	v_add_f32_e32 v194, v194, v210
	v_add_f32_e32 v195, v195, v211
	ds_read2_b32 v[204:205], v240 offset0:0 offset1:1
	ds_read2_b32 v[206:207], v240 offset0:2 offset1:3
	ds_read2_b32 v[208:209], v240 offset0:4 offset1:5
	ds_read2_b32 v[210:211], v240 offset0:6 offset1:7
	v_exp_f32_e32 v188, v188
	v_exp_f32_e32 v189, v189
	v_exp_f32_e32 v190, v190
	v_exp_f32_e32 v191, v191
	v_exp_f32_e32 v192, v192
	v_exp_f32_e32 v193, v193
	v_exp_f32_e32 v194, v194
	v_exp_f32_e32 v195, v195
	v_and_b32_e32 v188, v180, v188
	v_and_b32_e32 v189, v181, v189
	v_and_b32_e32 v190, v182, v190
	v_and_b32_e32 v191, v183, v191
	v_and_b32_e32 v192, v184, v192
	v_and_b32_e32 v193, v185, v193
	v_and_b32_e32 v194, v186, v194
	v_and_b32_e32 v195, v187, v195
	v_cvt_pk_bf16_f32 v246, v188, v189
	v_cvt_pk_bf16_f32 v247, v190, v191
	v_cvt_pk_bf16_f32 v248, v192, v193
	v_cvt_pk_bf16_f32 v249, v194, v195
	v_add_f32_e32 v1, v188, v189
	v_add_f32_e32 v2, v190, v191
	v_add_f32_e32 v3, v192, v193
	v_add_f32_e32 v85, v194, v195
	v_add_f32_e32 v1, v1, v2
	v_add_f32_e32 v3, v3, v85
	v_add_f32_e32 v1, v1, v3
	v_add_f32_e32 v223, v223, v1
	v_mfma_f32_16x16x32_bf16 v[188:191], v[176:179], v[156:159], v[76:79]
	v_mfma_f32_16x16x32_bf16 v[192:195], v[168:171], v[156:159], v[76:79]
	v_mfma_f32_16x16x32_bf16 v[188:191], v[172:175], v[160:163], v[188:191]
	v_mfma_f32_16x16x32_bf16 v[192:195], v[164:167], v[160:163], v[192:195]
	buffer_load_dwordx4 v[176:179], v233, s[24:27], s23 offen
	buffer_load_dwordx4 v[172:175], v235, s[24:27], s23 offen
	buffer_load_dwordx4 v[168:171], v80, s[24:27], s23 offen
	buffer_load_dwordx4 v[164:167], v81, s[24:27], s23 offen
	s_waitcnt vmcnt(12)
	s_waitcnt lgkmcnt(4)
	v_add_f32_e32 v196, v196, v212
	v_add_f32_e32 v197, v197, v213
	v_add_f32_e32 v198, v198, v214
	v_add_f32_e32 v199, v199, v215
	v_add_f32_e32 v200, v200, v242
	v_add_f32_e32 v201, v201, v243
	v_add_f32_e32 v202, v202, v244
	v_add_f32_e32 v203, v203, v245
	v_exp_f32_e32 v196, v196
	v_exp_f32_e32 v197, v197
	v_exp_f32_e32 v198, v198
	v_exp_f32_e32 v199, v199
	v_exp_f32_e32 v200, v200
	v_mfma_f32_16x16x32_bf16 v[64:67], v[32:35], v[246:249], v[64:67]
	v_exp_f32_e32 v201, v201
	v_exp_f32_e32 v202, v202
	v_exp_f32_e32 v203, v203
	v_and_b32_e32 v196, v180, v196
	v_and_b32_e32 v197, v181, v197
	v_mfma_f32_16x16x32_bf16 v[60:63], v[28:31], v[246:249], v[60:63]
	v_and_b32_e32 v198, v182, v198
	v_and_b32_e32 v199, v183, v199
	v_and_b32_e32 v200, v184, v200
	v_and_b32_e32 v201, v185, v201
	v_and_b32_e32 v202, v186, v202
	v_mfma_f32_16x16x32_bf16 v[56:59], v[24:27], v[246:249], v[56:59]
	v_and_b32_e32 v203, v187, v203
	v_cvt_pk_bf16_f32 v92, v196, v197
	v_cvt_pk_bf16_f32 v93, v198, v199
	v_cvt_pk_bf16_f32 v94, v200, v201
	v_cvt_pk_bf16_f32 v95, v202, v203
	v_mfma_f32_16x16x32_bf16 v[52:55], v[20:23], v[246:249], v[52:55]
	v_add_f32_e32 v86, v196, v197
	v_add_f32_e32 v87, v198, v199
	v_add_f32_e32 v220, v200, v201
	v_add_f32_e32 v221, v202, v203
	v_add_f32_e32 v86, v86, v87
	v_add_f32_e32 v220, v220, v221
	v_add_f32_e32 v86, v86, v220
	v_add_f32_e32 v224, v224, v86
	s_waitcnt lgkmcnt(0)
	v_add_f32_e32 v188, v188, v204
	v_add_f32_e32 v189, v189, v205
	v_add_f32_e32 v190, v190, v206
	v_add_f32_e32 v191, v191, v207
	v_add_f32_e32 v192, v192, v208
	v_add_f32_e32 v193, v193, v209
	v_add_f32_e32 v194, v194, v210
	v_add_f32_e32 v195, v195, v211
	v_exp_f32_e32 v188, v188
	v_exp_f32_e32 v189, v189
	v_exp_f32_e32 v190, v190
	v_exp_f32_e32 v191, v191
	v_exp_f32_e32 v192, v192
	v_mfma_f32_16x16x32_bf16 v[128:131], v[32:35], v[92:95], v[128:131]
	v_exp_f32_e32 v193, v193
	v_exp_f32_e32 v194, v194
	v_exp_f32_e32 v195, v195
	v_and_b32_e32 v188, v180, v188
	v_and_b32_e32 v189, v181, v189
	v_mfma_f32_16x16x32_bf16 v[124:127], v[28:31], v[92:95], v[124:127]
	v_and_b32_e32 v190, v182, v190
	v_and_b32_e32 v191, v183, v191
	v_and_b32_e32 v192, v184, v192
	v_and_b32_e32 v193, v185, v193
	v_and_b32_e32 v194, v186, v194
	v_mfma_f32_16x16x32_bf16 v[120:123], v[24:27], v[92:95], v[120:123]
	v_and_b32_e32 v195, v187, v195
	v_cvt_pk_bf16_f32 v246, v188, v189
	v_cvt_pk_bf16_f32 v247, v190, v191
	v_cvt_pk_bf16_f32 v248, v192, v193
	v_cvt_pk_bf16_f32 v249, v194, v195
	v_mfma_f32_16x16x32_bf16 v[116:119], v[20:23], v[92:95], v[116:119]
	v_add_f32_e32 v1, v188, v189
	v_add_f32_e32 v2, v190, v191
	v_add_f32_e32 v3, v192, v193
	v_add_f32_e32 v85, v194, v195
	v_add_f32_e32 v1, v1, v2
	v_add_f32_e32 v3, v3, v85
	v_add_f32_e32 v1, v1, v3
	v_add_f32_e32 v225, v225, v1
	v_mfma_f32_16x16x32_bf16 v[112:115], v[32:35], v[246:249], v[112:115]
	v_mfma_f32_16x16x32_bf16 v[108:111], v[28:31], v[246:249], v[108:111]
	v_mfma_f32_16x16x32_bf16 v[104:107], v[24:27], v[246:249], v[104:107]
	v_mfma_f32_16x16x32_bf16 v[100:103], v[20:23], v[246:249], v[100:103]
	s_cmp_eq_u32 s60, 0
	s_cbranch_scc1 .Latt_vc6
	buffer_load_dwordx4 v[32:35], v234, s[40:43], s33 offen
	buffer_load_dwordx4 v[28:31], v82, s[40:43], s33 offen
	buffer_load_dwordx4 v[24:27], v83, s[40:43], s33 offen
	buffer_load_dwordx4 v[20:23], v84, s[40:43], s33 offen
	s_branch .Latt_ve6

.Latt_ve6:
	v_add_u32_e32 v240, 0x100, v240
	s_add_i32 s92, s92, 1
	s_add_i32 s20, s92, 2
	s_min_i32 s20, s20, s80
	s_add_i32 s21, s20, s77
	s_lshl_b32 s21, s21, 6
	s_or_b32 s21, s21, s59
	s_sub_i32 s22, s20, s76
	s_lshl_b32 s22, s22, 5
	s_addk_i32 s22, 0x1000
	s_cmp_lt_i32 s20, s76
	s_cselect_b32 s60, 1, 0
	s_cselect_b32 s20, s21, s22
	s_lshl_b32 s23, s20, 10
	s_add_i32 s23, s23, s81
	s_lshr_b32 s33, s20, 5
	s_lshl_b32 s33, s33, 6
	s_add_i32 s33, s33, s82
	s_waitcnt vmcnt(12)
	ds_read2_b32 v[204:205], v240 offset0:64 offset1:65
	ds_read2_b32 v[206:207], v240 offset0:66 offset1:67
	ds_read2_b32 v[208:209], v240 offset0:68 offset1:69
	ds_read2_b32 v[210:211], v240 offset0:70 offset1:71
	ds_read2_b32 v[212:213], v240 offset0:0 offset1:1
	ds_read2_b32 v[214:215], v240 offset0:2 offset1:3
	ds_read2_b32 v[242:243], v240 offset0:4 offset1:5
	ds_read2_b32 v[244:245], v240 offset0:6 offset1:7
	v_mfma_f32_16x16x32_bf16 v[188:191], v[48:51], v[148:151], v[76:79]
	v_mfma_f32_16x16x32_bf16 v[192:195], v[40:43], v[148:151], v[76:79]
	v_mfma_f32_16x16x32_bf16 v[188:191], v[44:47], v[152:155], v[188:191]
	v_mfma_f32_16x16x32_bf16 v[192:195], v[36:39], v[152:155], v[192:195]
	v_mfma_f32_16x16x32_bf16 v[196:199], v[48:51], v[156:159], v[76:79]
	v_mfma_f32_16x16x32_bf16 v[200:203], v[40:43], v[156:159], v[76:79]
	v_mfma_f32_16x16x32_bf16 v[196:199], v[44:47], v[160:163], v[196:199]
	v_mfma_f32_16x16x32_bf16 v[200:203], v[36:39], v[160:163], v[200:203]
	buffer_load_dwordx4 v[48:51], v233, s[24:27], s23 offen
	buffer_load_dwordx4 v[44:47], v235, s[24:27], s23 offen
	buffer_load_dwordx4 v[40:43], v80, s[24:27], s23 offen
	buffer_load_dwordx4 v[36:39], v81, s[24:27], s23 offen
	s_waitcnt lgkmcnt(4)
	v_add_f32_e32 v188, v188, v204
	v_add_f32_e32 v189, v189, v205
	v_add_f32_e32 v190, v190, v206
	v_add_f32_e32 v191, v191, v207
	v_add_f32_e32 v192, v192, v208
	v_add_f32_e32 v193, v193, v209
	v_add_f32_e32 v194, v194, v210
	v_add_f32_e32 v195, v195, v211
	v_exp_f32_e32 v188, v188
	v_exp_f32_e32 v189, v189
	v_exp_f32_e32 v190, v190
	v_exp_f32_e32 v191, v191
	v_exp_f32_e32 v192, v192
	v_exp_f32_e32 v193, v193
	v_exp_f32_e32 v194, v194
	v_exp_f32_e32 v195, v195
	v_and_b32_e32 v188, v180, v188
	v_and_b32_e32 v189, v181, v189
	v_and_b32_e32 v190, v182, v190
	v_and_b32_e32 v191, v183, v191
	v_and_b32_e32 v192, v184, v192
	v_and_b32_e32 v193, v185, v193
	v_and_b32_e32 v194, v186, v194
	v_and_b32_e32 v195, v187, v195
	v_cvt_pk_bf16_f32 v246, v188, v189
	v_cvt_pk_bf16_f32 v247, v190, v191
	v_cvt_pk_bf16_f32 v248, v192, v193
	v_cvt_pk_bf16_f32 v249, v194, v195
	v_add_f32_e32 v1, v188, v189
	v_add_f32_e32 v2, v190, v191
	v_add_f32_e32 v3, v192, v193
	v_add_f32_e32 v85, v194, v195
	v_add_f32_e32 v1, v1, v2
	v_add_f32_e32 v3, v3, v85
	v_add_f32_e32 v1, v1, v3
	v_add_f32_e32 v224, v224, v1
	s_waitcnt vmcnt(12)
	s_waitcnt lgkmcnt(0)
	v_add_f32_e32 v196, v196, v212
	v_add_f32_e32 v197, v197, v213
	v_add_f32_e32 v198, v198, v214
	v_add_f32_e32 v199, v199, v215
	v_add_f32_e32 v200, v200, v242
	v_add_f32_e32 v201, v201, v243
	v_add_f32_e32 v202, v202, v244
	v_add_f32_e32 v203, v203, v245
	v_exp_f32_e32 v196, v196
	v_exp_f32_e32 v197, v197
	v_exp_f32_e32 v198, v198
	v_exp_f32_e32 v199, v199
	v_exp_f32_e32 v200, v200
	v_mfma_f32_16x16x32_bf16 v[128:131], v[16:19], v[246:249], v[128:131]
	v_exp_f32_e32 v201, v201
	v_exp_f32_e32 v202, v202
	v_exp_f32_e32 v203, v203
	v_and_b32_e32 v196, v180, v196
	v_and_b32_e32 v197, v181, v197
	v_mfma_f32_16x16x32_bf16 v[124:127], v[12:15], v[246:249], v[124:127]
	v_and_b32_e32 v198, v182, v198
	v_and_b32_e32 v199, v183, v199
	v_and_b32_e32 v200, v184, v200
	v_and_b32_e32 v201, v185, v201
	v_and_b32_e32 v202, v186, v202
	v_mfma_f32_16x16x32_bf16 v[120:123], v[8:11], v[246:249], v[120:123]
	v_and_b32_e32 v203, v187, v203
	v_cvt_pk_bf16_f32 v92, v196, v197
	v_cvt_pk_bf16_f32 v93, v198, v199
	v_cvt_pk_bf16_f32 v94, v200, v201
	v_cvt_pk_bf16_f32 v95, v202, v203
	v_mfma_f32_16x16x32_bf16 v[116:119], v[4:7], v[246:249], v[116:119]
	v_add_f32_e32 v86, v196, v197
	v_add_f32_e32 v87, v198, v199
	v_add_f32_e32 v220, v200, v201
	v_add_f32_e32 v221, v202, v203
	v_add_f32_e32 v86, v86, v87
	v_add_f32_e32 v220, v220, v221
	v_add_f32_e32 v86, v86, v220
	v_add_f32_e32 v225, v225, v86
	v_mfma_f32_16x16x32_bf16 v[112:115], v[16:19], v[92:95], v[112:115]
	v_mfma_f32_16x16x32_bf16 v[108:111], v[12:15], v[92:95], v[108:111]
	v_mfma_f32_16x16x32_bf16 v[104:107], v[8:11], v[92:95], v[104:107]
	v_mfma_f32_16x16x32_bf16 v[100:103], v[4:7], v[92:95], v[100:103]
	s_cmp_eq_u32 s60, 0
	s_cbranch_scc1 .Latt_vc7
	buffer_load_dwordx4 v[16:19], v234, s[40:43], s33 offen
	buffer_load_dwordx4 v[12:15], v82, s[40:43], s33 offen
	buffer_load_dwordx4 v[8:11], v83, s[40:43], s33 offen
	buffer_load_dwordx4 v[4:7], v84, s[40:43], s33 offen
	s_branch .Latt_ve7

.Latt_ve7:
	v_add_u32_e32 v240, 0x100, v240
	s_add_i32 s92, s92, 1
	s_add_i32 s20, s92, 2
	s_min_i32 s20, s20, s80
	s_add_i32 s21, s20, s77
	s_lshl_b32 s21, s21, 6
	s_or_b32 s21, s21, s59
	s_sub_i32 s22, s20, s76
	s_lshl_b32 s22, s22, 5
	s_addk_i32 s22, 0x1000
	s_cmp_lt_i32 s20, s76
	s_cselect_b32 s60, 1, 0
	s_cselect_b32 s20, s21, s22
	s_lshl_b32 s23, s20, 10
	s_add_i32 s23, s23, s81
	s_lshr_b32 s33, s20, 5
	s_lshl_b32 s33, s33, 6
	s_add_i32 s33, s33, s82
	s_waitcnt vmcnt(12)
	ds_read2_b32 v[204:205], v240 offset0:0 offset1:1
	ds_read2_b32 v[206:207], v240 offset0:2 offset1:3
	ds_read2_b32 v[208:209], v240 offset0:4 offset1:5
	ds_read2_b32 v[210:211], v240 offset0:6 offset1:7
	v_mfma_f32_16x16x32_bf16 v[188:191], v[176:179], v[156:159], v[76:79]
	v_mfma_f32_16x16x32_bf16 v[192:195], v[168:171], v[156:159], v[76:79]
	v_mfma_f32_16x16x32_bf16 v[188:191], v[172:175], v[160:163], v[188:191]
	v_mfma_f32_16x16x32_bf16 v[192:195], v[164:167], v[160:163], v[192:195]
	buffer_load_dwordx4 v[176:179], v233, s[24:27], s23 offen
	buffer_load_dwordx4 v[172:175], v235, s[24:27], s23 offen
	buffer_load_dwordx4 v[168:171], v80, s[24:27], s23 offen
	buffer_load_dwordx4 v[164:167], v81, s[24:27], s23 offen
	s_waitcnt lgkmcnt(0)
	s_nop 1
	v_add_f32_e32 v188, v188, v204
	v_add_f32_e32 v189, v189, v205
	v_add_f32_e32 v190, v190, v206
	v_add_f32_e32 v191, v191, v207
	v_add_f32_e32 v192, v192, v208
	v_add_f32_e32 v193, v193, v209
	v_add_f32_e32 v194, v194, v210
	v_add_f32_e32 v195, v195, v211
	v_exp_f32_e32 v188, v188
	v_exp_f32_e32 v189, v189
	v_exp_f32_e32 v190, v190
	v_exp_f32_e32 v191, v191
	v_exp_f32_e32 v192, v192
	v_exp_f32_e32 v193, v193
	v_exp_f32_e32 v194, v194
	v_exp_f32_e32 v195, v195
	v_and_b32_e32 v188, v180, v188
	v_and_b32_e32 v189, v181, v189
	v_and_b32_e32 v190, v182, v190
	v_and_b32_e32 v191, v183, v191
	v_and_b32_e32 v192, v184, v192
	v_and_b32_e32 v193, v185, v193
	v_and_b32_e32 v194, v186, v194
	v_and_b32_e32 v195, v187, v195
	v_cvt_pk_bf16_f32 v246, v188, v189
	v_cvt_pk_bf16_f32 v247, v190, v191
	v_cvt_pk_bf16_f32 v248, v192, v193
	v_cvt_pk_bf16_f32 v249, v194, v195
	v_add_f32_e32 v1, v188, v189
	v_add_f32_e32 v2, v190, v191
	v_add_f32_e32 v3, v192, v193
	v_add_f32_e32 v85, v194, v195
	v_add_f32_e32 v1, v1, v2
	v_add_f32_e32 v3, v3, v85
	v_add_f32_e32 v1, v1, v3
	v_add_f32_e32 v225, v225, v1
	s_waitcnt vmcnt(12)
	v_mfma_f32_16x16x32_bf16 v[112:115], v[32:35], v[246:249], v[112:115]
	v_mfma_f32_16x16x32_bf16 v[108:111], v[28:31], v[246:249], v[108:111]
	v_mfma_f32_16x16x32_bf16 v[104:107], v[24:27], v[246:249], v[104:107]
	v_mfma_f32_16x16x32_bf16 v[100:103], v[20:23], v[246:249], v[100:103]
	s_cmp_eq_u32 s60, 0
	s_cbranch_scc1 .Latt_vc8
	buffer_load_dwordx4 v[32:35], v234, s[40:43], s33 offen
	buffer_load_dwordx4 v[28:31], v82, s[40:43], s33 offen
	buffer_load_dwordx4 v[24:27], v83, s[40:43], s33 offen
	buffer_load_dwordx4 v[20:23], v84, s[40:43], s33 offen
	s_branch .Latt_ve8

.Latt_ve8:
	v_add_u32_e32 v240, 0x100, v240
	s_add_i32 s92, s92, 1
	s_mov_b32 s91, 8
	s_branch .Latt_CB

.Latt_CA:
	s_add_i32 s20, s92, 2
	s_min_i32 s20, s20, s80
	s_add_i32 s21, s20, s77
	s_lshl_b32 s21, s21, 6
	s_or_b32 s21, s21, s59
	s_sub_i32 s22, s20, s76
	s_lshl_b32 s22, s22, 5
	s_addk_i32 s22, 0x1000
	s_cmp_lt_i32 s20, s76
	s_cselect_b32 s60, 1, 0
	s_cselect_b32 s20, s21, s22
	s_lshl_b32 s23, s20, 10
	s_add_i32 s23, s23, s81
	s_lshr_b32 s33, s20, 5
	s_lshl_b32 s33, s33, 6
	s_add_i32 s33, s33, s82
	s_waitcnt vmcnt(12)
	v_mfma_f32_16x16x32_bf16 v[188:191], v[176:179], v[132:135], v[76:79]
	v_mfma_f32_16x16x32_bf16 v[192:195], v[168:171], v[132:135], v[76:79]
	v_mfma_f32_16x16x32_bf16 v[188:191], v[172:175], v[136:139], v[188:191]
	v_mfma_f32_16x16x32_bf16 v[192:195], v[164:167], v[136:139], v[192:195]
	v_mfma_f32_16x16x32_bf16 v[196:199], v[176:179], v[140:143], v[76:79]
	v_mfma_f32_16x16x32_bf16 v[200:203], v[168:171], v[140:143], v[76:79]
	v_mfma_f32_16x16x32_bf16 v[196:199], v[172:175], v[144:147], v[196:199]
	v_mfma_f32_16x16x32_bf16 v[200:203], v[164:167], v[144:147], v[200:203]
	s_nop 2
	v_exp_f32_e32 v188, v188
	v_exp_f32_e32 v189, v189
	v_exp_f32_e32 v190, v190
	v_exp_f32_e32 v191, v191
	v_exp_f32_e32 v192, v192
	v_exp_f32_e32 v193, v193
	v_exp_f32_e32 v194, v194
	v_exp_f32_e32 v195, v195
	v_cvt_pk_bf16_f32 v246, v188, v189
	v_cvt_pk_bf16_f32 v247, v190, v191
	v_cvt_pk_bf16_f32 v248, v192, v193
	v_cvt_pk_bf16_f32 v249, v194, v195
	v_add_f32_e32 v1, v188, v189
	v_add_f32_e32 v2, v190, v191
	v_add_f32_e32 v3, v192, v193
	v_add_f32_e32 v85, v194, v195
	v_add_f32_e32 v1, v1, v2
	v_add_f32_e32 v3, v3, v85
	v_add_f32_e32 v1, v1, v3
	v_add_f32_e32 v222, v222, v1
	v_mfma_f32_16x16x32_bf16 v[188:191], v[176:179], v[148:151], v[76:79]
	v_mfma_f32_16x16x32_bf16 v[192:195], v[168:171], v[148:151], v[76:79]
	v_mfma_f32_16x16x32_bf16 v[188:191], v[172:175], v[152:155], v[188:191]
	v_mfma_f32_16x16x32_bf16 v[192:195], v[164:167], v[152:155], v[192:195]
	s_waitcnt vmcnt(8)
	v_exp_f32_e32 v196, v196
	v_exp_f32_e32 v197, v197
	v_exp_f32_e32 v198, v198
	v_exp_f32_e32 v199, v199
	v_mfma_f32_16x16x32_bf16 v[96:99], v[32:35], v[246:249], v[96:99]
	v_exp_f32_e32 v200, v200
	v_exp_f32_e32 v201, v201
	v_exp_f32_e32 v202, v202
	v_exp_f32_e32 v203, v203
	v_mfma_f32_16x16x32_bf16 v[88:91], v[28:31], v[246:249], v[88:91]
	v_cvt_pk_bf16_f32 v92, v196, v197
	v_cvt_pk_bf16_f32 v93, v198, v199
	v_cvt_pk_bf16_f32 v94, v200, v201
	v_cvt_pk_bf16_f32 v95, v202, v203
	v_mfma_f32_16x16x32_bf16 v[72:75], v[24:27], v[246:249], v[72:75]
	v_add_f32_e32 v86, v196, v197
	v_add_f32_e32 v87, v198, v199
	v_add_f32_e32 v220, v200, v201
	v_add_f32_e32 v221, v202, v203
	v_mfma_f32_16x16x32_bf16 v[68:71], v[20:23], v[246:249], v[68:71]
	v_add_f32_e32 v86, v86, v87
	v_add_f32_e32 v220, v220, v221
	v_add_f32_e32 v86, v86, v220
	v_add_f32_e32 v223, v223, v86
	v_mfma_f32_16x16x32_bf16 v[196:199], v[176:179], v[156:159], v[76:79]
	v_mfma_f32_16x16x32_bf16 v[200:203], v[168:171], v[156:159], v[76:79]
	v_mfma_f32_16x16x32_bf16 v[196:199], v[172:175], v[160:163], v[196:199]
	v_mfma_f32_16x16x32_bf16 v[200:203], v[164:167], v[160:163], v[200:203]
	buffer_load_dwordx4 v[176:179], v233, s[24:27], s23 offen
	buffer_load_dwordx4 v[172:175], v235, s[24:27], s23 offen
	buffer_load_dwordx4 v[168:171], v80, s[24:27], s23 offen
	buffer_load_dwordx4 v[164:167], v81, s[24:27], s23 offen
	v_exp_f32_e32 v188, v188
	v_exp_f32_e32 v189, v189
	v_exp_f32_e32 v190, v190
	v_exp_f32_e32 v191, v191
	v_mfma_f32_16x16x32_bf16 v[64:67], v[32:35], v[92:95], v[64:67]
	v_exp_f32_e32 v192, v192
	v_exp_f32_e32 v193, v193
	v_exp_f32_e32 v194, v194
	v_exp_f32_e32 v195, v195
	v_mfma_f32_16x16x32_bf16 v[60:63], v[28:31], v[92:95], v[60:63]
	v_cvt_pk_bf16_f32 v246, v188, v189
	v_cvt_pk_bf16_f32 v247, v190, v191
	v_cvt_pk_bf16_f32 v248, v192, v193
	v_cvt_pk_bf16_f32 v249, v194, v195
	v_mfma_f32_16x16x32_bf16 v[56:59], v[24:27], v[92:95], v[56:59]
	v_add_f32_e32 v1, v188, v189
	v_add_f32_e32 v2, v190, v191
	v_add_f32_e32 v3, v192, v193
	v_add_f32_e32 v85, v194, v195
	v_mfma_f32_16x16x32_bf16 v[52:55], v[20:23], v[92:95], v[52:55]
	v_add_f32_e32 v1, v1, v2
	v_add_f32_e32 v3, v3, v85
	v_add_f32_e32 v1, v1, v3
	v_add_f32_e32 v224, v224, v1
	v_exp_f32_e32 v196, v196
	v_exp_f32_e32 v197, v197
	v_exp_f32_e32 v198, v198
	v_exp_f32_e32 v199, v199
	v_mfma_f32_16x16x32_bf16 v[128:131], v[32:35], v[246:249], v[128:131]
	v_exp_f32_e32 v200, v200
	v_exp_f32_e32 v201, v201
	v_exp_f32_e32 v202, v202
	v_exp_f32_e32 v203, v203
	v_mfma_f32_16x16x32_bf16 v[124:127], v[28:31], v[246:249], v[124:127]
	v_cvt_pk_bf16_f32 v92, v196, v197
	v_cvt_pk_bf16_f32 v93, v198, v199
	v_cvt_pk_bf16_f32 v94, v200, v201
	v_cvt_pk_bf16_f32 v95, v202, v203
	v_mfma_f32_16x16x32_bf16 v[120:123], v[24:27], v[246:249], v[120:123]
	v_add_f32_e32 v86, v196, v197
	v_add_f32_e32 v87, v198, v199
	v_add_f32_e32 v220, v200, v201
	v_add_f32_e32 v221, v202, v203
	v_mfma_f32_16x16x32_bf16 v[116:119], v[20:23], v[246:249], v[116:119]
	v_add_f32_e32 v86, v86, v87
	v_add_f32_e32 v220, v220, v221
	v_add_f32_e32 v86, v86, v220
	v_add_f32_e32 v225, v225, v86
	v_mfma_f32_16x16x32_bf16 v[112:115], v[32:35], v[92:95], v[112:115]
	v_mfma_f32_16x16x32_bf16 v[108:111], v[28:31], v[92:95], v[108:111]
	v_mfma_f32_16x16x32_bf16 v[104:107], v[24:27], v[92:95], v[104:107]
	v_mfma_f32_16x16x32_bf16 v[100:103], v[20:23], v[92:95], v[100:103]
	s_cmp_eq_u32 s60, 0
	s_cbranch_scc1 .Latt_vc9
	buffer_load_dwordx4 v[32:35], v234, s[40:43], s33 offen
	buffer_load_dwordx4 v[28:31], v82, s[40:43], s33 offen
	buffer_load_dwordx4 v[24:27], v83, s[40:43], s33 offen
	buffer_load_dwordx4 v[20:23], v84, s[40:43], s33 offen
	s_branch .Latt_ve9

.Latt_ve9:
	s_add_i32 s92, s92, 1
	s_sub_u32 s91, s91, 1
	s_cmp_eq_u32 s91, 0
	s_cbranch_scc1 .Latt_done
.Latt_CB:
	s_add_i32 s20, s92, 2
	s_min_i32 s20, s20, s80
	s_add_i32 s21, s20, s77
	s_lshl_b32 s21, s21, 6
	s_or_b32 s21, s21, s59
	s_sub_i32 s22, s20, s76
	s_lshl_b32 s22, s22, 5
	s_addk_i32 s22, 0x1000
	s_cmp_lt_i32 s20, s76
	s_cselect_b32 s60, 1, 0
	s_cselect_b32 s20, s21, s22
	s_lshl_b32 s23, s20, 10
	s_add_i32 s23, s23, s81
	s_lshr_b32 s33, s20, 5
	s_lshl_b32 s33, s33, 6
	s_add_i32 s33, s33, s82
	s_waitcnt vmcnt(12)
	v_mfma_f32_16x16x32_bf16 v[188:191], v[48:51], v[132:135], v[76:79]
	v_mfma_f32_16x16x32_bf16 v[192:195], v[40:43], v[132:135], v[76:79]
	v_mfma_f32_16x16x32_bf16 v[188:191], v[44:47], v[136:139], v[188:191]
	v_mfma_f32_16x16x32_bf16 v[192:195], v[36:39], v[136:139], v[192:195]
	v_mfma_f32_16x16x32_bf16 v[196:199], v[48:51], v[140:143], v[76:79]
	v_mfma_f32_16x16x32_bf16 v[200:203], v[40:43], v[140:143], v[76:79]
	v_mfma_f32_16x16x32_bf16 v[196:199], v[44:47], v[144:147], v[196:199]
	v_mfma_f32_16x16x32_bf16 v[200:203], v[36:39], v[144:147], v[200:203]
	s_nop 2
	v_exp_f32_e32 v188, v188
	v_exp_f32_e32 v189, v189
	v_exp_f32_e32 v190, v190
	v_exp_f32_e32 v191, v191
	v_exp_f32_e32 v192, v192
	v_exp_f32_e32 v193, v193
	v_exp_f32_e32 v194, v194
	v_exp_f32_e32 v195, v195
	v_cvt_pk_bf16_f32 v246, v188, v189
	v_cvt_pk_bf16_f32 v247, v190, v191
	v_cvt_pk_bf16_f32 v248, v192, v193
	v_cvt_pk_bf16_f32 v249, v194, v195
	v_add_f32_e32 v1, v188, v189
	v_add_f32_e32 v2, v190, v191
	v_add_f32_e32 v3, v192, v193
	v_add_f32_e32 v85, v194, v195
	v_add_f32_e32 v1, v1, v2
	v_add_f32_e32 v3, v3, v85
	v_add_f32_e32 v1, v1, v3
	v_add_f32_e32 v222, v222, v1
	v_mfma_f32_16x16x32_bf16 v[188:191], v[48:51], v[148:151], v[76:79]
	v_mfma_f32_16x16x32_bf16 v[192:195], v[40:43], v[148:151], v[76:79]
	v_mfma_f32_16x16x32_bf16 v[188:191], v[44:47], v[152:155], v[188:191]
	v_mfma_f32_16x16x32_bf16 v[192:195], v[36:39], v[152:155], v[192:195]
	s_waitcnt vmcnt(8)
	v_exp_f32_e32 v196, v196
	v_exp_f32_e32 v197, v197
	v_exp_f32_e32 v198, v198
	v_exp_f32_e32 v199, v199
	v_mfma_f32_16x16x32_bf16 v[96:99], v[16:19], v[246:249], v[96:99]
	v_exp_f32_e32 v200, v200
	v_exp_f32_e32 v201, v201
	v_exp_f32_e32 v202, v202
	v_exp_f32_e32 v203, v203
	v_mfma_f32_16x16x32_bf16 v[88:91], v[12:15], v[246:249], v[88:91]
	v_cvt_pk_bf16_f32 v92, v196, v197
	v_cvt_pk_bf16_f32 v93, v198, v199
	v_cvt_pk_bf16_f32 v94, v200, v201
	v_cvt_pk_bf16_f32 v95, v202, v203
	v_mfma_f32_16x16x32_bf16 v[72:75], v[8:11], v[246:249], v[72:75]
	v_add_f32_e32 v86, v196, v197
	v_add_f32_e32 v87, v198, v199
	v_add_f32_e32 v220, v200, v201
	v_add_f32_e32 v221, v202, v203
	v_mfma_f32_16x16x32_bf16 v[68:71], v[4:7], v[246:249], v[68:71]
	v_add_f32_e32 v86, v86, v87
	v_add_f32_e32 v220, v220, v221
	v_add_f32_e32 v86, v86, v220
	v_add_f32_e32 v223, v223, v86
	v_mfma_f32_16x16x32_bf16 v[196:199], v[48:51], v[156:159], v[76:79]
	v_mfma_f32_16x16x32_bf16 v[200:203], v[40:43], v[156:159], v[76:79]
	v_mfma_f32_16x16x32_bf16 v[196:199], v[44:47], v[160:163], v[196:199]
	v_mfma_f32_16x16x32_bf16 v[200:203], v[36:39], v[160:163], v[200:203]
	buffer_load_dwordx4 v[48:51], v233, s[24:27], s23 offen
	buffer_load_dwordx4 v[44:47], v235, s[24:27], s23 offen
	buffer_load_dwordx4 v[40:43], v80, s[24:27], s23 offen
	buffer_load_dwordx4 v[36:39], v81, s[24:27], s23 offen
	v_exp_f32_e32 v188, v188
	v_exp_f32_e32 v189, v189
	v_exp_f32_e32 v190, v190
	v_exp_f32_e32 v191, v191
	v_mfma_f32_16x16x32_bf16 v[64:67], v[16:19], v[92:95], v[64:67]
	v_exp_f32_e32 v192, v192
	v_exp_f32_e32 v193, v193
	v_exp_f32_e32 v194, v194
	v_exp_f32_e32 v195, v195
	v_mfma_f32_16x16x32_bf16 v[60:63], v[12:15], v[92:95], v[60:63]
	v_cvt_pk_bf16_f32 v246, v188, v189
	v_cvt_pk_bf16_f32 v247, v190, v191
	v_cvt_pk_bf16_f32 v248, v192, v193
	v_cvt_pk_bf16_f32 v249, v194, v195
	v_mfma_f32_16x16x32_bf16 v[56:59], v[8:11], v[92:95], v[56:59]
	v_add_f32_e32 v1, v188, v189
	v_add_f32_e32 v2, v190, v191
	v_add_f32_e32 v3, v192, v193
	v_add_f32_e32 v85, v194, v195
	v_mfma_f32_16x16x32_bf16 v[52:55], v[4:7], v[92:95], v[52:55]
	v_add_f32_e32 v1, v1, v2
	v_add_f32_e32 v3, v3, v85
	v_add_f32_e32 v1, v1, v3
	v_add_f32_e32 v224, v224, v1
	v_exp_f32_e32 v196, v196
	v_exp_f32_e32 v197, v197
	v_exp_f32_e32 v198, v198
	v_exp_f32_e32 v199, v199
	v_mfma_f32_16x16x32_bf16 v[128:131], v[16:19], v[246:249], v[128:131]
	v_exp_f32_e32 v200, v200
	v_exp_f32_e32 v201, v201
	v_exp_f32_e32 v202, v202
	v_exp_f32_e32 v203, v203
	v_mfma_f32_16x16x32_bf16 v[124:127], v[12:15], v[246:249], v[124:127]
	v_cvt_pk_bf16_f32 v92, v196, v197
	v_cvt_pk_bf16_f32 v93, v198, v199
	v_cvt_pk_bf16_f32 v94, v200, v201
	v_cvt_pk_bf16_f32 v95, v202, v203
	v_mfma_f32_16x16x32_bf16 v[120:123], v[8:11], v[246:249], v[120:123]
	v_add_f32_e32 v86, v196, v197
	v_add_f32_e32 v87, v198, v199
	v_add_f32_e32 v220, v200, v201
	v_add_f32_e32 v221, v202, v203
	v_mfma_f32_16x16x32_bf16 v[116:119], v[4:7], v[246:249], v[116:119]
	v_add_f32_e32 v86, v86, v87
	v_add_f32_e32 v220, v220, v221
	v_add_f32_e32 v86, v86, v220
	v_add_f32_e32 v225, v225, v86
	v_mfma_f32_16x16x32_bf16 v[112:115], v[16:19], v[92:95], v[112:115]
	v_mfma_f32_16x16x32_bf16 v[108:111], v[12:15], v[92:95], v[108:111]
	v_mfma_f32_16x16x32_bf16 v[104:107], v[8:11], v[92:95], v[104:107]
	v_mfma_f32_16x16x32_bf16 v[100:103], v[4:7], v[92:95], v[100:103]
	s_cmp_eq_u32 s60, 0
	s_cbranch_scc1 .Latt_vc10
	buffer_load_dwordx4 v[16:19], v234, s[40:43], s33 offen
	buffer_load_dwordx4 v[12:15], v82, s[40:43], s33 offen
	buffer_load_dwordx4 v[8:11], v83, s[40:43], s33 offen
	buffer_load_dwordx4 v[4:7], v84, s[40:43], s33 offen
	s_branch .Latt_ve10

.Latt_ve10:
	s_add_i32 s92, s92, 1
	s_sub_u32 s91, s91, 1
	s_cmp_lg_u32 s91, 0
	s_cbranch_scc1 .Latt_CA

	.amdhsa_kernel _Z6k_mega6Params
		.amdhsa_group_segment_fixed_size 0
		.amdhsa_private_segment_fixed_size 0
		.amdhsa_kernarg_size 504
		.amdhsa_user_sgpr_count 2
		.amdhsa_user_sgpr_dispatch_ptr 0
		.amdhsa_user_sgpr_queue_ptr 0
		.amdhsa_user_sgpr_kernarg_segment_ptr 1
		.amdhsa_user_sgpr_dispatch_id 0
		.amdhsa_user_sgpr_kernarg_preload_length 0
		.amdhsa_user_sgpr_kernarg_preload_offset 0
		.amdhsa_user_sgpr_private_segment_size 0
		.amdhsa_uses_dynamic_stack 0
		.amdhsa_enable_private_segment 0
		.amdhsa_system_sgpr_workgroup_id_x 1
		.amdhsa_system_sgpr_workgroup_id_y 0
		.amdhsa_system_sgpr_workgroup_id_z 0
		.amdhsa_system_sgpr_workgroup_info 0
		.amdhsa_system_vgpr_workitem_id 2
		.amdhsa_next_free_vgpr 256
		.amdhsa_next_free_sgpr 98
		.amdhsa_accum_offset 256
		.amdhsa_reserve_vcc 1
		.amdhsa_float_round_mode_32 0
		.amdhsa_float_round_mode_16_64 0
		.amdhsa_float_denorm_mode_32 3
		.amdhsa_float_denorm_mode_16_64 3
		.amdhsa_dx10_clamp 1
		.amdhsa_ieee_mode 1
		.amdhsa_fp16_overflow 0
		.amdhsa_tg_split 0
		.amdhsa_exception_fp_ieee_invalid_op 0
		.amdhsa_exception_fp_denorm_src 0
		.amdhsa_exception_fp_ieee_div_zero 0
		.amdhsa_exception_fp_ieee_overflow 0
		.amdhsa_exception_fp_ieee_underflow 0
		.amdhsa_exception_fp_ieee_inexact 0
		.amdhsa_exception_int_div_zero 0
	.end_amdhsa_kernel

amdhsa.kernels:
  - .agpr_count:     0
    .args:
      - .offset:         0
        .size:           248
        .value_kind:     by_value
      - .offset:         248
        .size:           4
        .value_kind:     hidden_block_count_x
      - .offset:         252
        .size:           4
        .value_kind:     hidden_block_count_y
      - .offset:         256
        .size:           4
        .value_kind:     hidden_block_count_z
      - .offset:         260
        .size:           2
        .value_kind:     hidden_group_size_x
      - .offset:         262
        .size:           2
        .value_kind:     hidden_group_size_y
      - .offset:         264
        .size:           2
        .value_kind:     hidden_group_size_z
      - .offset:         266
        .size:           2
        .value_kind:     hidden_remainder_x
      - .offset:         268
        .size:           2
        .value_kind:     hidden_remainder_y
      - .offset:         270
        .size:           2
        .value_kind:     hidden_remainder_z
      - .offset:         288
        .size:           8
        .value_kind:     hidden_global_offset_x
      - .offset:         296
        .size:           8
        .value_kind:     hidden_global_offset_y
      - .offset:         304
        .size:           8
        .value_kind:     hidden_global_offset_z
      - .offset:         312
        .size:           2
        .value_kind:     hidden_grid_dims
      - .offset:         336
        .size:           8
        .value_kind:     hidden_multigrid_sync_arg
      - .offset:         368
        .size:           4
        .value_kind:     hidden_dynamic_lds_size
    .group_segment_fixed_size: 0
    .kernarg_segment_align: 8
    .kernarg_segment_size: 504
    .language:       OpenCL C
    .language_version:
      - 2
      - 0
    .max_flat_workgroup_size: 512
    .name:           _Z6k_mega6Params
    .private_segment_fixed_size: 0
    .sgpr_count:     104
    .sgpr_spill_count: 12
    .symbol:         _Z6k_mega6Params.kd
    .uniform_work_group_size: 1
    .uses_dynamic_stack: false
    .vgpr_count:     256
    .vgpr_spill_count: 0
    .wavefront_size: 64
